# residual-epilogue stores (y, AP, ssq) issued write-through (sc1) so the release fences of the following hand-offs find no dirty L2 lines
# baseline (speedup 1.0000x reference)
;     DI void operator()(AccRef acc, const Unit& u, int wr, int wc, int fr, int fq) const {
;     ...
; #pragma unroll
;         for (int ai = 0; ai < 2; ++ai) {
;             const int rb = u.pm * 256 + ai * 128 + wr * 64 + fr;
;             int mb, pos0, kv0; row_info(rb, mb, pos0, kv0);
;             f32x4 gt[2][2], gs[2][2];
; #pragma unroll
;             for (int bj = 0; bj < 2; ++bj)
; #pragma unroll
;                 for (int n = 0; n < 2; ++n) {
;                     const int c = u.pn * 256 + bj * 128 + cl + 4 * n;
;                     gt[bj][n] = *(const f32x4*)(gate + (size_t)mb * 6144 + c);
;                     if (ap) { const f32x4 g = *(const f32x4*)(gn + c), s = *(const f32x4*)(scn + (size_t)mb * 6144 + c); gs[bj][n] = g * (s + 1.f); }
;                 }
.LBB0_1094:
	v_readlane_b32 s3, v253, 32
	v_mbcnt_lo_u32_b32 v100, -1, 0
	v_mbcnt_hi_u32_b32 v100, -1, v100
	s_mov_b32 s3, s30
	v_and_b32_e32 v202, 15, v100
	v_bfe_u32 v204, v100, 4, 2
	s_mov_b32 s12, s36
	s_lshl_b32 s16, s16, 8
	s_lshl_b32 s3, s3, 6
	s_add_i32 s3, s3, s16
	v_add_u32_e32 v192, s3, v202
	s_lshl_b32 s13, s12, 5
	s_lshl_b32 s3, s2, 8
	v_add_u32_e32 v224, 0xffffc000, v192
	s_add_i32 s13, s13, s3
	v_lshrrev_b32_e32 v101, 6, v224
	v_lshl_add_u32 v188, v204, 3, s13
	v_ashrrev_i32_e32 v100, 11, v192
	v_add_u32_e32 v101, 8, v101
	v_cmp_gt_i32_e32 vcc, s94, v192
	v_mov_b64_e32 v[102:103], s[60:61]
	v_ashrrev_i32_e32 v189, 31, v188
	v_cndmask_b32_e32 v104, v101, v100, vcc
	v_mov_b64_e32 v[100:101], s[8:9]
	v_mad_i64_i32 v[100:101], s[16:17], v104, s75, v[100:101]
	v_mad_i64_i32 v[102:103], s[16:17], v104, s75, v[102:103]
	v_lshlrev_b64 v[190:191], 2, v[188:189]
	v_lshl_add_u64 v[104:105], v[100:101], 0, v[190:191]
	v_lshl_add_u64 v[194:195], s[72:73], 0, v[190:191]
	v_lshl_add_u64 v[168:169], v[102:103], 0, v[190:191]
	global_load_dwordx4 v[108:111], v[104:105], off offset:16
	global_load_dwordx4 v[116:119], v[104:105], off
	global_load_dwordx4 v[148:151], v[194:195], off offset:16
	global_load_dwordx4 v[164:167], v[194:195], off
	global_load_dwordx4 v[160:163], v[168:169], off offset:16
	global_load_dwordx4 v[172:175], v[168:169], off
	global_load_dwordx4 v[100:103], v[104:105], off offset:528
	s_nop 0
	global_load_dwordx4 v[104:107], v[104:105], off offset:512
	s_nop 0
	global_load_dwordx4 v[144:147], v[194:195], off offset:528
	global_load_dwordx4 v[156:159], v[194:195], off offset:512
	global_load_dwordx4 v[152:155], v[168:169], off offset:528
	s_nop 0
	global_load_dwordx4 v[168:171], v[168:169], off offset:512
	s_movk_i32 s3, 0x3fff
	v_cmp_lt_i32_e32 vcc, s3, v192
	s_and_saveexec_b64 s[16:17], vcc
	s_xor_b64 s[16:17], exec, s[16:17]
	v_lshlrev_b64 v[196:197], 12, v[224:225]
	v_mov_b32_e32 v193, v225
	v_lshl_add_u64 v[198:199], s[20:21], 0, v[196:197]
	v_lshlrev_b64 v[196:197], 12, v[192:193]
	s_andn2_saveexec_b64 s[16:17], s[16:17]
	v_ashrrev_i32_e32 v193, 31, v192
	v_lshlrev_b64 v[196:197], 12, v[192:193]
	v_lshl_add_u64 v[198:199], s[42:43], 0, v[196:197]
	s_or_b64 exec, exec, s[16:17]
	s_sub_u32 s82, s20, 0x4000000
	s_subb_u32 s83, s21, 0
	s_cmp_ge_u32 s16, 0x4000
	s_cselect_b32 s82, s82, s42
	s_cselect_b32 s83, s83, s43
	v_lshl_add_u32 v206, v192, 12, v190
	v_lshlrev_b32_e32 v213, 4, v204
	v_sub_u32_e32 v206, v206, v213
	v_lshlrev_b32_e32 v213, 11, v192
	v_lshlrev_b32_e32 v209, 6, v192
	v_mov_b32_e32 v207, v206
	v_lshl_add_u32 v208, v188, 1, v213
	global_load_dwordx4 v[232:235], v206, s[82:83] offset:64
	global_load_dwordx4 v[240:243], v206, s[82:83] offset:576
	global_load_dwordx4 v[228:231], v206, s[82:83]
	global_load_dwordx4 v[236:239], v206, s[82:83] offset:512
	v_add_u32_e32 v206, 0x10000, v206
	global_load_dwordx4 v[248:251], v206, s[82:83] offset:64
	global_load_dwordx4 v[220:223], v206, s[82:83] offset:576
	global_load_dwordx4 v[244:247], v206, s[82:83]
	global_load_dwordx4 v[216:219], v206, s[82:83] offset:512
	v_add_u32_e32 v206, 0x10000, v206
	s_waitcnt vmcnt(8)
	v_pk_add_f32 v[172:173], v[172:173], 1.0 op_sel_hi:[1,0]
	v_pk_add_f32 v[154:155], v[154:155], 1.0 op_sel_hi:[1,0]
	v_pk_mul_f32 v[164:165], v[164:165], v[172:173]
	v_pk_add_f32 v[172:173], v[160:161], 1.0 op_sel_hi:[1,0]
	v_pk_add_f32 v[160:161], v[162:163], 1.0 op_sel_hi:[1,0]
	v_pk_mul_f32 v[162:163], v[148:149], v[172:173]
	v_pk_mul_f32 v[160:161], v[150:151], v[160:161]
	v_pk_add_f32 v[148:149], v[170:171], 1.0 op_sel_hi:[1,0]
	v_pk_add_f32 v[150:151], v[168:169], 1.0 op_sel_hi:[1,0]
	v_pk_mul_f32 v[146:147], v[146:147], v[154:155]
	v_lshl_add_u64 v[154:155], v[198:199], 0, v[190:191]
	v_pk_mul_f32 v[148:149], v[158:159], v[148:149]
	v_pk_mul_f32 v[150:151], v[156:157], v[150:151]
	v_pk_add_f32 v[174:175], v[174:175], 1.0 op_sel_hi:[1,0]
	v_pk_add_f32 v[152:153], v[152:153], 1.0 op_sel_hi:[1,0]
	v_pk_mul_f32 v[166:167], v[166:167], v[174:175]
	v_pk_mul_f32 v[144:145], v[144:145], v[152:153]
	v_lshlrev_b64 v[152:153], 11, v[192:193]
	v_lshl_add_u64 v[152:153], s[64:65], 0, v[152:153]
	v_lshlrev_b32_e32 v202, 2, v202
	v_lshl_add_u32 v202, v204, 6, v202
	v_xor_b32_e32 v203, 64, v202
	s_lshl_b32 s2, s2, 2
	v_xor_b32_e32 v202, 0x80, v202
	s_ashr_i32 s3, s2, 31
	s_ashr_i32 s13, s12, 31
	s_lshl_b64 s[2:3], s[2:3], 2
	s_add_u32 s16, s39, s2
	s_addc_u32 s17, s40, s3
	s_lshl_b64 s[2:3], s[12:13], 2
	s_add_u32 s90, s16, s2
	v_cmp_eq_u32_e32 vcc, 0, v204
	s_addc_u32 s91, s17, s3
	s_waitcnt vmcnt(4)
; DI u32x4 pack8(const float* v) { u32x4 w; w.x = pk2(v[0], v[1]); w.y = pk2(v[2], v[3]); w.z = pk2(v[4], v[5]); w.w = pk2(v[6], v[7]); return w; }
; #define xor16_32(s) xor16_32_l((s), fr + 16 * fq)
;     DI void operator()(AccRef acc, const Unit& u, int wr, int wc, int fr, int fq) const {
;     ...
;             for (int m = 0; m < 4; ++m) {
;                 const int row = rb + 16 * m;
;                 const float* xi = row < MP ? xin_p + (size_t)row * 1024 : xin_s + (size_t)(row - MP) * 1024;
;                 float s = 0.f;
; #pragma unroll
;                 for (int bj = 0; bj < 2; ++bj) {
;                     const int c = u.pn * 256 + bj * 128 + cl;
;                     float v[8];
; #pragma unroll
;                     for (int n = 0; n < 2; ++n) {
;                         const f32x4 x = *(const f32x4*)(xi + c + 4 * n);
;                         const f32x4 y = x + gt[bj][n] * acc[ai][bj][m][n];
;                         *(f32x4*)(xout + (size_t)row * 1024 + c + 4 * n) = y;
; #pragma unroll
;                         for (int j = 0; j < 4; ++j) { s += y[j] * y[j]; v[4 * n + j] = ap ? y[j] * gs[bj][n][j] : 0.f; }
;                     }
;                     if (ap) *(u32x4*)(ap + (size_t)row * 1024 + c) = pack8(v);
;                 }
;                 s = xor16_32(s);
;                 if (fq == 0) ssq[(size_t)row * 16 + u.pn * 4 + wc] = s;
;             }
	v_permlane32_swap_b32_e32 v228, v232
	v_permlane32_swap_b32_e32 v229, v233
	v_permlane32_swap_b32_e32 v230, v234
	v_permlane32_swap_b32_e32 v231, v235
	v_permlane32_swap_b32_e32 v236, v240
	v_permlane32_swap_b32_e32 v237, v241
	v_permlane32_swap_b32_e32 v238, v242
	v_permlane32_swap_b32_e32 v239, v243
	v_permlane16_swap_b32_e32 v228, v232
	v_permlane16_swap_b32_e32 v229, v233
	v_permlane16_swap_b32_e32 v230, v234
	v_permlane16_swap_b32_e32 v231, v235
	v_permlane16_swap_b32_e32 v236, v240
	v_permlane16_swap_b32_e32 v237, v241
	v_permlane16_swap_b32_e32 v238, v242
	v_permlane16_swap_b32_e32 v239, v243
	v_pk_fma_f32 v[140:141], v[140:141], v[116:117], v[228:229]
	v_pk_fma_f32 v[142:143], v[142:143], v[118:119], v[230:231]
	v_mul_f32_e32 v210, v141, v141
	v_fmac_f32_e32 v210, v140, v140
	v_fmac_f32_e32 v210, v142, v142
	v_fmac_f32_e32 v210, v143, v143
	v_pk_mul_f32 v[228:229], v[164:165], v[140:141]
	v_pk_mul_f32 v[230:231], v[166:167], v[142:143]
	v_pk_fma_f32 v[136:137], v[136:137], v[108:109], v[232:233]
	v_pk_fma_f32 v[138:139], v[138:139], v[110:111], v[234:235]
	v_fmac_f32_e32 v210, v136, v136
	v_fmac_f32_e32 v210, v137, v137
	v_fmac_f32_e32 v210, v138, v138
	v_fmac_f32_e32 v210, v139, v139
	v_pk_mul_f32 v[232:233], v[162:163], v[136:137]
	v_pk_mul_f32 v[234:235], v[160:161], v[138:139]
	v_cvt_pk_bf16_f32 v228, v228, v229
	v_cvt_pk_bf16_f32 v229, v230, v231
	v_cvt_pk_bf16_f32 v230, v232, v233
	v_cvt_pk_bf16_f32 v231, v234, v235
	global_store_dwordx4 v208, v[228:231], s[64:65] sc1
	v_pk_fma_f32 v[132:133], v[132:133], v[104:105], v[236:237]
	v_pk_fma_f32 v[134:135], v[134:135], v[106:107], v[238:239]
	v_fmac_f32_e32 v210, v132, v132
	v_fmac_f32_e32 v210, v133, v133
	v_fmac_f32_e32 v210, v134, v134
	v_fmac_f32_e32 v210, v135, v135
	v_pk_mul_f32 v[236:237], v[150:151], v[132:133]
	v_pk_mul_f32 v[238:239], v[148:149], v[134:135]
	v_pk_fma_f32 v[128:129], v[128:129], v[100:101], v[240:241]
	v_pk_fma_f32 v[130:131], v[130:131], v[102:103], v[242:243]
	v_fmac_f32_e32 v210, v128, v128
	v_fmac_f32_e32 v210, v129, v129
	v_fmac_f32_e32 v210, v130, v130
	v_fmac_f32_e32 v210, v131, v131
	v_pk_mul_f32 v[240:241], v[144:145], v[128:129]
	v_pk_mul_f32 v[242:243], v[146:147], v[130:131]
	v_cvt_pk_bf16_f32 v236, v236, v237
	v_cvt_pk_bf16_f32 v237, v238, v239
	v_cvt_pk_bf16_f32 v238, v240, v241
	v_cvt_pk_bf16_f32 v239, v242, v243
	global_store_dwordx4 v208, v[236:239], s[64:65] offset:256 sc1
	ds_bpermute_b32 v211, v203, v210
	v_permlane16_swap_b32_e32 v140, v136
	v_permlane16_swap_b32_e32 v141, v137
	v_permlane16_swap_b32_e32 v142, v138
	v_permlane16_swap_b32_e32 v143, v139
	v_permlane16_swap_b32_e32 v132, v128
	v_permlane16_swap_b32_e32 v133, v129
	v_permlane16_swap_b32_e32 v134, v130
	v_permlane16_swap_b32_e32 v135, v131
	v_permlane32_swap_b32_e32 v140, v136
	v_permlane32_swap_b32_e32 v141, v137
	v_permlane32_swap_b32_e32 v142, v138
	v_permlane32_swap_b32_e32 v143, v139
	v_permlane32_swap_b32_e32 v132, v128
	v_permlane32_swap_b32_e32 v133, v129
	v_permlane32_swap_b32_e32 v134, v130
	v_permlane32_swap_b32_e32 v135, v131
	global_store_dwordx4 v207, v[140:143], s[92:93] sc1
	global_store_dwordx4 v207, v[136:139], s[92:93] offset:64 sc1
	global_store_dwordx4 v207, v[132:135], s[92:93] offset:512 sc1
	global_store_dwordx4 v207, v[128:131], s[92:93] offset:576 sc1
	v_add_u32_e32 v207, 0x10000, v207
	global_load_dwordx4 v[232:235], v206, s[82:83] offset:64
	global_load_dwordx4 v[240:243], v206, s[82:83] offset:576
	global_load_dwordx4 v[228:231], v206, s[82:83]
	global_load_dwordx4 v[236:239], v206, s[82:83] offset:512
	s_waitcnt lgkmcnt(0)
	v_add_f32_e32 v211, v210, v211
	ds_bpermute_b32 v212, v202, v211
	v_add_u32_e32 v208, 0x8000, v208
	s_waitcnt lgkmcnt(0)
	v_add_f32_e32 v211, v211, v212
	s_mov_b64 exec, 0xffff
	global_store_dword v209, v211, s[90:91] sc1
	s_mov_b64 exec, -1
	v_add_u32_e32 v209, 0x400, v209
	s_waitcnt vmcnt(11)
	v_permlane32_swap_b32_e32 v244, v248
	v_permlane32_swap_b32_e32 v245, v249
	v_permlane32_swap_b32_e32 v246, v250
	v_permlane32_swap_b32_e32 v247, v251
	v_permlane32_swap_b32_e32 v216, v220
	v_permlane32_swap_b32_e32 v217, v221
	v_permlane32_swap_b32_e32 v218, v222
	v_permlane32_swap_b32_e32 v219, v223
	v_permlane16_swap_b32_e32 v244, v248
	v_permlane16_swap_b32_e32 v245, v249
	v_permlane16_swap_b32_e32 v246, v250
	v_permlane16_swap_b32_e32 v247, v251
	v_permlane16_swap_b32_e32 v216, v220
	v_permlane16_swap_b32_e32 v217, v221
	v_permlane16_swap_b32_e32 v218, v222
	v_permlane16_swap_b32_e32 v219, v223
	v_pk_fma_f32 v[124:125], v[124:125], v[116:117], v[244:245]
	v_pk_fma_f32 v[126:127], v[126:127], v[118:119], v[246:247]
	v_mul_f32_e32 v210, v125, v125
	v_fmac_f32_e32 v210, v124, v124
	v_fmac_f32_e32 v210, v126, v126
	v_fmac_f32_e32 v210, v127, v127
	v_pk_mul_f32 v[244:245], v[164:165], v[124:125]
	v_pk_mul_f32 v[246:247], v[166:167], v[126:127]
	v_pk_fma_f32 v[120:121], v[120:121], v[108:109], v[248:249]
	v_pk_fma_f32 v[122:123], v[122:123], v[110:111], v[250:251]
	v_fmac_f32_e32 v210, v120, v120
	v_fmac_f32_e32 v210, v121, v121
	v_fmac_f32_e32 v210, v122, v122
	v_fmac_f32_e32 v210, v123, v123
	v_pk_mul_f32 v[248:249], v[162:163], v[120:121]
	v_pk_mul_f32 v[250:251], v[160:161], v[122:123]
	v_cvt_pk_bf16_f32 v244, v244, v245
	v_cvt_pk_bf16_f32 v245, v246, v247
	v_cvt_pk_bf16_f32 v246, v248, v249
	v_cvt_pk_bf16_f32 v247, v250, v251
	global_store_dwordx4 v208, v[244:247], s[64:65] sc1
	v_pk_fma_f32 v[112:113], v[112:113], v[104:105], v[216:217]
	v_pk_fma_f32 v[114:115], v[114:115], v[106:107], v[218:219]
	v_fmac_f32_e32 v210, v112, v112
	v_fmac_f32_e32 v210, v113, v113
	v_fmac_f32_e32 v210, v114, v114
	v_fmac_f32_e32 v210, v115, v115
; DI u32x4 pack8(const float* v) { u32x4 w; w.x = pk2(v[0], v[1]); w.y = pk2(v[2], v[3]); w.z = pk2(v[4], v[5]); w.w = pk2(v[6], v[7]); return w; }
; #define xor16_32(s) xor16_32_l((s), fr + 16 * fq)
;     DI void operator()(AccRef acc, const Unit& u, int wr, int wc, int fr, int fq) const {
;     ...
;             for (int m = 0; m < 4; ++m) {
;                 const int row = rb + 16 * m;
;                 const float* xi = row < MP ? xin_p + (size_t)row * 1024 : xin_s + (size_t)(row - MP) * 1024;
;                 float s = 0.f;
; #pragma unroll
;                 for (int bj = 0; bj < 2; ++bj) {
;                     const int c = u.pn * 256 + bj * 128 + cl;
;                     float v[8];
; #pragma unroll
;                     for (int n = 0; n < 2; ++n) {
;                         const f32x4 x = *(const f32x4*)(xi + c + 4 * n);
;                         const f32x4 y = x + gt[bj][n] * acc[ai][bj][m][n];
;                         *(f32x4*)(xout + (size_t)row * 1024 + c + 4 * n) = y;
; #pragma unroll
;                         for (int j = 0; j < 4; ++j) { s += y[j] * y[j]; v[4 * n + j] = ap ? y[j] * gs[bj][n][j] : 0.f; }
;                     }
;                     if (ap) *(u32x4*)(ap + (size_t)row * 1024 + c) = pack8(v);
;                 }
;                 s = xor16_32(s);
;                 if (fq == 0) ssq[(size_t)row * 16 + u.pn * 4 + wc] = s;
;             }
	v_pk_mul_f32 v[216:217], v[150:151], v[112:113]
	v_pk_mul_f32 v[218:219], v[148:149], v[114:115]
	v_pk_fma_f32 v[96:97], v[96:97], v[100:101], v[220:221]
	v_pk_fma_f32 v[98:99], v[98:99], v[102:103], v[222:223]
	v_fmac_f32_e32 v210, v96, v96
	v_fmac_f32_e32 v210, v97, v97
	v_fmac_f32_e32 v210, v98, v98
	v_fmac_f32_e32 v210, v99, v99
	v_pk_mul_f32 v[220:221], v[144:145], v[96:97]
	v_pk_mul_f32 v[222:223], v[146:147], v[98:99]
	v_cvt_pk_bf16_f32 v216, v216, v217
	v_cvt_pk_bf16_f32 v217, v218, v219
	v_cvt_pk_bf16_f32 v218, v220, v221
	v_cvt_pk_bf16_f32 v219, v222, v223
	global_store_dwordx4 v208, v[216:219], s[64:65] offset:256 sc1
	ds_bpermute_b32 v211, v203, v210
	v_permlane16_swap_b32_e32 v124, v120
	v_permlane16_swap_b32_e32 v125, v121
	v_permlane16_swap_b32_e32 v126, v122
	v_permlane16_swap_b32_e32 v127, v123
	v_permlane16_swap_b32_e32 v112, v96
	v_permlane16_swap_b32_e32 v113, v97
	v_permlane16_swap_b32_e32 v114, v98
	v_permlane16_swap_b32_e32 v115, v99
	v_permlane32_swap_b32_e32 v124, v120
	v_permlane32_swap_b32_e32 v125, v121
	v_permlane32_swap_b32_e32 v126, v122
	v_permlane32_swap_b32_e32 v127, v123
	v_permlane32_swap_b32_e32 v112, v96
	v_permlane32_swap_b32_e32 v113, v97
	v_permlane32_swap_b32_e32 v114, v98
	v_permlane32_swap_b32_e32 v115, v99
	global_store_dwordx4 v207, v[124:127], s[92:93] sc1
	global_store_dwordx4 v207, v[120:123], s[92:93] offset:64 sc1
	global_store_dwordx4 v207, v[112:115], s[92:93] offset:512 sc1
	global_store_dwordx4 v207, v[96:99], s[92:93] offset:576 sc1
	v_add_u32_e32 v207, 0x10000, v207
	v_add_u32_e32 v206, 0x10000, v206
	global_load_dwordx4 v[248:251], v206, s[82:83] offset:64
	global_load_dwordx4 v[220:223], v206, s[82:83] offset:576
	global_load_dwordx4 v[244:247], v206, s[82:83]
	global_load_dwordx4 v[216:219], v206, s[82:83] offset:512
	s_waitcnt lgkmcnt(0)
	v_add_f32_e32 v211, v210, v211
	ds_bpermute_b32 v212, v202, v211
	v_add_u32_e32 v208, 0x8000, v208
	s_waitcnt lgkmcnt(0)
	v_add_f32_e32 v211, v211, v212
	s_mov_b64 exec, 0xffff
	global_store_dword v209, v211, s[90:91] sc1
	s_mov_b64 exec, -1
	v_add_u32_e32 v209, 0x400, v209
	s_waitcnt vmcnt(12)
	v_permlane32_swap_b32_e32 v228, v232
	v_permlane32_swap_b32_e32 v229, v233
	v_permlane32_swap_b32_e32 v230, v234
	v_permlane32_swap_b32_e32 v231, v235
	v_permlane32_swap_b32_e32 v236, v240
	v_permlane32_swap_b32_e32 v237, v241
	v_permlane32_swap_b32_e32 v238, v242
	v_permlane32_swap_b32_e32 v239, v243
	v_permlane16_swap_b32_e32 v228, v232
	v_permlane16_swap_b32_e32 v229, v233
	v_permlane16_swap_b32_e32 v230, v234
	v_permlane16_swap_b32_e32 v231, v235
	v_permlane16_swap_b32_e32 v236, v240
	v_permlane16_swap_b32_e32 v237, v241
	v_permlane16_swap_b32_e32 v238, v242
	v_permlane16_swap_b32_e32 v239, v243
	v_pk_fma_f32 v[92:93], v[92:93], v[116:117], v[228:229]
	v_pk_fma_f32 v[94:95], v[94:95], v[118:119], v[230:231]
	v_mul_f32_e32 v210, v93, v93
	v_fmac_f32_e32 v210, v92, v92
	v_fmac_f32_e32 v210, v94, v94
	v_fmac_f32_e32 v210, v95, v95
	v_pk_mul_f32 v[228:229], v[164:165], v[92:93]
	v_pk_mul_f32 v[230:231], v[166:167], v[94:95]
	v_pk_fma_f32 v[88:89], v[88:89], v[108:109], v[232:233]
	v_pk_fma_f32 v[90:91], v[90:91], v[110:111], v[234:235]
	v_fmac_f32_e32 v210, v88, v88
	v_fmac_f32_e32 v210, v89, v89
	v_fmac_f32_e32 v210, v90, v90
	v_fmac_f32_e32 v210, v91, v91
	v_pk_mul_f32 v[232:233], v[162:163], v[88:89]
	v_pk_mul_f32 v[234:235], v[160:161], v[90:91]
	v_cvt_pk_bf16_f32 v228, v228, v229
	v_cvt_pk_bf16_f32 v229, v230, v231
	v_cvt_pk_bf16_f32 v230, v232, v233
	v_cvt_pk_bf16_f32 v231, v234, v235
	global_store_dwordx4 v208, v[228:231], s[64:65] sc1
	v_pk_fma_f32 v[84:85], v[84:85], v[104:105], v[236:237]
	v_pk_fma_f32 v[86:87], v[86:87], v[106:107], v[238:239]
	v_fmac_f32_e32 v210, v84, v84
	v_fmac_f32_e32 v210, v85, v85
	v_fmac_f32_e32 v210, v86, v86
	v_fmac_f32_e32 v210, v87, v87
	v_pk_mul_f32 v[236:237], v[150:151], v[84:85]
	v_pk_mul_f32 v[238:239], v[148:149], v[86:87]
	v_pk_fma_f32 v[80:81], v[80:81], v[100:101], v[240:241]
	v_pk_fma_f32 v[82:83], v[82:83], v[102:103], v[242:243]
	v_fmac_f32_e32 v210, v80, v80
	v_fmac_f32_e32 v210, v81, v81
	v_fmac_f32_e32 v210, v82, v82
	v_fmac_f32_e32 v210, v83, v83
	v_pk_mul_f32 v[240:241], v[144:145], v[80:81]
	v_pk_mul_f32 v[242:243], v[146:147], v[82:83]
	v_cvt_pk_bf16_f32 v236, v236, v237
	v_cvt_pk_bf16_f32 v237, v238, v239
	v_cvt_pk_bf16_f32 v238, v240, v241
	v_cvt_pk_bf16_f32 v239, v242, v243
	global_store_dwordx4 v208, v[236:239], s[64:65] offset:256 sc1
	ds_bpermute_b32 v211, v203, v210
	v_permlane16_swap_b32_e32 v92, v88
	v_permlane16_swap_b32_e32 v93, v89
	v_permlane16_swap_b32_e32 v94, v90
	v_permlane16_swap_b32_e32 v95, v91
	v_permlane16_swap_b32_e32 v84, v80
	v_permlane16_swap_b32_e32 v85, v81
	v_permlane16_swap_b32_e32 v86, v82
	v_permlane16_swap_b32_e32 v87, v83
	v_permlane32_swap_b32_e32 v92, v88
	v_permlane32_swap_b32_e32 v93, v89
	v_permlane32_swap_b32_e32 v94, v90
	v_permlane32_swap_b32_e32 v95, v91
	v_permlane32_swap_b32_e32 v84, v80
	v_permlane32_swap_b32_e32 v85, v81
	v_permlane32_swap_b32_e32 v86, v82
	v_permlane32_swap_b32_e32 v87, v83
	global_store_dwordx4 v207, v[92:95], s[92:93] sc1
	global_store_dwordx4 v207, v[88:91], s[92:93] offset:64 sc1
	global_store_dwordx4 v207, v[84:87], s[92:93] offset:512 sc1
	global_store_dwordx4 v207, v[80:83], s[92:93] offset:576 sc1
	v_add_u32_e32 v207, 0x10000, v207
	v_add_u32_e32 v206, 0x50000, v206
	global_load_dwordx4 v[232:235], v206, s[82:83] offset:64
	global_load_dwordx4 v[240:243], v206, s[82:83] offset:576
	global_load_dwordx4 v[228:231], v206, s[82:83]
	global_load_dwordx4 v[236:239], v206, s[82:83] offset:512
	s_waitcnt lgkmcnt(0)
; DI u32x4 pack8(const float* v) { u32x4 w; w.x = pk2(v[0], v[1]); w.y = pk2(v[2], v[3]); w.z = pk2(v[4], v[5]); w.w = pk2(v[6], v[7]); return w; }
; #define xor16_32(s) xor16_32_l((s), fr + 16 * fq)
;     DI void operator()(AccRef acc, const Unit& u, int wr, int wc, int fr, int fq) const {
;     ...
; #pragma unroll
;         for (int ai = 0; ai < 2; ++ai) {
;             const int rb = u.pm * 256 + ai * 128 + wr * 64 + fr;
;             int mb, pos0, kv0; row_info(rb, mb, pos0, kv0);
;             f32x4 gt[2][2], gs[2][2];
; #pragma unroll
;             for (int bj = 0; bj < 2; ++bj)
; #pragma unroll
;                 for (int n = 0; n < 2; ++n) {
;                     const int c = u.pn * 256 + bj * 128 + cl + 4 * n;
;                     gt[bj][n] = *(const f32x4*)(gate + (size_t)mb * 6144 + c);
;                     if (ap) { const f32x4 g = *(const f32x4*)(gn + c), s = *(const f32x4*)(scn + (size_t)mb * 6144 + c); gs[bj][n] = g * (s + 1.f); }
;                 }
; #pragma unroll
;             for (int m = 0; m < 4; ++m) {
;                 const int row = rb + 16 * m;
;                 const float* xi = row < MP ? xin_p + (size_t)row * 1024 : xin_s + (size_t)(row - MP) * 1024;
;                 float s = 0.f;
; #pragma unroll
;                 for (int bj = 0; bj < 2; ++bj) {
;                     const int c = u.pn * 256 + bj * 128 + cl;
;                     float v[8];
; #pragma unroll
;                     for (int n = 0; n < 2; ++n) {
;                         const f32x4 x = *(const f32x4*)(xi + c + 4 * n);
;                         const f32x4 y = x + gt[bj][n] * acc[ai][bj][m][n];
;                         *(f32x4*)(xout + (size_t)row * 1024 + c + 4 * n) = y;
; #pragma unroll
;                         for (int j = 0; j < 4; ++j) { s += y[j] * y[j]; v[4 * n + j] = ap ? y[j] * gs[bj][n][j] : 0.f; }
;                     }
;                     if (ap) *(u32x4*)(ap + (size_t)row * 1024 + c) = pack8(v);
;                 }
;                 s = xor16_32(s);
;                 if (fq == 0) ssq[(size_t)row * 16 + u.pn * 4 + wc] = s;
;             }
	v_add_f32_e32 v211, v210, v211
	ds_bpermute_b32 v212, v202, v211
	v_add_u32_e32 v208, 0x8000, v208
	s_waitcnt lgkmcnt(0)
	v_add_f32_e32 v211, v211, v212
	s_mov_b64 exec, 0xffff
	global_store_dword v209, v211, s[90:91] sc1
	s_mov_b64 exec, -1
	v_add_u32_e32 v209, 0x400, v209
	s_waitcnt vmcnt(12)
	v_permlane32_swap_b32_e32 v244, v248
	v_permlane32_swap_b32_e32 v245, v249
	v_permlane32_swap_b32_e32 v246, v250
	v_permlane32_swap_b32_e32 v247, v251
	v_permlane32_swap_b32_e32 v216, v220
	v_permlane32_swap_b32_e32 v217, v221
	v_permlane32_swap_b32_e32 v218, v222
	v_permlane32_swap_b32_e32 v219, v223
	v_permlane16_swap_b32_e32 v244, v248
	v_permlane16_swap_b32_e32 v245, v249
	v_permlane16_swap_b32_e32 v246, v250
	v_permlane16_swap_b32_e32 v247, v251
	v_permlane16_swap_b32_e32 v216, v220
	v_permlane16_swap_b32_e32 v217, v221
	v_permlane16_swap_b32_e32 v218, v222
	v_permlane16_swap_b32_e32 v219, v223
	v_pk_fma_f32 v[76:77], v[76:77], v[116:117], v[244:245]
	v_pk_fma_f32 v[78:79], v[78:79], v[118:119], v[246:247]
	v_mul_f32_e32 v210, v77, v77
	v_fmac_f32_e32 v210, v76, v76
	v_fmac_f32_e32 v210, v78, v78
	v_fmac_f32_e32 v210, v79, v79
	v_pk_mul_f32 v[244:245], v[164:165], v[76:77]
	v_pk_mul_f32 v[246:247], v[166:167], v[78:79]
	v_pk_fma_f32 v[72:73], v[72:73], v[108:109], v[248:249]
	v_pk_fma_f32 v[74:75], v[74:75], v[110:111], v[250:251]
	v_fmac_f32_e32 v210, v72, v72
	v_fmac_f32_e32 v210, v73, v73
	v_fmac_f32_e32 v210, v74, v74
	v_fmac_f32_e32 v210, v75, v75
	v_pk_mul_f32 v[248:249], v[162:163], v[72:73]
	v_pk_mul_f32 v[250:251], v[160:161], v[74:75]
	v_cvt_pk_bf16_f32 v244, v244, v245
	v_cvt_pk_bf16_f32 v245, v246, v247
	v_cvt_pk_bf16_f32 v246, v248, v249
	v_cvt_pk_bf16_f32 v247, v250, v251
	global_store_dwordx4 v208, v[244:247], s[64:65] sc1
	v_pk_fma_f32 v[68:69], v[68:69], v[104:105], v[216:217]
	v_pk_fma_f32 v[70:71], v[70:71], v[106:107], v[218:219]
	v_fmac_f32_e32 v210, v68, v68
	v_fmac_f32_e32 v210, v69, v69
	v_fmac_f32_e32 v210, v70, v70
	v_fmac_f32_e32 v210, v71, v71
	v_pk_mul_f32 v[216:217], v[150:151], v[68:69]
	v_pk_mul_f32 v[218:219], v[148:149], v[70:71]
	v_pk_fma_f32 v[64:65], v[64:65], v[100:101], v[220:221]
	v_pk_fma_f32 v[66:67], v[66:67], v[102:103], v[222:223]
	v_fmac_f32_e32 v210, v64, v64
	v_fmac_f32_e32 v210, v65, v65
	v_fmac_f32_e32 v210, v66, v66
	v_fmac_f32_e32 v210, v67, v67
	v_pk_mul_f32 v[220:221], v[144:145], v[64:65]
	v_pk_mul_f32 v[222:223], v[146:147], v[66:67]
	v_cvt_pk_bf16_f32 v216, v216, v217
	v_cvt_pk_bf16_f32 v217, v218, v219
	v_cvt_pk_bf16_f32 v218, v220, v221
	v_cvt_pk_bf16_f32 v219, v222, v223
	global_store_dwordx4 v208, v[216:219], s[64:65] offset:256 sc1
	ds_bpermute_b32 v211, v203, v210
	v_permlane16_swap_b32_e32 v76, v72
	v_permlane16_swap_b32_e32 v77, v73
	v_permlane16_swap_b32_e32 v78, v74
	v_permlane16_swap_b32_e32 v79, v75
	v_permlane16_swap_b32_e32 v68, v64
	v_permlane16_swap_b32_e32 v69, v65
	v_permlane16_swap_b32_e32 v70, v66
	v_permlane16_swap_b32_e32 v71, v67
	v_permlane32_swap_b32_e32 v76, v72
	v_permlane32_swap_b32_e32 v77, v73
	v_permlane32_swap_b32_e32 v78, v74
	v_permlane32_swap_b32_e32 v79, v75
	v_permlane32_swap_b32_e32 v68, v64
	v_permlane32_swap_b32_e32 v69, v65
	v_permlane32_swap_b32_e32 v70, v66
	v_permlane32_swap_b32_e32 v71, v67
	global_store_dwordx4 v207, v[76:79], s[92:93] sc1
	global_store_dwordx4 v207, v[72:75], s[92:93] offset:64 sc1
	global_store_dwordx4 v207, v[68:71], s[92:93] offset:512 sc1
	global_store_dwordx4 v207, v[64:67], s[92:93] offset:576 sc1
	v_add_u32_e32 v207, 0x50000, v207
	v_add_u32_e32 v206, 0x10000, v206
	global_load_dwordx4 v[248:251], v206, s[82:83] offset:64
	global_load_dwordx4 v[220:223], v206, s[82:83] offset:576
	global_load_dwordx4 v[244:247], v206, s[82:83]
	global_load_dwordx4 v[216:219], v206, s[82:83] offset:512
	s_waitcnt lgkmcnt(0)
	v_add_f32_e32 v211, v210, v211
	ds_bpermute_b32 v212, v202, v211
	v_add_u32_e32 v208, 0x28000, v208
	s_waitcnt lgkmcnt(0)
	v_add_f32_e32 v211, v211, v212
	s_mov_b64 exec, 0xffff
	global_store_dword v209, v211, s[90:91] sc1
	s_mov_b64 exec, -1
	v_add_u32_e32 v209, 0x1400, v209
	v_add_u32_e32 v224, 0xffffc080, v192
	v_add_u32_e32 v112, 0x80, v192
	s_waitcnt lgkmcnt(0)
	v_lshrrev_b32_e32 v65, 6, v224
	v_ashrrev_i32_e32 v64, 11, v112
	v_add_u32_e32 v65, 8, v65
	v_cmp_gt_i32_e64 s[2:3], s94, v112
	v_mov_b64_e32 v[66:67], s[60:61]
	s_nop 0
	v_cndmask_b32_e64 v68, v65, v64, s[2:3]
	v_mov_b64_e32 v[64:65], s[8:9]
	v_mad_i64_i32 v[64:65], s[2:3], v68, s75, v[64:65]
	v_mad_i64_i32 v[66:67], s[2:3], v68, s75, v[66:67]
	v_lshl_add_u64 v[68:69], v[64:65], 0, v[190:191]
	v_lshl_add_u64 v[104:105], v[66:67], 0, v[190:191]
	global_load_dwordx4 v[72:75], v[68:69], off offset:16
	global_load_dwordx4 v[76:79], v[68:69], off
	global_load_dwordx4 v[84:87], v[194:195], off offset:16
	global_load_dwordx4 v[100:103], v[194:195], off
	global_load_dwordx4 v[96:99], v[104:105], off offset:16
	global_load_dwordx4 v[108:111], v[104:105], off
	global_load_dwordx4 v[64:67], v[68:69], off offset:528
	s_nop 0
	global_load_dwordx4 v[68:71], v[68:69], off offset:512
	s_nop 0
	global_load_dwordx4 v[80:83], v[194:195], off offset:528
	global_load_dwordx4 v[92:95], v[194:195], off offset:512
	global_load_dwordx4 v[88:91], v[104:105], off offset:528
	s_nop 0
	global_load_dwordx4 v[104:107], v[104:105], off offset:512
	s_movk_i32 s2, 0x3fff
	v_cmp_lt_i32_e64 s[2:3], s2, v112
	s_and_saveexec_b64 s[12:13], s[2:3]
	s_xor_b64 s[2:3], exec, s[12:13]
	v_lshlrev_b64 v[114:115], 12, v[224:225]
	v_mov_b32_e32 v113, v225
	v_lshl_add_u64 v[116:117], s[20:21], 0, v[114:115]
	v_lshlrev_b64 v[114:115], 12, v[112:113]
	s_andn2_saveexec_b64 s[2:3], s[2:3]
	v_ashrrev_i32_e32 v113, 31, v112
	v_lshlrev_b64 v[114:115], 12, v[112:113]
	v_lshl_add_u64 v[116:117], s[42:43], 0, v[114:115]
	s_or_b64 exec, exec, s[2:3]
	s_waitcnt vmcnt(6)
; DI u32x4 pack8(const float* v) { u32x4 w; w.x = pk2(v[0], v[1]); w.y = pk2(v[2], v[3]); w.z = pk2(v[4], v[5]); w.w = pk2(v[6], v[7]); return w; }
; #define xor16_32(s) xor16_32_l((s), fr + 16 * fq)
;     DI void operator()(AccRef acc, const Unit& u, int wr, int wc, int fr, int fq) const {
;     ...
; #pragma unroll
;         for (int ai = 0; ai < 2; ++ai) {
;             const int rb = u.pm * 256 + ai * 128 + wr * 64 + fr;
;             int mb, pos0, kv0; row_info(rb, mb, pos0, kv0);
;             f32x4 gt[2][2], gs[2][2];
; #pragma unroll
;             for (int bj = 0; bj < 2; ++bj)
; #pragma unroll
;                 for (int n = 0; n < 2; ++n) {
;                     const int c = u.pn * 256 + bj * 128 + cl + 4 * n;
;                     gt[bj][n] = *(const f32x4*)(gate + (size_t)mb * 6144 + c);
;                     if (ap) { const f32x4 g = *(const f32x4*)(gn + c), s = *(const f32x4*)(scn + (size_t)mb * 6144 + c); gs[bj][n] = g * (s + 1.f); }
;                 }
; #pragma unroll
;             for (int m = 0; m < 4; ++m) {
;                 const int row = rb + 16 * m;
;                 const float* xi = row < MP ? xin_p + (size_t)row * 1024 : xin_s + (size_t)(row - MP) * 1024;
;                 float s = 0.f;
; #pragma unroll
;                 for (int bj = 0; bj < 2; ++bj) {
;                     const int c = u.pn * 256 + bj * 128 + cl;
;                     float v[8];
; #pragma unroll
;                     for (int n = 0; n < 2; ++n) {
;                         const f32x4 x = *(const f32x4*)(xi + c + 4 * n);
;                         const f32x4 y = x + gt[bj][n] * acc[ai][bj][m][n];
;                         *(f32x4*)(xout + (size_t)row * 1024 + c + 4 * n) = y;
; #pragma unroll
;                         for (int j = 0; j < 4; ++j) { s += y[j] * y[j]; v[4 * n + j] = ap ? y[j] * gs[bj][n][j] : 0.f; }
;                     }
;                     if (ap) *(u32x4*)(ap + (size_t)row * 1024 + c) = pack8(v);
;                 }
;                 s = xor16_32(s);
;                 if (fq == 0) ssq[(size_t)row * 16 + u.pn * 4 + wc] = s;
;             }
	v_pk_add_f32 v[108:109], v[108:109], 1.0 op_sel_hi:[1,0]
	s_waitcnt vmcnt(1)
	v_pk_add_f32 v[90:91], v[90:91], 1.0 op_sel_hi:[1,0]
	v_pk_mul_f32 v[100:101], v[100:101], v[108:109]
	v_pk_add_f32 v[108:109], v[96:97], 1.0 op_sel_hi:[1,0]
	v_pk_add_f32 v[96:97], v[98:99], 1.0 op_sel_hi:[1,0]
	v_pk_mul_f32 v[98:99], v[84:85], v[108:109]
	v_pk_mul_f32 v[96:97], v[86:87], v[96:97]
	s_waitcnt vmcnt(0)
	v_pk_add_f32 v[84:85], v[106:107], 1.0 op_sel_hi:[1,0]
	v_pk_add_f32 v[86:87], v[104:105], 1.0 op_sel_hi:[1,0]
	v_pk_mul_f32 v[82:83], v[82:83], v[90:91]
	v_lshl_add_u64 v[90:91], v[116:117], 0, v[190:191]
	v_pk_mul_f32 v[84:85], v[94:95], v[84:85]
	v_pk_mul_f32 v[86:87], v[92:93], v[86:87]
	v_pk_add_f32 v[110:111], v[110:111], 1.0 op_sel_hi:[1,0]
	v_pk_add_f32 v[88:89], v[88:89], 1.0 op_sel_hi:[1,0]
	v_pk_mul_f32 v[102:103], v[102:103], v[110:111]
	v_pk_mul_f32 v[80:81], v[80:81], v[88:89]
	v_lshlrev_b64 v[88:89], 11, v[112:113]
	v_lshl_add_u64 v[88:89], s[64:65], 0, v[88:89]
	v_permlane32_swap_b32_e32 v228, v232
	v_permlane32_swap_b32_e32 v229, v233
	v_permlane32_swap_b32_e32 v230, v234
	v_permlane32_swap_b32_e32 v231, v235
	v_permlane32_swap_b32_e32 v236, v240
	v_permlane32_swap_b32_e32 v237, v241
	v_permlane32_swap_b32_e32 v238, v242
	v_permlane32_swap_b32_e32 v239, v243
	v_permlane16_swap_b32_e32 v228, v232
	v_permlane16_swap_b32_e32 v229, v233
	v_permlane16_swap_b32_e32 v230, v234
	v_permlane16_swap_b32_e32 v231, v235
	v_permlane16_swap_b32_e32 v236, v240
	v_permlane16_swap_b32_e32 v237, v241
	v_permlane16_swap_b32_e32 v238, v242
	v_permlane16_swap_b32_e32 v239, v243
	v_pk_fma_f32 v[60:61], v[60:61], v[76:77], v[228:229]
	v_pk_fma_f32 v[62:63], v[62:63], v[78:79], v[230:231]
	v_mul_f32_e32 v210, v61, v61
	v_fmac_f32_e32 v210, v60, v60
	v_fmac_f32_e32 v210, v62, v62
	v_fmac_f32_e32 v210, v63, v63
	v_pk_mul_f32 v[228:229], v[100:101], v[60:61]
	v_pk_mul_f32 v[230:231], v[102:103], v[62:63]
	v_pk_fma_f32 v[56:57], v[56:57], v[72:73], v[232:233]
	v_pk_fma_f32 v[58:59], v[58:59], v[74:75], v[234:235]
	v_fmac_f32_e32 v210, v56, v56
	v_fmac_f32_e32 v210, v57, v57
	v_fmac_f32_e32 v210, v58, v58
	v_fmac_f32_e32 v210, v59, v59
	v_pk_mul_f32 v[232:233], v[98:99], v[56:57]
	v_pk_mul_f32 v[234:235], v[96:97], v[58:59]
	v_cvt_pk_bf16_f32 v228, v228, v229
	v_cvt_pk_bf16_f32 v229, v230, v231
	v_cvt_pk_bf16_f32 v230, v232, v233
	v_cvt_pk_bf16_f32 v231, v234, v235
	global_store_dwordx4 v208, v[228:231], s[64:65] sc1
	v_pk_fma_f32 v[52:53], v[52:53], v[68:69], v[236:237]
	v_pk_fma_f32 v[54:55], v[54:55], v[70:71], v[238:239]
	v_fmac_f32_e32 v210, v52, v52
	v_fmac_f32_e32 v210, v53, v53
	v_fmac_f32_e32 v210, v54, v54
	v_fmac_f32_e32 v210, v55, v55
	v_pk_mul_f32 v[236:237], v[86:87], v[52:53]
	v_pk_mul_f32 v[238:239], v[84:85], v[54:55]
	v_pk_fma_f32 v[48:49], v[48:49], v[64:65], v[240:241]
	v_pk_fma_f32 v[50:51], v[50:51], v[66:67], v[242:243]
	v_fmac_f32_e32 v210, v48, v48
	v_fmac_f32_e32 v210, v49, v49
	v_fmac_f32_e32 v210, v50, v50
	v_fmac_f32_e32 v210, v51, v51
	v_pk_mul_f32 v[240:241], v[80:81], v[48:49]
	v_pk_mul_f32 v[242:243], v[82:83], v[50:51]
	v_cvt_pk_bf16_f32 v236, v236, v237
	v_cvt_pk_bf16_f32 v237, v238, v239
	v_cvt_pk_bf16_f32 v238, v240, v241
	v_cvt_pk_bf16_f32 v239, v242, v243
	global_store_dwordx4 v208, v[236:239], s[64:65] offset:256 sc1
	ds_bpermute_b32 v211, v203, v210
	v_permlane16_swap_b32_e32 v60, v56
	v_permlane16_swap_b32_e32 v61, v57
	v_permlane16_swap_b32_e32 v62, v58
	v_permlane16_swap_b32_e32 v63, v59
	v_permlane16_swap_b32_e32 v52, v48
	v_permlane16_swap_b32_e32 v53, v49
	v_permlane16_swap_b32_e32 v54, v50
	v_permlane16_swap_b32_e32 v55, v51
	v_permlane32_swap_b32_e32 v60, v56
	v_permlane32_swap_b32_e32 v61, v57
	v_permlane32_swap_b32_e32 v62, v58
	v_permlane32_swap_b32_e32 v63, v59
	v_permlane32_swap_b32_e32 v52, v48
	v_permlane32_swap_b32_e32 v53, v49
	v_permlane32_swap_b32_e32 v54, v50
	v_permlane32_swap_b32_e32 v55, v51
	global_store_dwordx4 v207, v[60:63], s[92:93] sc1
	global_store_dwordx4 v207, v[56:59], s[92:93] offset:64 sc1
	global_store_dwordx4 v207, v[52:55], s[92:93] offset:512 sc1
	global_store_dwordx4 v207, v[48:51], s[92:93] offset:576 sc1
	v_add_u32_e32 v207, 0x10000, v207
	v_add_u32_e32 v206, 0x10000, v206
	global_load_dwordx4 v[232:235], v206, s[82:83] offset:64
	global_load_dwordx4 v[240:243], v206, s[82:83] offset:576
	global_load_dwordx4 v[228:231], v206, s[82:83]
	global_load_dwordx4 v[236:239], v206, s[82:83] offset:512
	s_waitcnt lgkmcnt(0)
	v_add_f32_e32 v211, v210, v211
	ds_bpermute_b32 v212, v202, v211
	v_add_u32_e32 v208, 0x8000, v208
	s_waitcnt lgkmcnt(0)
; DI u32x4 pack8(const float* v) { u32x4 w; w.x = pk2(v[0], v[1]); w.y = pk2(v[2], v[3]); w.z = pk2(v[4], v[5]); w.w = pk2(v[6], v[7]); return w; }
; #define xor16_32(s) xor16_32_l((s), fr + 16 * fq)
;     DI void operator()(AccRef acc, const Unit& u, int wr, int wc, int fr, int fq) const {
;     ...
;             for (int m = 0; m < 4; ++m) {
;                 const int row = rb + 16 * m;
;                 const float* xi = row < MP ? xin_p + (size_t)row * 1024 : xin_s + (size_t)(row - MP) * 1024;
;                 float s = 0.f;
; #pragma unroll
;                 for (int bj = 0; bj < 2; ++bj) {
;                     const int c = u.pn * 256 + bj * 128 + cl;
;                     float v[8];
; #pragma unroll
;                     for (int n = 0; n < 2; ++n) {
;                         const f32x4 x = *(const f32x4*)(xi + c + 4 * n);
;                         const f32x4 y = x + gt[bj][n] * acc[ai][bj][m][n];
;                         *(f32x4*)(xout + (size_t)row * 1024 + c + 4 * n) = y;
; #pragma unroll
;                         for (int j = 0; j < 4; ++j) { s += y[j] * y[j]; v[4 * n + j] = ap ? y[j] * gs[bj][n][j] : 0.f; }
;                     }
;                     if (ap) *(u32x4*)(ap + (size_t)row * 1024 + c) = pack8(v);
;                 }
;                 s = xor16_32(s);
;                 if (fq == 0) ssq[(size_t)row * 16 + u.pn * 4 + wc] = s;
;             }
	v_add_f32_e32 v211, v211, v212
	s_mov_b64 exec, 0xffff
	global_store_dword v209, v211, s[90:91] sc1
	s_mov_b64 exec, -1
	v_add_u32_e32 v209, 0x400, v209
	v_permlane32_swap_b32_e32 v244, v248
	v_permlane32_swap_b32_e32 v245, v249
	v_permlane32_swap_b32_e32 v246, v250
	v_permlane32_swap_b32_e32 v247, v251
	v_permlane32_swap_b32_e32 v216, v220
	v_permlane32_swap_b32_e32 v217, v221
	v_permlane32_swap_b32_e32 v218, v222
	v_permlane32_swap_b32_e32 v219, v223
	v_permlane16_swap_b32_e32 v244, v248
	v_permlane16_swap_b32_e32 v245, v249
	v_permlane16_swap_b32_e32 v246, v250
	v_permlane16_swap_b32_e32 v247, v251
	v_permlane16_swap_b32_e32 v216, v220
	v_permlane16_swap_b32_e32 v217, v221
	v_permlane16_swap_b32_e32 v218, v222
	v_permlane16_swap_b32_e32 v219, v223
	v_pk_fma_f32 v[44:45], v[44:45], v[76:77], v[244:245]
	v_pk_fma_f32 v[46:47], v[46:47], v[78:79], v[246:247]
	v_mul_f32_e32 v210, v45, v45
	v_fmac_f32_e32 v210, v44, v44
	v_fmac_f32_e32 v210, v46, v46
	v_fmac_f32_e32 v210, v47, v47
	v_pk_mul_f32 v[244:245], v[100:101], v[44:45]
	v_pk_mul_f32 v[246:247], v[102:103], v[46:47]
	v_pk_fma_f32 v[40:41], v[40:41], v[72:73], v[248:249]
	v_pk_fma_f32 v[42:43], v[42:43], v[74:75], v[250:251]
	v_fmac_f32_e32 v210, v40, v40
	v_fmac_f32_e32 v210, v41, v41
	v_fmac_f32_e32 v210, v42, v42
	v_fmac_f32_e32 v210, v43, v43
	v_pk_mul_f32 v[248:249], v[98:99], v[40:41]
	v_pk_mul_f32 v[250:251], v[96:97], v[42:43]
	v_cvt_pk_bf16_f32 v244, v244, v245
	v_cvt_pk_bf16_f32 v245, v246, v247
	v_cvt_pk_bf16_f32 v246, v248, v249
	v_cvt_pk_bf16_f32 v247, v250, v251
	global_store_dwordx4 v208, v[244:247], s[64:65] sc1
	v_pk_fma_f32 v[36:37], v[36:37], v[68:69], v[216:217]
	v_pk_fma_f32 v[38:39], v[38:39], v[70:71], v[218:219]
	v_fmac_f32_e32 v210, v36, v36
	v_fmac_f32_e32 v210, v37, v37
	v_fmac_f32_e32 v210, v38, v38
	v_fmac_f32_e32 v210, v39, v39
	v_pk_mul_f32 v[216:217], v[86:87], v[36:37]
	v_pk_mul_f32 v[218:219], v[84:85], v[38:39]
	v_pk_fma_f32 v[32:33], v[32:33], v[64:65], v[220:221]
	v_pk_fma_f32 v[34:35], v[34:35], v[66:67], v[222:223]
	v_fmac_f32_e32 v210, v32, v32
	v_fmac_f32_e32 v210, v33, v33
	v_fmac_f32_e32 v210, v34, v34
	v_fmac_f32_e32 v210, v35, v35
	v_pk_mul_f32 v[220:221], v[80:81], v[32:33]
	v_pk_mul_f32 v[222:223], v[82:83], v[34:35]
	v_cvt_pk_bf16_f32 v216, v216, v217
	v_cvt_pk_bf16_f32 v217, v218, v219
	v_cvt_pk_bf16_f32 v218, v220, v221
	v_cvt_pk_bf16_f32 v219, v222, v223
	global_store_dwordx4 v208, v[216:219], s[64:65] offset:256 sc1
	ds_bpermute_b32 v211, v203, v210
	v_permlane16_swap_b32_e32 v44, v40
	v_permlane16_swap_b32_e32 v45, v41
	v_permlane16_swap_b32_e32 v46, v42
	v_permlane16_swap_b32_e32 v47, v43
	v_permlane16_swap_b32_e32 v36, v32
	v_permlane16_swap_b32_e32 v37, v33
	v_permlane16_swap_b32_e32 v38, v34
	v_permlane16_swap_b32_e32 v39, v35
	v_permlane32_swap_b32_e32 v44, v40
	v_permlane32_swap_b32_e32 v45, v41
	v_permlane32_swap_b32_e32 v46, v42
	v_permlane32_swap_b32_e32 v47, v43
	v_permlane32_swap_b32_e32 v36, v32
	v_permlane32_swap_b32_e32 v37, v33
	v_permlane32_swap_b32_e32 v38, v34
	v_permlane32_swap_b32_e32 v39, v35
	global_store_dwordx4 v207, v[44:47], s[92:93] sc1
	global_store_dwordx4 v207, v[40:43], s[92:93] offset:64 sc1
	global_store_dwordx4 v207, v[36:39], s[92:93] offset:512 sc1
	global_store_dwordx4 v207, v[32:35], s[92:93] offset:576 sc1
	v_add_u32_e32 v207, 0x10000, v207
	v_add_u32_e32 v206, 0x10000, v206
	global_load_dwordx4 v[248:251], v206, s[82:83] offset:64
	global_load_dwordx4 v[220:223], v206, s[82:83] offset:576
	global_load_dwordx4 v[244:247], v206, s[82:83]
	global_load_dwordx4 v[216:219], v206, s[82:83] offset:512
	s_waitcnt lgkmcnt(0)
	v_add_f32_e32 v211, v210, v211
	ds_bpermute_b32 v212, v202, v211
	v_add_u32_e32 v208, 0x8000, v208
	s_waitcnt lgkmcnt(0)
	v_add_f32_e32 v211, v211, v212
	s_mov_b64 exec, 0xffff
	global_store_dword v209, v211, s[90:91] sc1
	s_mov_b64 exec, -1
	v_add_u32_e32 v209, 0x400, v209
	s_waitcnt vmcnt(12)
; DI u32x4 pack8(const float* v) { u32x4 w; w.x = pk2(v[0], v[1]); w.y = pk2(v[2], v[3]); w.z = pk2(v[4], v[5]); w.w = pk2(v[6], v[7]); return w; }
; #define xor16_32(s) xor16_32_l((s), fr + 16 * fq)
;     DI void operator()(AccRef acc, const Unit& u, int wr, int wc, int fr, int fq) const {
;     ...
;             for (int m = 0; m < 4; ++m) {
;                 const int row = rb + 16 * m;
;                 const float* xi = row < MP ? xin_p + (size_t)row * 1024 : xin_s + (size_t)(row - MP) * 1024;
;                 float s = 0.f;
; #pragma unroll
;                 for (int bj = 0; bj < 2; ++bj) {
;                     const int c = u.pn * 256 + bj * 128 + cl;
;                     float v[8];
; #pragma unroll
;                     for (int n = 0; n < 2; ++n) {
;                         const f32x4 x = *(const f32x4*)(xi + c + 4 * n);
;                         const f32x4 y = x + gt[bj][n] * acc[ai][bj][m][n];
;                         *(f32x4*)(xout + (size_t)row * 1024 + c + 4 * n) = y;
; #pragma unroll
;                         for (int j = 0; j < 4; ++j) { s += y[j] * y[j]; v[4 * n + j] = ap ? y[j] * gs[bj][n][j] : 0.f; }
;                     }
;                     if (ap) *(u32x4*)(ap + (size_t)row * 1024 + c) = pack8(v);
;                 }
;                 s = xor16_32(s);
;                 if (fq == 0) ssq[(size_t)row * 16 + u.pn * 4 + wc] = s;
;             }
	v_permlane32_swap_b32_e32 v228, v232
	v_permlane32_swap_b32_e32 v229, v233
	v_permlane32_swap_b32_e32 v230, v234
	v_permlane32_swap_b32_e32 v231, v235
	v_permlane32_swap_b32_e32 v236, v240
	v_permlane32_swap_b32_e32 v237, v241
	v_permlane32_swap_b32_e32 v238, v242
	v_permlane32_swap_b32_e32 v239, v243
	v_permlane16_swap_b32_e32 v228, v232
	v_permlane16_swap_b32_e32 v229, v233
	v_permlane16_swap_b32_e32 v230, v234
	v_permlane16_swap_b32_e32 v231, v235
	v_permlane16_swap_b32_e32 v236, v240
	v_permlane16_swap_b32_e32 v237, v241
	v_permlane16_swap_b32_e32 v238, v242
	v_permlane16_swap_b32_e32 v239, v243
	v_pk_fma_f32 v[28:29], v[28:29], v[76:77], v[228:229]
	v_pk_fma_f32 v[30:31], v[30:31], v[78:79], v[230:231]
	v_mul_f32_e32 v210, v29, v29
	v_fmac_f32_e32 v210, v28, v28
	v_fmac_f32_e32 v210, v30, v30
	v_fmac_f32_e32 v210, v31, v31
	v_pk_mul_f32 v[228:229], v[100:101], v[28:29]
	v_pk_mul_f32 v[230:231], v[102:103], v[30:31]
	v_pk_fma_f32 v[24:25], v[24:25], v[72:73], v[232:233]
	v_pk_fma_f32 v[26:27], v[26:27], v[74:75], v[234:235]
	v_fmac_f32_e32 v210, v24, v24
	v_fmac_f32_e32 v210, v25, v25
	v_fmac_f32_e32 v210, v26, v26
	v_fmac_f32_e32 v210, v27, v27
	v_pk_mul_f32 v[232:233], v[98:99], v[24:25]
	v_pk_mul_f32 v[234:235], v[96:97], v[26:27]
	v_cvt_pk_bf16_f32 v228, v228, v229
	v_cvt_pk_bf16_f32 v229, v230, v231
	v_cvt_pk_bf16_f32 v230, v232, v233
	v_cvt_pk_bf16_f32 v231, v234, v235
	global_store_dwordx4 v208, v[228:231], s[64:65] sc1
	v_pk_fma_f32 v[20:21], v[20:21], v[68:69], v[236:237]
	v_pk_fma_f32 v[22:23], v[22:23], v[70:71], v[238:239]
	v_fmac_f32_e32 v210, v20, v20
	v_fmac_f32_e32 v210, v21, v21
	v_fmac_f32_e32 v210, v22, v22
	v_fmac_f32_e32 v210, v23, v23
	v_pk_mul_f32 v[236:237], v[86:87], v[20:21]
	v_pk_mul_f32 v[238:239], v[84:85], v[22:23]
	v_pk_fma_f32 v[16:17], v[16:17], v[64:65], v[240:241]
	v_pk_fma_f32 v[18:19], v[18:19], v[66:67], v[242:243]
	v_fmac_f32_e32 v210, v16, v16
	v_fmac_f32_e32 v210, v17, v17
	v_fmac_f32_e32 v210, v18, v18
	v_fmac_f32_e32 v210, v19, v19
	v_pk_mul_f32 v[240:241], v[80:81], v[16:17]
	v_pk_mul_f32 v[242:243], v[82:83], v[18:19]
	v_cvt_pk_bf16_f32 v236, v236, v237
	v_cvt_pk_bf16_f32 v237, v238, v239
	v_cvt_pk_bf16_f32 v238, v240, v241
	v_cvt_pk_bf16_f32 v239, v242, v243
	global_store_dwordx4 v208, v[236:239], s[64:65] offset:256 sc1
	ds_bpermute_b32 v211, v203, v210
	v_permlane16_swap_b32_e32 v28, v24
	v_permlane16_swap_b32_e32 v29, v25
	v_permlane16_swap_b32_e32 v30, v26
	v_permlane16_swap_b32_e32 v31, v27
	v_permlane16_swap_b32_e32 v20, v16
	v_permlane16_swap_b32_e32 v21, v17
	v_permlane16_swap_b32_e32 v22, v18
	v_permlane16_swap_b32_e32 v23, v19
	v_permlane32_swap_b32_e32 v28, v24
	v_permlane32_swap_b32_e32 v29, v25
	v_permlane32_swap_b32_e32 v30, v26
	v_permlane32_swap_b32_e32 v31, v27
	v_permlane32_swap_b32_e32 v20, v16
	v_permlane32_swap_b32_e32 v21, v17
	v_permlane32_swap_b32_e32 v22, v18
	v_permlane32_swap_b32_e32 v23, v19
	global_store_dwordx4 v207, v[28:31], s[92:93] sc1
	global_store_dwordx4 v207, v[24:27], s[92:93] offset:64 sc1
	global_store_dwordx4 v207, v[20:23], s[92:93] offset:512 sc1
	global_store_dwordx4 v207, v[16:19], s[92:93] offset:576 sc1
	v_add_u32_e32 v207, 0x10000, v207
	s_waitcnt lgkmcnt(0)
	v_add_f32_e32 v211, v210, v211
	ds_bpermute_b32 v212, v202, v211
	v_add_u32_e32 v208, 0x8000, v208
	s_waitcnt lgkmcnt(0)
	v_add_f32_e32 v211, v211, v212
	s_mov_b64 exec, 0xffff
	global_store_dword v209, v211, s[90:91] sc1
	s_mov_b64 exec, -1
	v_add_u32_e32 v209, 0x400, v209
	s_waitcnt vmcnt(8)
	v_permlane32_swap_b32_e32 v244, v248
	v_permlane32_swap_b32_e32 v245, v249
	v_permlane32_swap_b32_e32 v246, v250
	v_permlane32_swap_b32_e32 v247, v251
	v_permlane32_swap_b32_e32 v216, v220
	v_permlane32_swap_b32_e32 v217, v221
	v_permlane32_swap_b32_e32 v218, v222
	v_permlane32_swap_b32_e32 v219, v223
	v_permlane16_swap_b32_e32 v244, v248
	v_permlane16_swap_b32_e32 v245, v249
	v_permlane16_swap_b32_e32 v246, v250
	v_permlane16_swap_b32_e32 v247, v251
	v_permlane16_swap_b32_e32 v216, v220
	v_permlane16_swap_b32_e32 v217, v221
	v_permlane16_swap_b32_e32 v218, v222
	v_permlane16_swap_b32_e32 v219, v223
	v_pk_fma_f32 v[12:13], v[12:13], v[76:77], v[244:245]
	v_pk_fma_f32 v[14:15], v[14:15], v[78:79], v[246:247]
	v_mul_f32_e32 v210, v13, v13
	v_fmac_f32_e32 v210, v12, v12
	v_fmac_f32_e32 v210, v14, v14
	v_fmac_f32_e32 v210, v15, v15
	v_pk_mul_f32 v[244:245], v[100:101], v[12:13]
	v_pk_mul_f32 v[246:247], v[102:103], v[14:15]
	v_pk_fma_f32 v[8:9], v[8:9], v[72:73], v[248:249]
	v_pk_fma_f32 v[10:11], v[10:11], v[74:75], v[250:251]
	v_fmac_f32_e32 v210, v8, v8
	v_fmac_f32_e32 v210, v9, v9
	v_fmac_f32_e32 v210, v10, v10
	v_fmac_f32_e32 v210, v11, v11
	v_pk_mul_f32 v[248:249], v[98:99], v[8:9]
	v_pk_mul_f32 v[250:251], v[96:97], v[10:11]
	v_cvt_pk_bf16_f32 v244, v244, v245
	v_cvt_pk_bf16_f32 v245, v246, v247
	v_cvt_pk_bf16_f32 v246, v248, v249
	v_cvt_pk_bf16_f32 v247, v250, v251
	global_store_dwordx4 v208, v[244:247], s[64:65] sc1
	v_pk_fma_f32 v[4:5], v[4:5], v[68:69], v[216:217]
	v_pk_fma_f32 v[6:7], v[6:7], v[70:71], v[218:219]
	v_fmac_f32_e32 v210, v4, v4
	v_fmac_f32_e32 v210, v5, v5
	v_fmac_f32_e32 v210, v6, v6
	v_fmac_f32_e32 v210, v7, v7
	v_pk_mul_f32 v[216:217], v[86:87], v[4:5]
	v_pk_mul_f32 v[218:219], v[84:85], v[6:7]
	v_pk_fma_f32 v[0:1], v[0:1], v[64:65], v[220:221]
	v_pk_fma_f32 v[2:3], v[2:3], v[66:67], v[222:223]
	v_fmac_f32_e32 v210, v0, v0
	v_fmac_f32_e32 v210, v1, v1
	v_fmac_f32_e32 v210, v2, v2
	v_fmac_f32_e32 v210, v3, v3
	v_pk_mul_f32 v[220:221], v[80:81], v[0:1]
	v_pk_mul_f32 v[222:223], v[82:83], v[2:3]
	v_cvt_pk_bf16_f32 v216, v216, v217
	v_cvt_pk_bf16_f32 v217, v218, v219
	v_cvt_pk_bf16_f32 v218, v220, v221
	v_cvt_pk_bf16_f32 v219, v222, v223
	global_store_dwordx4 v208, v[216:219], s[64:65] offset:256 sc1
	ds_bpermute_b32 v211, v203, v210
	v_permlane16_swap_b32_e32 v12, v8
	v_permlane16_swap_b32_e32 v13, v9
	v_permlane16_swap_b32_e32 v14, v10
	v_permlane16_swap_b32_e32 v15, v11
	v_permlane16_swap_b32_e32 v4, v0
	v_permlane16_swap_b32_e32 v5, v1
	v_permlane16_swap_b32_e32 v6, v2
	v_permlane16_swap_b32_e32 v7, v3
	v_permlane32_swap_b32_e32 v12, v8
	v_permlane32_swap_b32_e32 v13, v9
	v_permlane32_swap_b32_e32 v14, v10
	v_permlane32_swap_b32_e32 v15, v11
	v_permlane32_swap_b32_e32 v4, v0
	v_permlane32_swap_b32_e32 v5, v1
	v_permlane32_swap_b32_e32 v6, v2
	v_permlane32_swap_b32_e32 v7, v3
	global_store_dwordx4 v207, v[12:15], s[92:93] sc1
	global_store_dwordx4 v207, v[8:11], s[92:93] offset:64 sc1
	global_store_dwordx4 v207, v[4:7], s[92:93] offset:512 sc1
	global_store_dwordx4 v207, v[0:3], s[92:93] offset:576 sc1
	s_waitcnt lgkmcnt(0)
	v_add_f32_e32 v211, v210, v211
	ds_bpermute_b32 v212, v202, v211
	s_waitcnt lgkmcnt(0)
	v_add_f32_e32 v211, v211, v212
	s_mov_b64 exec, 0xffff
	global_store_dword v209, v211, s[90:91] sc1
	s_mov_b64 exec, -1
	s_andn2_b64 vcc, exec, s[0:1]
	s_mov_b64 s[0:1], -1
	s_cbranch_vccnz .LBB0_1083
	s_andn2_b64 vcc, exec, s[4:5]
	s_cbranch_vccnz .LBB0_1082
	s_barrier
	s_branch .LBB0_1082

;     DI void operator()(AccRef acc, const Unit& u, int wr, int wc, int fr, int fq) const {
;     ...
; #pragma unroll
;         for (int ai = 0; ai < 2; ++ai) {
;             const int rb = u.pm * 256 + ai * 128 + wr * 64 + fr;
;             int mb, pos0, kv0; row_info(rb, mb, pos0, kv0);
;             f32x4 gt[2][2], gs[2][2];
; #pragma unroll
;             for (int bj = 0; bj < 2; ++bj)
; #pragma unroll
;                 for (int n = 0; n < 2; ++n) {
;                     const int c = u.pn * 256 + bj * 128 + cl + 4 * n;
;                     gt[bj][n] = *(const f32x4*)(gate + (size_t)mb * 6144 + c);
;                     if (ap) { const f32x4 g = *(const f32x4*)(gn + c), s = *(const f32x4*)(scn + (size_t)mb * 6144 + c); gs[bj][n] = g * (s + 1.f); }
;                 }
.LBB0_1303:
	v_readlane_b32 s1, v253, 32
	v_mbcnt_lo_u32_b32 v100, -1, 0
	v_mbcnt_hi_u32_b32 v100, -1, v100
	s_mov_b32 s1, s28
	v_and_b32_e32 v202, 15, v100
	v_bfe_u32 v204, v100, 4, 2
	s_mov_b32 s12, s34
	s_lshl_b32 s16, s16, 8
	s_lshl_b32 s1, s1, 6
	s_add_i32 s1, s1, s16
	v_add_u32_e32 v192, s1, v202
	s_lshl_b32 s13, s12, 5
	s_lshl_b32 s1, s0, 8
	v_add_u32_e32 v224, 0xffffc000, v192
	s_add_i32 s13, s13, s1
	v_lshrrev_b32_e32 v101, 6, v224
	v_lshl_add_u32 v188, v204, 3, s13
	v_ashrrev_i32_e32 v100, 11, v192
	v_add_u32_e32 v101, 8, v101
	v_cmp_gt_i32_e32 vcc, s94, v192
	v_mov_b64_e32 v[102:103], s[56:57]
	v_ashrrev_i32_e32 v189, 31, v188
	v_cndmask_b32_e32 v104, v101, v100, vcc
	v_mov_b64_e32 v[100:101], s[6:7]
	v_mad_i64_i32 v[100:101], s[16:17], v104, s75, v[100:101]
	v_mad_i64_i32 v[102:103], s[16:17], v104, s75, v[102:103]
	v_lshlrev_b64 v[190:191], 2, v[188:189]
	v_lshl_add_u64 v[104:105], v[100:101], 0, v[190:191]
	v_lshl_add_u64 v[194:195], s[72:73], 0, v[190:191]
	v_lshl_add_u64 v[168:169], v[102:103], 0, v[190:191]
	global_load_dwordx4 v[108:111], v[104:105], off offset:16
	global_load_dwordx4 v[116:119], v[104:105], off
	global_load_dwordx4 v[148:151], v[194:195], off offset:16
	global_load_dwordx4 v[164:167], v[194:195], off
	global_load_dwordx4 v[160:163], v[168:169], off offset:16
	global_load_dwordx4 v[172:175], v[168:169], off
	global_load_dwordx4 v[100:103], v[104:105], off offset:528
	s_nop 0
	global_load_dwordx4 v[104:107], v[104:105], off offset:512
	s_nop 0
	global_load_dwordx4 v[144:147], v[194:195], off offset:528
	global_load_dwordx4 v[156:159], v[194:195], off offset:512
	global_load_dwordx4 v[152:155], v[168:169], off offset:528
	s_nop 0
	global_load_dwordx4 v[168:171], v[168:169], off offset:512
	s_movk_i32 s1, 0x3fff
	v_cmp_lt_i32_e32 vcc, s1, v192
	s_and_saveexec_b64 s[16:17], vcc
	s_xor_b64 s[16:17], exec, s[16:17]
	v_lshlrev_b64 v[196:197], 12, v[224:225]
	v_mov_b32_e32 v193, v225
	v_lshl_add_u64 v[198:199], s[20:21], 0, v[196:197]
	v_lshlrev_b64 v[196:197], 12, v[192:193]
	s_andn2_saveexec_b64 s[16:17], s[16:17]
	v_ashrrev_i32_e32 v193, 31, v192
	v_lshlrev_b64 v[196:197], 12, v[192:193]
	v_lshl_add_u64 v[198:199], s[42:43], 0, v[196:197]
	s_or_b64 exec, exec, s[16:17]
	s_sub_u32 s82, s20, 0x4000000
	s_subb_u32 s83, s21, 0
	s_cmp_ge_u32 s16, 0x4000
	s_cselect_b32 s82, s82, s42
	s_cselect_b32 s83, s83, s43
	v_lshl_add_u32 v206, v192, 12, v190
	v_lshlrev_b32_e32 v213, 4, v204
	v_sub_u32_e32 v206, v206, v213
	v_lshlrev_b32_e32 v213, 11, v192
	v_lshlrev_b32_e32 v209, 6, v192
	v_mov_b32_e32 v207, v206
	v_lshl_add_u32 v208, v188, 1, v213
	global_load_dwordx4 v[232:235], v206, s[82:83] offset:64
	global_load_dwordx4 v[240:243], v206, s[82:83] offset:576
	global_load_dwordx4 v[228:231], v206, s[82:83]
	global_load_dwordx4 v[236:239], v206, s[82:83] offset:512
	v_add_u32_e32 v206, 0x10000, v206
	global_load_dwordx4 v[248:251], v206, s[82:83] offset:64
	global_load_dwordx4 v[220:223], v206, s[82:83] offset:576
	global_load_dwordx4 v[244:247], v206, s[82:83]
	global_load_dwordx4 v[216:219], v206, s[82:83] offset:512
	v_add_u32_e32 v206, 0x10000, v206
	s_waitcnt vmcnt(8)
	v_pk_add_f32 v[172:173], v[172:173], 1.0 op_sel_hi:[1,0]
	v_pk_add_f32 v[154:155], v[154:155], 1.0 op_sel_hi:[1,0]
	v_pk_mul_f32 v[164:165], v[164:165], v[172:173]
	v_pk_add_f32 v[172:173], v[160:161], 1.0 op_sel_hi:[1,0]
	v_pk_add_f32 v[160:161], v[162:163], 1.0 op_sel_hi:[1,0]
	v_pk_mul_f32 v[162:163], v[148:149], v[172:173]
	v_pk_mul_f32 v[160:161], v[150:151], v[160:161]
	v_pk_add_f32 v[148:149], v[170:171], 1.0 op_sel_hi:[1,0]
	v_pk_add_f32 v[150:151], v[168:169], 1.0 op_sel_hi:[1,0]
	v_pk_mul_f32 v[146:147], v[146:147], v[154:155]
	v_lshl_add_u64 v[154:155], v[198:199], 0, v[190:191]
	v_pk_mul_f32 v[148:149], v[158:159], v[148:149]
	v_pk_mul_f32 v[150:151], v[156:157], v[150:151]
	v_pk_add_f32 v[174:175], v[174:175], 1.0 op_sel_hi:[1,0]
	v_pk_add_f32 v[152:153], v[152:153], 1.0 op_sel_hi:[1,0]
	v_pk_mul_f32 v[166:167], v[166:167], v[174:175]
	v_pk_mul_f32 v[144:145], v[144:145], v[152:153]
	v_lshlrev_b64 v[152:153], 11, v[192:193]
	v_lshl_add_u64 v[152:153], s[58:59], 0, v[152:153]
	v_lshlrev_b32_e32 v202, 2, v202
	v_lshl_add_u32 v202, v204, 6, v202
	v_xor_b32_e32 v203, 64, v202
	s_lshl_b32 s0, s0, 2
	v_xor_b32_e32 v202, 0x80, v202
	s_ashr_i32 s1, s0, 31
	s_ashr_i32 s13, s12, 31
	s_lshl_b64 s[0:1], s[0:1], 2
	s_add_u32 s16, s37, s0
	s_addc_u32 s17, s38, s1
	s_lshl_b64 s[0:1], s[12:13], 2
	s_add_u32 s90, s16, s0
	v_cmp_eq_u32_e32 vcc, 0, v204
	s_addc_u32 s91, s17, s1
	s_waitcnt vmcnt(4)
; DI u32x4 pack8(const float* v) { u32x4 w; w.x = pk2(v[0], v[1]); w.y = pk2(v[2], v[3]); w.z = pk2(v[4], v[5]); w.w = pk2(v[6], v[7]); return w; }
; #define xor16_32(s) xor16_32_l((s), fr + 16 * fq)
;     DI void operator()(AccRef acc, const Unit& u, int wr, int wc, int fr, int fq) const {
;     ...
;             for (int m = 0; m < 4; ++m) {
;                 const int row = rb + 16 * m;
;                 const float* xi = row < MP ? xin_p + (size_t)row * 1024 : xin_s + (size_t)(row - MP) * 1024;
;                 float s = 0.f;
; #pragma unroll
;                 for (int bj = 0; bj < 2; ++bj) {
;                     const int c = u.pn * 256 + bj * 128 + cl;
;                     float v[8];
; #pragma unroll
;                     for (int n = 0; n < 2; ++n) {
;                         const f32x4 x = *(const f32x4*)(xi + c + 4 * n);
;                         const f32x4 y = x + gt[bj][n] * acc[ai][bj][m][n];
;                         *(f32x4*)(xout + (size_t)row * 1024 + c + 4 * n) = y;
; #pragma unroll
;                         for (int j = 0; j < 4; ++j) { s += y[j] * y[j]; v[4 * n + j] = ap ? y[j] * gs[bj][n][j] : 0.f; }
;                     }
;                     if (ap) *(u32x4*)(ap + (size_t)row * 1024 + c) = pack8(v);
;                 }
;                 s = xor16_32(s);
;                 if (fq == 0) ssq[(size_t)row * 16 + u.pn * 4 + wc] = s;
;             }
	v_permlane32_swap_b32_e32 v228, v232
	v_permlane32_swap_b32_e32 v229, v233
	v_permlane32_swap_b32_e32 v230, v234
	v_permlane32_swap_b32_e32 v231, v235
	v_permlane32_swap_b32_e32 v236, v240
	v_permlane32_swap_b32_e32 v237, v241
	v_permlane32_swap_b32_e32 v238, v242
	v_permlane32_swap_b32_e32 v239, v243
	v_permlane16_swap_b32_e32 v228, v232
	v_permlane16_swap_b32_e32 v229, v233
	v_permlane16_swap_b32_e32 v230, v234
	v_permlane16_swap_b32_e32 v231, v235
	v_permlane16_swap_b32_e32 v236, v240
	v_permlane16_swap_b32_e32 v237, v241
	v_permlane16_swap_b32_e32 v238, v242
	v_permlane16_swap_b32_e32 v239, v243
	v_pk_fma_f32 v[140:141], v[140:141], v[116:117], v[228:229]
	v_pk_fma_f32 v[142:143], v[142:143], v[118:119], v[230:231]
	v_mul_f32_e32 v210, v141, v141
	v_fmac_f32_e32 v210, v140, v140
	v_fmac_f32_e32 v210, v142, v142
	v_fmac_f32_e32 v210, v143, v143
	v_pk_mul_f32 v[228:229], v[164:165], v[140:141]
	v_pk_mul_f32 v[230:231], v[166:167], v[142:143]
	v_pk_fma_f32 v[136:137], v[136:137], v[108:109], v[232:233]
	v_pk_fma_f32 v[138:139], v[138:139], v[110:111], v[234:235]
	v_fmac_f32_e32 v210, v136, v136
	v_fmac_f32_e32 v210, v137, v137
	v_fmac_f32_e32 v210, v138, v138
	v_fmac_f32_e32 v210, v139, v139
	v_pk_mul_f32 v[232:233], v[162:163], v[136:137]
	v_pk_mul_f32 v[234:235], v[160:161], v[138:139]
	v_cvt_pk_bf16_f32 v228, v228, v229
	v_cvt_pk_bf16_f32 v229, v230, v231
	v_cvt_pk_bf16_f32 v230, v232, v233
	v_cvt_pk_bf16_f32 v231, v234, v235
	global_store_dwordx4 v208, v[228:231], s[58:59] sc1
	v_pk_fma_f32 v[132:133], v[132:133], v[104:105], v[236:237]
	v_pk_fma_f32 v[134:135], v[134:135], v[106:107], v[238:239]
	v_fmac_f32_e32 v210, v132, v132
	v_fmac_f32_e32 v210, v133, v133
	v_fmac_f32_e32 v210, v134, v134
	v_fmac_f32_e32 v210, v135, v135
	v_pk_mul_f32 v[236:237], v[150:151], v[132:133]
	v_pk_mul_f32 v[238:239], v[148:149], v[134:135]
	v_pk_fma_f32 v[128:129], v[128:129], v[100:101], v[240:241]
	v_pk_fma_f32 v[130:131], v[130:131], v[102:103], v[242:243]
	v_fmac_f32_e32 v210, v128, v128
	v_fmac_f32_e32 v210, v129, v129
	v_fmac_f32_e32 v210, v130, v130
	v_fmac_f32_e32 v210, v131, v131
	v_pk_mul_f32 v[240:241], v[144:145], v[128:129]
	v_pk_mul_f32 v[242:243], v[146:147], v[130:131]
	v_cvt_pk_bf16_f32 v236, v236, v237
	v_cvt_pk_bf16_f32 v237, v238, v239
	v_cvt_pk_bf16_f32 v238, v240, v241
	v_cvt_pk_bf16_f32 v239, v242, v243
	global_store_dwordx4 v208, v[236:239], s[58:59] offset:256 sc1
	ds_bpermute_b32 v211, v203, v210
	v_permlane16_swap_b32_e32 v140, v136
	v_permlane16_swap_b32_e32 v141, v137
	v_permlane16_swap_b32_e32 v142, v138
	v_permlane16_swap_b32_e32 v143, v139
	v_permlane16_swap_b32_e32 v132, v128
	v_permlane16_swap_b32_e32 v133, v129
	v_permlane16_swap_b32_e32 v134, v130
	v_permlane16_swap_b32_e32 v135, v131
	v_permlane32_swap_b32_e32 v140, v136
	v_permlane32_swap_b32_e32 v141, v137
	v_permlane32_swap_b32_e32 v142, v138
	v_permlane32_swap_b32_e32 v143, v139
	v_permlane32_swap_b32_e32 v132, v128
	v_permlane32_swap_b32_e32 v133, v129
	v_permlane32_swap_b32_e32 v134, v130
	v_permlane32_swap_b32_e32 v135, v131
	global_store_dwordx4 v207, v[140:143], s[92:93] sc1
	global_store_dwordx4 v207, v[136:139], s[92:93] offset:64 sc1
	global_store_dwordx4 v207, v[132:135], s[92:93] offset:512 sc1
	global_store_dwordx4 v207, v[128:131], s[92:93] offset:576 sc1
	v_add_u32_e32 v207, 0x10000, v207
	global_load_dwordx4 v[232:235], v206, s[82:83] offset:64
	global_load_dwordx4 v[240:243], v206, s[82:83] offset:576
	global_load_dwordx4 v[228:231], v206, s[82:83]
	global_load_dwordx4 v[236:239], v206, s[82:83] offset:512
	s_waitcnt lgkmcnt(0)
	v_add_f32_e32 v211, v210, v211
	ds_bpermute_b32 v212, v202, v211
	v_add_u32_e32 v208, 0x8000, v208
	s_waitcnt lgkmcnt(0)
	v_add_f32_e32 v211, v211, v212
	s_mov_b64 exec, 0xffff
	global_store_dword v209, v211, s[90:91] sc1
	s_mov_b64 exec, -1
	v_add_u32_e32 v209, 0x400, v209
	s_waitcnt vmcnt(11)
	v_permlane32_swap_b32_e32 v244, v248
	v_permlane32_swap_b32_e32 v245, v249
	v_permlane32_swap_b32_e32 v246, v250
	v_permlane32_swap_b32_e32 v247, v251
	v_permlane32_swap_b32_e32 v216, v220
	v_permlane32_swap_b32_e32 v217, v221
	v_permlane32_swap_b32_e32 v218, v222
	v_permlane32_swap_b32_e32 v219, v223
	v_permlane16_swap_b32_e32 v244, v248
	v_permlane16_swap_b32_e32 v245, v249
	v_permlane16_swap_b32_e32 v246, v250
	v_permlane16_swap_b32_e32 v247, v251
	v_permlane16_swap_b32_e32 v216, v220
	v_permlane16_swap_b32_e32 v217, v221
	v_permlane16_swap_b32_e32 v218, v222
	v_permlane16_swap_b32_e32 v219, v223
	v_pk_fma_f32 v[124:125], v[124:125], v[116:117], v[244:245]
	v_pk_fma_f32 v[126:127], v[126:127], v[118:119], v[246:247]
	v_mul_f32_e32 v210, v125, v125
	v_fmac_f32_e32 v210, v124, v124
	v_fmac_f32_e32 v210, v126, v126
	v_fmac_f32_e32 v210, v127, v127
	v_pk_mul_f32 v[244:245], v[164:165], v[124:125]
	v_pk_mul_f32 v[246:247], v[166:167], v[126:127]
	v_pk_fma_f32 v[120:121], v[120:121], v[108:109], v[248:249]
	v_pk_fma_f32 v[122:123], v[122:123], v[110:111], v[250:251]
	v_fmac_f32_e32 v210, v120, v120
	v_fmac_f32_e32 v210, v121, v121
	v_fmac_f32_e32 v210, v122, v122
	v_fmac_f32_e32 v210, v123, v123
	v_pk_mul_f32 v[248:249], v[162:163], v[120:121]
	v_pk_mul_f32 v[250:251], v[160:161], v[122:123]
	v_cvt_pk_bf16_f32 v244, v244, v245
	v_cvt_pk_bf16_f32 v245, v246, v247
	v_cvt_pk_bf16_f32 v246, v248, v249
	v_cvt_pk_bf16_f32 v247, v250, v251
	global_store_dwordx4 v208, v[244:247], s[58:59] sc1
	v_pk_fma_f32 v[112:113], v[112:113], v[104:105], v[216:217]
	v_pk_fma_f32 v[114:115], v[114:115], v[106:107], v[218:219]
	v_fmac_f32_e32 v210, v112, v112
	v_fmac_f32_e32 v210, v113, v113
	v_fmac_f32_e32 v210, v114, v114
	v_fmac_f32_e32 v210, v115, v115
; DI u32x4 pack8(const float* v) { u32x4 w; w.x = pk2(v[0], v[1]); w.y = pk2(v[2], v[3]); w.z = pk2(v[4], v[5]); w.w = pk2(v[6], v[7]); return w; }
; #define xor16_32(s) xor16_32_l((s), fr + 16 * fq)
;     DI void operator()(AccRef acc, const Unit& u, int wr, int wc, int fr, int fq) const {
;     ...
;             for (int m = 0; m < 4; ++m) {
;                 const int row = rb + 16 * m;
;                 const float* xi = row < MP ? xin_p + (size_t)row * 1024 : xin_s + (size_t)(row - MP) * 1024;
;                 float s = 0.f;
; #pragma unroll
;                 for (int bj = 0; bj < 2; ++bj) {
;                     const int c = u.pn * 256 + bj * 128 + cl;
;                     float v[8];
; #pragma unroll
;                     for (int n = 0; n < 2; ++n) {
;                         const f32x4 x = *(const f32x4*)(xi + c + 4 * n);
;                         const f32x4 y = x + gt[bj][n] * acc[ai][bj][m][n];
;                         *(f32x4*)(xout + (size_t)row * 1024 + c + 4 * n) = y;
; #pragma unroll
;                         for (int j = 0; j < 4; ++j) { s += y[j] * y[j]; v[4 * n + j] = ap ? y[j] * gs[bj][n][j] : 0.f; }
;                     }
;                     if (ap) *(u32x4*)(ap + (size_t)row * 1024 + c) = pack8(v);
;                 }
;                 s = xor16_32(s);
;                 if (fq == 0) ssq[(size_t)row * 16 + u.pn * 4 + wc] = s;
	v_pk_mul_f32 v[216:217], v[150:151], v[112:113]
	v_pk_mul_f32 v[218:219], v[148:149], v[114:115]
	v_pk_fma_f32 v[96:97], v[96:97], v[100:101], v[220:221]
	v_pk_fma_f32 v[98:99], v[98:99], v[102:103], v[222:223]
	v_fmac_f32_e32 v210, v96, v96
	v_fmac_f32_e32 v210, v97, v97
	v_fmac_f32_e32 v210, v98, v98
	v_fmac_f32_e32 v210, v99, v99
	v_pk_mul_f32 v[220:221], v[144:145], v[96:97]
	v_pk_mul_f32 v[222:223], v[146:147], v[98:99]
	v_cvt_pk_bf16_f32 v216, v216, v217
	v_cvt_pk_bf16_f32 v217, v218, v219
	v_cvt_pk_bf16_f32 v218, v220, v221
	v_cvt_pk_bf16_f32 v219, v222, v223
	global_store_dwordx4 v208, v[216:219], s[58:59] offset:256 sc1
	ds_bpermute_b32 v211, v203, v210
	v_permlane16_swap_b32_e32 v124, v120
	v_permlane16_swap_b32_e32 v125, v121
	v_permlane16_swap_b32_e32 v126, v122
	v_permlane16_swap_b32_e32 v127, v123
	v_permlane16_swap_b32_e32 v112, v96
	v_permlane16_swap_b32_e32 v113, v97
	v_permlane16_swap_b32_e32 v114, v98
	v_permlane16_swap_b32_e32 v115, v99
	v_permlane32_swap_b32_e32 v124, v120
	v_permlane32_swap_b32_e32 v125, v121
	v_permlane32_swap_b32_e32 v126, v122
	v_permlane32_swap_b32_e32 v127, v123
	v_permlane32_swap_b32_e32 v112, v96
	v_permlane32_swap_b32_e32 v113, v97
	v_permlane32_swap_b32_e32 v114, v98
	v_permlane32_swap_b32_e32 v115, v99
	global_store_dwordx4 v207, v[124:127], s[92:93] sc1
	global_store_dwordx4 v207, v[120:123], s[92:93] offset:64 sc1
	global_store_dwordx4 v207, v[112:115], s[92:93] offset:512 sc1
	global_store_dwordx4 v207, v[96:99], s[92:93] offset:576 sc1
	v_add_u32_e32 v207, 0x10000, v207
	v_add_u32_e32 v206, 0x10000, v206
	global_load_dwordx4 v[248:251], v206, s[82:83] offset:64
	global_load_dwordx4 v[220:223], v206, s[82:83] offset:576
	global_load_dwordx4 v[244:247], v206, s[82:83]
	global_load_dwordx4 v[216:219], v206, s[82:83] offset:512
	s_waitcnt lgkmcnt(0)
	v_add_f32_e32 v211, v210, v211
	ds_bpermute_b32 v212, v202, v211
	v_add_u32_e32 v208, 0x8000, v208
	s_waitcnt lgkmcnt(0)
	v_add_f32_e32 v211, v211, v212
	s_mov_b64 exec, 0xffff
	global_store_dword v209, v211, s[90:91] sc1
	s_mov_b64 exec, -1
	v_add_u32_e32 v209, 0x400, v209
	s_waitcnt vmcnt(12)
	v_permlane32_swap_b32_e32 v228, v232
	v_permlane32_swap_b32_e32 v229, v233
	v_permlane32_swap_b32_e32 v230, v234
	v_permlane32_swap_b32_e32 v231, v235
	v_permlane32_swap_b32_e32 v236, v240
	v_permlane32_swap_b32_e32 v237, v241
	v_permlane32_swap_b32_e32 v238, v242
	v_permlane32_swap_b32_e32 v239, v243
	v_permlane16_swap_b32_e32 v228, v232
	v_permlane16_swap_b32_e32 v229, v233
	v_permlane16_swap_b32_e32 v230, v234
	v_permlane16_swap_b32_e32 v231, v235
	v_permlane16_swap_b32_e32 v236, v240
	v_permlane16_swap_b32_e32 v237, v241
	v_permlane16_swap_b32_e32 v238, v242
	v_permlane16_swap_b32_e32 v239, v243
	v_pk_fma_f32 v[92:93], v[92:93], v[116:117], v[228:229]
	v_pk_fma_f32 v[94:95], v[94:95], v[118:119], v[230:231]
	v_mul_f32_e32 v210, v93, v93
	v_fmac_f32_e32 v210, v92, v92
	v_fmac_f32_e32 v210, v94, v94
	v_fmac_f32_e32 v210, v95, v95
	v_pk_mul_f32 v[228:229], v[164:165], v[92:93]
	v_pk_mul_f32 v[230:231], v[166:167], v[94:95]
	v_pk_fma_f32 v[88:89], v[88:89], v[108:109], v[232:233]
	v_pk_fma_f32 v[90:91], v[90:91], v[110:111], v[234:235]
	v_fmac_f32_e32 v210, v88, v88
	v_fmac_f32_e32 v210, v89, v89
	v_fmac_f32_e32 v210, v90, v90
	v_fmac_f32_e32 v210, v91, v91
	v_pk_mul_f32 v[232:233], v[162:163], v[88:89]
	v_pk_mul_f32 v[234:235], v[160:161], v[90:91]
	v_cvt_pk_bf16_f32 v228, v228, v229
	v_cvt_pk_bf16_f32 v229, v230, v231
	v_cvt_pk_bf16_f32 v230, v232, v233
	v_cvt_pk_bf16_f32 v231, v234, v235
	global_store_dwordx4 v208, v[228:231], s[58:59] sc1
	v_pk_fma_f32 v[84:85], v[84:85], v[104:105], v[236:237]
	v_pk_fma_f32 v[86:87], v[86:87], v[106:107], v[238:239]
	v_fmac_f32_e32 v210, v84, v84
	v_fmac_f32_e32 v210, v85, v85
	v_fmac_f32_e32 v210, v86, v86
	v_fmac_f32_e32 v210, v87, v87
	v_pk_mul_f32 v[236:237], v[150:151], v[84:85]
	v_pk_mul_f32 v[238:239], v[148:149], v[86:87]
	v_pk_fma_f32 v[80:81], v[80:81], v[100:101], v[240:241]
	v_pk_fma_f32 v[82:83], v[82:83], v[102:103], v[242:243]
	v_fmac_f32_e32 v210, v80, v80
	v_fmac_f32_e32 v210, v81, v81
	v_fmac_f32_e32 v210, v82, v82
	v_fmac_f32_e32 v210, v83, v83
	v_pk_mul_f32 v[240:241], v[144:145], v[80:81]
	v_pk_mul_f32 v[242:243], v[146:147], v[82:83]
	v_cvt_pk_bf16_f32 v236, v236, v237
	v_cvt_pk_bf16_f32 v237, v238, v239
	v_cvt_pk_bf16_f32 v238, v240, v241
	v_cvt_pk_bf16_f32 v239, v242, v243
	global_store_dwordx4 v208, v[236:239], s[58:59] offset:256 sc1
	ds_bpermute_b32 v211, v203, v210
	v_permlane16_swap_b32_e32 v92, v88
	v_permlane16_swap_b32_e32 v93, v89
	v_permlane16_swap_b32_e32 v94, v90
	v_permlane16_swap_b32_e32 v95, v91
	v_permlane16_swap_b32_e32 v84, v80
	v_permlane16_swap_b32_e32 v85, v81
	v_permlane16_swap_b32_e32 v86, v82
	v_permlane16_swap_b32_e32 v87, v83
	v_permlane32_swap_b32_e32 v92, v88
	v_permlane32_swap_b32_e32 v93, v89
	v_permlane32_swap_b32_e32 v94, v90
	v_permlane32_swap_b32_e32 v95, v91
	v_permlane32_swap_b32_e32 v84, v80
	v_permlane32_swap_b32_e32 v85, v81
	v_permlane32_swap_b32_e32 v86, v82
	v_permlane32_swap_b32_e32 v87, v83
	global_store_dwordx4 v207, v[92:95], s[92:93] sc1
	global_store_dwordx4 v207, v[88:91], s[92:93] offset:64 sc1
	global_store_dwordx4 v207, v[84:87], s[92:93] offset:512 sc1
	global_store_dwordx4 v207, v[80:83], s[92:93] offset:576 sc1
	v_add_u32_e32 v207, 0x10000, v207
	v_add_u32_e32 v206, 0x50000, v206
	global_load_dwordx4 v[232:235], v206, s[82:83] offset:64
	global_load_dwordx4 v[240:243], v206, s[82:83] offset:576
	global_load_dwordx4 v[228:231], v206, s[82:83]
	global_load_dwordx4 v[236:239], v206, s[82:83] offset:512
	s_waitcnt lgkmcnt(0)
; DI u32x4 pack8(const float* v) { u32x4 w; w.x = pk2(v[0], v[1]); w.y = pk2(v[2], v[3]); w.z = pk2(v[4], v[5]); w.w = pk2(v[6], v[7]); return w; }
; #define xor16_32(s) xor16_32_l((s), fr + 16 * fq)
;     DI void operator()(AccRef acc, const Unit& u, int wr, int wc, int fr, int fq) const {
;     ...
;         for (int ai = 0; ai < 2; ++ai) {
;             const int rb = u.pm * 256 + ai * 128 + wr * 64 + fr;
;             int mb, pos0, kv0; row_info(rb, mb, pos0, kv0);
;             f32x4 gt[2][2], gs[2][2];
; #pragma unroll
;             for (int bj = 0; bj < 2; ++bj)
; #pragma unroll
;                 for (int n = 0; n < 2; ++n) {
;                     const int c = u.pn * 256 + bj * 128 + cl + 4 * n;
;                     gt[bj][n] = *(const f32x4*)(gate + (size_t)mb * 6144 + c);
;                     if (ap) { const f32x4 g = *(const f32x4*)(gn + c), s = *(const f32x4*)(scn + (size_t)mb * 6144 + c); gs[bj][n] = g * (s + 1.f); }
;                 }
;     ...
;             for (int m = 0; m < 4; ++m) {
;                 const int row = rb + 16 * m;
;                 const float* xi = row < MP ? xin_p + (size_t)row * 1024 : xin_s + (size_t)(row - MP) * 1024;
;                 float s = 0.f;
; #pragma unroll
;                 for (int bj = 0; bj < 2; ++bj) {
;                     const int c = u.pn * 256 + bj * 128 + cl;
;                     float v[8];
; #pragma unroll
;                     for (int n = 0; n < 2; ++n) {
;                         const f32x4 x = *(const f32x4*)(xi + c + 4 * n);
;                         const f32x4 y = x + gt[bj][n] * acc[ai][bj][m][n];
;                         *(f32x4*)(xout + (size_t)row * 1024 + c + 4 * n) = y;
; #pragma unroll
;                         for (int j = 0; j < 4; ++j) { s += y[j] * y[j]; v[4 * n + j] = ap ? y[j] * gs[bj][n][j] : 0.f; }
;                     }
;                     if (ap) *(u32x4*)(ap + (size_t)row * 1024 + c) = pack8(v);
;                 }
;                 s = xor16_32(s);
;                 if (fq == 0) ssq[(size_t)row * 16 + u.pn * 4 + wc] = s;
	v_add_f32_e32 v211, v210, v211
	ds_bpermute_b32 v212, v202, v211
	v_add_u32_e32 v208, 0x8000, v208
	s_waitcnt lgkmcnt(0)
	v_add_f32_e32 v211, v211, v212
	s_mov_b64 exec, 0xffff
	global_store_dword v209, v211, s[90:91] sc1
	s_mov_b64 exec, -1
	v_add_u32_e32 v209, 0x400, v209
	s_waitcnt vmcnt(12)
	v_permlane32_swap_b32_e32 v244, v248
	v_permlane32_swap_b32_e32 v245, v249
	v_permlane32_swap_b32_e32 v246, v250
	v_permlane32_swap_b32_e32 v247, v251
	v_permlane32_swap_b32_e32 v216, v220
	v_permlane32_swap_b32_e32 v217, v221
	v_permlane32_swap_b32_e32 v218, v222
	v_permlane32_swap_b32_e32 v219, v223
	v_permlane16_swap_b32_e32 v244, v248
	v_permlane16_swap_b32_e32 v245, v249
	v_permlane16_swap_b32_e32 v246, v250
	v_permlane16_swap_b32_e32 v247, v251
	v_permlane16_swap_b32_e32 v216, v220
	v_permlane16_swap_b32_e32 v217, v221
	v_permlane16_swap_b32_e32 v218, v222
	v_permlane16_swap_b32_e32 v219, v223
	v_pk_fma_f32 v[76:77], v[76:77], v[116:117], v[244:245]
	v_pk_fma_f32 v[78:79], v[78:79], v[118:119], v[246:247]
	v_mul_f32_e32 v210, v77, v77
	v_fmac_f32_e32 v210, v76, v76
	v_fmac_f32_e32 v210, v78, v78
	v_fmac_f32_e32 v210, v79, v79
	v_pk_mul_f32 v[244:245], v[164:165], v[76:77]
	v_pk_mul_f32 v[246:247], v[166:167], v[78:79]
	v_pk_fma_f32 v[72:73], v[72:73], v[108:109], v[248:249]
	v_pk_fma_f32 v[74:75], v[74:75], v[110:111], v[250:251]
	v_fmac_f32_e32 v210, v72, v72
	v_fmac_f32_e32 v210, v73, v73
	v_fmac_f32_e32 v210, v74, v74
	v_fmac_f32_e32 v210, v75, v75
	v_pk_mul_f32 v[248:249], v[162:163], v[72:73]
	v_pk_mul_f32 v[250:251], v[160:161], v[74:75]
	v_cvt_pk_bf16_f32 v244, v244, v245
	v_cvt_pk_bf16_f32 v245, v246, v247
	v_cvt_pk_bf16_f32 v246, v248, v249
	v_cvt_pk_bf16_f32 v247, v250, v251
	global_store_dwordx4 v208, v[244:247], s[58:59] sc1
	v_pk_fma_f32 v[68:69], v[68:69], v[104:105], v[216:217]
	v_pk_fma_f32 v[70:71], v[70:71], v[106:107], v[218:219]
	v_fmac_f32_e32 v210, v68, v68
	v_fmac_f32_e32 v210, v69, v69
	v_fmac_f32_e32 v210, v70, v70
	v_fmac_f32_e32 v210, v71, v71
	v_pk_mul_f32 v[216:217], v[150:151], v[68:69]
	v_pk_mul_f32 v[218:219], v[148:149], v[70:71]
	v_pk_fma_f32 v[64:65], v[64:65], v[100:101], v[220:221]
	v_pk_fma_f32 v[66:67], v[66:67], v[102:103], v[222:223]
	v_fmac_f32_e32 v210, v64, v64
	v_fmac_f32_e32 v210, v65, v65
	v_fmac_f32_e32 v210, v66, v66
	v_fmac_f32_e32 v210, v67, v67
	v_pk_mul_f32 v[220:221], v[144:145], v[64:65]
	v_pk_mul_f32 v[222:223], v[146:147], v[66:67]
	v_cvt_pk_bf16_f32 v216, v216, v217
	v_cvt_pk_bf16_f32 v217, v218, v219
	v_cvt_pk_bf16_f32 v218, v220, v221
	v_cvt_pk_bf16_f32 v219, v222, v223
	global_store_dwordx4 v208, v[216:219], s[58:59] offset:256 sc1
	ds_bpermute_b32 v211, v203, v210
	v_permlane16_swap_b32_e32 v76, v72
	v_permlane16_swap_b32_e32 v77, v73
	v_permlane16_swap_b32_e32 v78, v74
	v_permlane16_swap_b32_e32 v79, v75
	v_permlane16_swap_b32_e32 v68, v64
	v_permlane16_swap_b32_e32 v69, v65
	v_permlane16_swap_b32_e32 v70, v66
	v_permlane16_swap_b32_e32 v71, v67
	v_permlane32_swap_b32_e32 v76, v72
	v_permlane32_swap_b32_e32 v77, v73
	v_permlane32_swap_b32_e32 v78, v74
	v_permlane32_swap_b32_e32 v79, v75
	v_permlane32_swap_b32_e32 v68, v64
	v_permlane32_swap_b32_e32 v69, v65
	v_permlane32_swap_b32_e32 v70, v66
	v_permlane32_swap_b32_e32 v71, v67
	global_store_dwordx4 v207, v[76:79], s[92:93] sc1
	global_store_dwordx4 v207, v[72:75], s[92:93] offset:64 sc1
	global_store_dwordx4 v207, v[68:71], s[92:93] offset:512 sc1
	global_store_dwordx4 v207, v[64:67], s[92:93] offset:576 sc1
	v_add_u32_e32 v207, 0x50000, v207
	v_add_u32_e32 v206, 0x10000, v206
	global_load_dwordx4 v[248:251], v206, s[82:83] offset:64
	global_load_dwordx4 v[220:223], v206, s[82:83] offset:576
	global_load_dwordx4 v[244:247], v206, s[82:83]
	global_load_dwordx4 v[216:219], v206, s[82:83] offset:512
	s_waitcnt lgkmcnt(0)
	v_add_f32_e32 v211, v210, v211
	ds_bpermute_b32 v212, v202, v211
	v_add_u32_e32 v208, 0x28000, v208
	s_waitcnt lgkmcnt(0)
	v_add_f32_e32 v211, v211, v212
	s_mov_b64 exec, 0xffff
	global_store_dword v209, v211, s[90:91] sc1
	s_mov_b64 exec, -1
	v_add_u32_e32 v209, 0x1400, v209
	v_add_u32_e32 v224, 0xffffc080, v192
	v_add_u32_e32 v112, 0x80, v192
	s_waitcnt lgkmcnt(0)
	v_lshrrev_b32_e32 v65, 6, v224
	v_ashrrev_i32_e32 v64, 11, v112
	v_add_u32_e32 v65, 8, v65
	v_cmp_gt_i32_e64 s[0:1], s94, v112
	v_mov_b64_e32 v[66:67], s[56:57]
	s_nop 0
	v_cndmask_b32_e64 v68, v65, v64, s[0:1]
	v_mov_b64_e32 v[64:65], s[6:7]
	v_mad_i64_i32 v[64:65], s[0:1], v68, s75, v[64:65]
	v_mad_i64_i32 v[66:67], s[0:1], v68, s75, v[66:67]
	v_lshl_add_u64 v[68:69], v[64:65], 0, v[190:191]
	v_lshl_add_u64 v[104:105], v[66:67], 0, v[190:191]
	global_load_dwordx4 v[72:75], v[68:69], off offset:16
	global_load_dwordx4 v[76:79], v[68:69], off
	global_load_dwordx4 v[84:87], v[194:195], off offset:16
	global_load_dwordx4 v[100:103], v[194:195], off
	global_load_dwordx4 v[96:99], v[104:105], off offset:16
	global_load_dwordx4 v[108:111], v[104:105], off
	global_load_dwordx4 v[64:67], v[68:69], off offset:528
	s_nop 0
	global_load_dwordx4 v[68:71], v[68:69], off offset:512
	s_nop 0
	global_load_dwordx4 v[80:83], v[194:195], off offset:528
	global_load_dwordx4 v[92:95], v[194:195], off offset:512
	global_load_dwordx4 v[88:91], v[104:105], off offset:528
	s_nop 0
	global_load_dwordx4 v[104:107], v[104:105], off offset:512
	s_movk_i32 s0, 0x3fff
	v_cmp_lt_i32_e64 s[0:1], s0, v112
	s_and_saveexec_b64 s[12:13], s[0:1]
	s_xor_b64 s[0:1], exec, s[12:13]
	v_lshlrev_b64 v[114:115], 12, v[224:225]
	v_mov_b32_e32 v113, v225
	v_lshl_add_u64 v[116:117], s[20:21], 0, v[114:115]
	v_lshlrev_b64 v[114:115], 12, v[112:113]
	s_andn2_saveexec_b64 s[0:1], s[0:1]
	v_ashrrev_i32_e32 v113, 31, v112
	v_lshlrev_b64 v[114:115], 12, v[112:113]
	v_lshl_add_u64 v[116:117], s[42:43], 0, v[114:115]
	s_or_b64 exec, exec, s[0:1]
	s_waitcnt vmcnt(6)
; DI u32x4 pack8(const float* v) { u32x4 w; w.x = pk2(v[0], v[1]); w.y = pk2(v[2], v[3]); w.z = pk2(v[4], v[5]); w.w = pk2(v[6], v[7]); return w; }
; #define xor16_32(s) xor16_32_l((s), fr + 16 * fq)
;     DI void operator()(AccRef acc, const Unit& u, int wr, int wc, int fr, int fq) const {
;     ...
;                     gt[bj][n] = *(const f32x4*)(gate + (size_t)mb * 6144 + c);
;                     if (ap) { const f32x4 g = *(const f32x4*)(gn + c), s = *(const f32x4*)(scn + (size_t)mb * 6144 + c); gs[bj][n] = g * (s + 1.f); }
;                 }
; #pragma unroll
;             for (int m = 0; m < 4; ++m) {
;                 const int row = rb + 16 * m;
;                 const float* xi = row < MP ? xin_p + (size_t)row * 1024 : xin_s + (size_t)(row - MP) * 1024;
;                 float s = 0.f;
; #pragma unroll
;                 for (int bj = 0; bj < 2; ++bj) {
;                     const int c = u.pn * 256 + bj * 128 + cl;
;                     float v[8];
; #pragma unroll
;                     for (int n = 0; n < 2; ++n) {
;                         const f32x4 x = *(const f32x4*)(xi + c + 4 * n);
;                         const f32x4 y = x + gt[bj][n] * acc[ai][bj][m][n];
;                         *(f32x4*)(xout + (size_t)row * 1024 + c + 4 * n) = y;
; #pragma unroll
;                         for (int j = 0; j < 4; ++j) { s += y[j] * y[j]; v[4 * n + j] = ap ? y[j] * gs[bj][n][j] : 0.f; }
;                     }
;                     if (ap) *(u32x4*)(ap + (size_t)row * 1024 + c) = pack8(v);
;                 }
;                 s = xor16_32(s);
;                 if (fq == 0) ssq[(size_t)row * 16 + u.pn * 4 + wc] = s;
	v_pk_add_f32 v[108:109], v[108:109], 1.0 op_sel_hi:[1,0]
	s_waitcnt vmcnt(1)
	v_pk_add_f32 v[90:91], v[90:91], 1.0 op_sel_hi:[1,0]
	v_pk_mul_f32 v[100:101], v[100:101], v[108:109]
	v_pk_add_f32 v[108:109], v[96:97], 1.0 op_sel_hi:[1,0]
	v_pk_add_f32 v[96:97], v[98:99], 1.0 op_sel_hi:[1,0]
	v_pk_mul_f32 v[98:99], v[84:85], v[108:109]
	v_pk_mul_f32 v[96:97], v[86:87], v[96:97]
	s_waitcnt vmcnt(0)
	v_pk_add_f32 v[84:85], v[106:107], 1.0 op_sel_hi:[1,0]
	v_pk_add_f32 v[86:87], v[104:105], 1.0 op_sel_hi:[1,0]
	v_pk_mul_f32 v[82:83], v[82:83], v[90:91]
	v_lshl_add_u64 v[90:91], v[116:117], 0, v[190:191]
	v_pk_mul_f32 v[84:85], v[94:95], v[84:85]
	v_pk_mul_f32 v[86:87], v[92:93], v[86:87]
	v_pk_add_f32 v[110:111], v[110:111], 1.0 op_sel_hi:[1,0]
	v_pk_add_f32 v[88:89], v[88:89], 1.0 op_sel_hi:[1,0]
	v_pk_mul_f32 v[102:103], v[102:103], v[110:111]
	v_pk_mul_f32 v[80:81], v[80:81], v[88:89]
	v_lshlrev_b64 v[88:89], 11, v[112:113]
	v_lshl_add_u64 v[88:89], s[58:59], 0, v[88:89]
	v_permlane32_swap_b32_e32 v228, v232
	v_permlane32_swap_b32_e32 v229, v233
	v_permlane32_swap_b32_e32 v230, v234
	v_permlane32_swap_b32_e32 v231, v235
	v_permlane32_swap_b32_e32 v236, v240
	v_permlane32_swap_b32_e32 v237, v241
	v_permlane32_swap_b32_e32 v238, v242
	v_permlane32_swap_b32_e32 v239, v243
	v_permlane16_swap_b32_e32 v228, v232
	v_permlane16_swap_b32_e32 v229, v233
	v_permlane16_swap_b32_e32 v230, v234
	v_permlane16_swap_b32_e32 v231, v235
	v_permlane16_swap_b32_e32 v236, v240
	v_permlane16_swap_b32_e32 v237, v241
	v_permlane16_swap_b32_e32 v238, v242
	v_permlane16_swap_b32_e32 v239, v243
	v_pk_fma_f32 v[60:61], v[60:61], v[76:77], v[228:229]
	v_pk_fma_f32 v[62:63], v[62:63], v[78:79], v[230:231]
	v_mul_f32_e32 v210, v61, v61
	v_fmac_f32_e32 v210, v60, v60
	v_fmac_f32_e32 v210, v62, v62
	v_fmac_f32_e32 v210, v63, v63
	v_pk_mul_f32 v[228:229], v[100:101], v[60:61]
	v_pk_mul_f32 v[230:231], v[102:103], v[62:63]
	v_pk_fma_f32 v[56:57], v[56:57], v[72:73], v[232:233]
	v_pk_fma_f32 v[58:59], v[58:59], v[74:75], v[234:235]
	v_fmac_f32_e32 v210, v56, v56
	v_fmac_f32_e32 v210, v57, v57
	v_fmac_f32_e32 v210, v58, v58
	v_fmac_f32_e32 v210, v59, v59
	v_pk_mul_f32 v[232:233], v[98:99], v[56:57]
	v_pk_mul_f32 v[234:235], v[96:97], v[58:59]
	v_cvt_pk_bf16_f32 v228, v228, v229
	v_cvt_pk_bf16_f32 v229, v230, v231
	v_cvt_pk_bf16_f32 v230, v232, v233
	v_cvt_pk_bf16_f32 v231, v234, v235
	global_store_dwordx4 v208, v[228:231], s[58:59] sc1
	v_pk_fma_f32 v[52:53], v[52:53], v[68:69], v[236:237]
	v_pk_fma_f32 v[54:55], v[54:55], v[70:71], v[238:239]
	v_fmac_f32_e32 v210, v52, v52
	v_fmac_f32_e32 v210, v53, v53
	v_fmac_f32_e32 v210, v54, v54
	v_fmac_f32_e32 v210, v55, v55
	v_pk_mul_f32 v[236:237], v[86:87], v[52:53]
	v_pk_mul_f32 v[238:239], v[84:85], v[54:55]
	v_pk_fma_f32 v[48:49], v[48:49], v[64:65], v[240:241]
	v_pk_fma_f32 v[50:51], v[50:51], v[66:67], v[242:243]
	v_fmac_f32_e32 v210, v48, v48
	v_fmac_f32_e32 v210, v49, v49
	v_fmac_f32_e32 v210, v50, v50
	v_fmac_f32_e32 v210, v51, v51
	v_pk_mul_f32 v[240:241], v[80:81], v[48:49]
	v_pk_mul_f32 v[242:243], v[82:83], v[50:51]
	v_cvt_pk_bf16_f32 v236, v236, v237
	v_cvt_pk_bf16_f32 v237, v238, v239
	v_cvt_pk_bf16_f32 v238, v240, v241
	v_cvt_pk_bf16_f32 v239, v242, v243
	global_store_dwordx4 v208, v[236:239], s[58:59] offset:256 sc1
	ds_bpermute_b32 v211, v203, v210
	v_permlane16_swap_b32_e32 v60, v56
	v_permlane16_swap_b32_e32 v61, v57
	v_permlane16_swap_b32_e32 v62, v58
	v_permlane16_swap_b32_e32 v63, v59
	v_permlane16_swap_b32_e32 v52, v48
	v_permlane16_swap_b32_e32 v53, v49
	v_permlane16_swap_b32_e32 v54, v50
	v_permlane16_swap_b32_e32 v55, v51
	v_permlane32_swap_b32_e32 v60, v56
	v_permlane32_swap_b32_e32 v61, v57
	v_permlane32_swap_b32_e32 v62, v58
	v_permlane32_swap_b32_e32 v63, v59
	v_permlane32_swap_b32_e32 v52, v48
	v_permlane32_swap_b32_e32 v53, v49
	v_permlane32_swap_b32_e32 v54, v50
	v_permlane32_swap_b32_e32 v55, v51
	global_store_dwordx4 v207, v[60:63], s[92:93] sc1
	global_store_dwordx4 v207, v[56:59], s[92:93] offset:64 sc1
	global_store_dwordx4 v207, v[52:55], s[92:93] offset:512 sc1
	global_store_dwordx4 v207, v[48:51], s[92:93] offset:576 sc1
	v_add_u32_e32 v207, 0x10000, v207
	v_add_u32_e32 v206, 0x10000, v206
	global_load_dwordx4 v[232:235], v206, s[82:83] offset:64
	global_load_dwordx4 v[240:243], v206, s[82:83] offset:576
	global_load_dwordx4 v[228:231], v206, s[82:83]
	global_load_dwordx4 v[236:239], v206, s[82:83] offset:512
	s_waitcnt lgkmcnt(0)
	v_add_f32_e32 v211, v210, v211
	ds_bpermute_b32 v212, v202, v211
	v_add_u32_e32 v208, 0x8000, v208
	s_waitcnt lgkmcnt(0)
; DI u32x4 pack8(const float* v) { u32x4 w; w.x = pk2(v[0], v[1]); w.y = pk2(v[2], v[3]); w.z = pk2(v[4], v[5]); w.w = pk2(v[6], v[7]); return w; }
; #define xor16_32(s) xor16_32_l((s), fr + 16 * fq)
;     DI void operator()(AccRef acc, const Unit& u, int wr, int wc, int fr, int fq) const {
;     ...
;             for (int m = 0; m < 4; ++m) {
;                 const int row = rb + 16 * m;
;                 const float* xi = row < MP ? xin_p + (size_t)row * 1024 : xin_s + (size_t)(row - MP) * 1024;
;                 float s = 0.f;
; #pragma unroll
;                 for (int bj = 0; bj < 2; ++bj) {
;                     const int c = u.pn * 256 + bj * 128 + cl;
;                     float v[8];
; #pragma unroll
;                     for (int n = 0; n < 2; ++n) {
;                         const f32x4 x = *(const f32x4*)(xi + c + 4 * n);
;                         const f32x4 y = x + gt[bj][n] * acc[ai][bj][m][n];
;                         *(f32x4*)(xout + (size_t)row * 1024 + c + 4 * n) = y;
; #pragma unroll
;                         for (int j = 0; j < 4; ++j) { s += y[j] * y[j]; v[4 * n + j] = ap ? y[j] * gs[bj][n][j] : 0.f; }
;                     }
;                     if (ap) *(u32x4*)(ap + (size_t)row * 1024 + c) = pack8(v);
;                 }
;                 s = xor16_32(s);
;                 if (fq == 0) ssq[(size_t)row * 16 + u.pn * 4 + wc] = s;
	v_add_f32_e32 v211, v211, v212
	s_mov_b64 exec, 0xffff
	global_store_dword v209, v211, s[90:91] sc1
	s_mov_b64 exec, -1
	v_add_u32_e32 v209, 0x400, v209
	v_permlane32_swap_b32_e32 v244, v248
	v_permlane32_swap_b32_e32 v245, v249
	v_permlane32_swap_b32_e32 v246, v250
	v_permlane32_swap_b32_e32 v247, v251
	v_permlane32_swap_b32_e32 v216, v220
	v_permlane32_swap_b32_e32 v217, v221
	v_permlane32_swap_b32_e32 v218, v222
	v_permlane32_swap_b32_e32 v219, v223
	v_permlane16_swap_b32_e32 v244, v248
	v_permlane16_swap_b32_e32 v245, v249
	v_permlane16_swap_b32_e32 v246, v250
	v_permlane16_swap_b32_e32 v247, v251
	v_permlane16_swap_b32_e32 v216, v220
	v_permlane16_swap_b32_e32 v217, v221
	v_permlane16_swap_b32_e32 v218, v222
	v_permlane16_swap_b32_e32 v219, v223
	v_pk_fma_f32 v[44:45], v[44:45], v[76:77], v[244:245]
	v_pk_fma_f32 v[46:47], v[46:47], v[78:79], v[246:247]
	v_mul_f32_e32 v210, v45, v45
	v_fmac_f32_e32 v210, v44, v44
	v_fmac_f32_e32 v210, v46, v46
	v_fmac_f32_e32 v210, v47, v47
	v_pk_mul_f32 v[244:245], v[100:101], v[44:45]
	v_pk_mul_f32 v[246:247], v[102:103], v[46:47]
	v_pk_fma_f32 v[40:41], v[40:41], v[72:73], v[248:249]
	v_pk_fma_f32 v[42:43], v[42:43], v[74:75], v[250:251]
	v_fmac_f32_e32 v210, v40, v40
	v_fmac_f32_e32 v210, v41, v41
	v_fmac_f32_e32 v210, v42, v42
	v_fmac_f32_e32 v210, v43, v43
	v_pk_mul_f32 v[248:249], v[98:99], v[40:41]
	v_pk_mul_f32 v[250:251], v[96:97], v[42:43]
	v_cvt_pk_bf16_f32 v244, v244, v245
	v_cvt_pk_bf16_f32 v245, v246, v247
	v_cvt_pk_bf16_f32 v246, v248, v249
	v_cvt_pk_bf16_f32 v247, v250, v251
	global_store_dwordx4 v208, v[244:247], s[58:59] sc1
	v_pk_fma_f32 v[36:37], v[36:37], v[68:69], v[216:217]
	v_pk_fma_f32 v[38:39], v[38:39], v[70:71], v[218:219]
	v_fmac_f32_e32 v210, v36, v36
	v_fmac_f32_e32 v210, v37, v37
	v_fmac_f32_e32 v210, v38, v38
	v_fmac_f32_e32 v210, v39, v39
	v_pk_mul_f32 v[216:217], v[86:87], v[36:37]
	v_pk_mul_f32 v[218:219], v[84:85], v[38:39]
	v_pk_fma_f32 v[32:33], v[32:33], v[64:65], v[220:221]
	v_pk_fma_f32 v[34:35], v[34:35], v[66:67], v[222:223]
	v_fmac_f32_e32 v210, v32, v32
	v_fmac_f32_e32 v210, v33, v33
	v_fmac_f32_e32 v210, v34, v34
	v_fmac_f32_e32 v210, v35, v35
	v_pk_mul_f32 v[220:221], v[80:81], v[32:33]
	v_pk_mul_f32 v[222:223], v[82:83], v[34:35]
	v_cvt_pk_bf16_f32 v216, v216, v217
	v_cvt_pk_bf16_f32 v217, v218, v219
	v_cvt_pk_bf16_f32 v218, v220, v221
	v_cvt_pk_bf16_f32 v219, v222, v223
	global_store_dwordx4 v208, v[216:219], s[58:59] offset:256 sc1
	ds_bpermute_b32 v211, v203, v210
	v_permlane16_swap_b32_e32 v44, v40
	v_permlane16_swap_b32_e32 v45, v41
	v_permlane16_swap_b32_e32 v46, v42
	v_permlane16_swap_b32_e32 v47, v43
	v_permlane16_swap_b32_e32 v36, v32
	v_permlane16_swap_b32_e32 v37, v33
	v_permlane16_swap_b32_e32 v38, v34
	v_permlane16_swap_b32_e32 v39, v35
	v_permlane32_swap_b32_e32 v44, v40
	v_permlane32_swap_b32_e32 v45, v41
	v_permlane32_swap_b32_e32 v46, v42
	v_permlane32_swap_b32_e32 v47, v43
	v_permlane32_swap_b32_e32 v36, v32
	v_permlane32_swap_b32_e32 v37, v33
	v_permlane32_swap_b32_e32 v38, v34
	v_permlane32_swap_b32_e32 v39, v35
	global_store_dwordx4 v207, v[44:47], s[92:93] sc1
	global_store_dwordx4 v207, v[40:43], s[92:93] offset:64 sc1
	global_store_dwordx4 v207, v[36:39], s[92:93] offset:512 sc1
	global_store_dwordx4 v207, v[32:35], s[92:93] offset:576 sc1
	v_add_u32_e32 v207, 0x10000, v207
	v_add_u32_e32 v206, 0x10000, v206
	global_load_dwordx4 v[248:251], v206, s[82:83] offset:64
	global_load_dwordx4 v[220:223], v206, s[82:83] offset:576
	global_load_dwordx4 v[244:247], v206, s[82:83]
	global_load_dwordx4 v[216:219], v206, s[82:83] offset:512
	s_waitcnt lgkmcnt(0)
	v_add_f32_e32 v211, v210, v211
	ds_bpermute_b32 v212, v202, v211
	v_add_u32_e32 v208, 0x8000, v208
	s_waitcnt lgkmcnt(0)
	v_add_f32_e32 v211, v211, v212
	s_mov_b64 exec, 0xffff
	global_store_dword v209, v211, s[90:91] sc1
	s_mov_b64 exec, -1
	v_add_u32_e32 v209, 0x400, v209
	s_waitcnt vmcnt(12)
; DI u32x4 pack8(const float* v) { u32x4 w; w.x = pk2(v[0], v[1]); w.y = pk2(v[2], v[3]); w.z = pk2(v[4], v[5]); w.w = pk2(v[6], v[7]); return w; }
; #define xor16_32(s) xor16_32_l((s), fr + 16 * fq)
;     DI void operator()(AccRef acc, const Unit& u, int wr, int wc, int fr, int fq) const {
;     ...
;             for (int m = 0; m < 4; ++m) {
;                 const int row = rb + 16 * m;
;                 const float* xi = row < MP ? xin_p + (size_t)row * 1024 : xin_s + (size_t)(row - MP) * 1024;
;                 float s = 0.f;
; #pragma unroll
;                 for (int bj = 0; bj < 2; ++bj) {
;                     const int c = u.pn * 256 + bj * 128 + cl;
;                     float v[8];
; #pragma unroll
;                     for (int n = 0; n < 2; ++n) {
;                         const f32x4 x = *(const f32x4*)(xi + c + 4 * n);
;                         const f32x4 y = x + gt[bj][n] * acc[ai][bj][m][n];
;                         *(f32x4*)(xout + (size_t)row * 1024 + c + 4 * n) = y;
; #pragma unroll
;                         for (int j = 0; j < 4; ++j) { s += y[j] * y[j]; v[4 * n + j] = ap ? y[j] * gs[bj][n][j] : 0.f; }
;                     }
;                     if (ap) *(u32x4*)(ap + (size_t)row * 1024 + c) = pack8(v);
;                 }
;                 s = xor16_32(s);
;                 if (fq == 0) ssq[(size_t)row * 16 + u.pn * 4 + wc] = s;
	v_permlane32_swap_b32_e32 v228, v232
	v_permlane32_swap_b32_e32 v229, v233
	v_permlane32_swap_b32_e32 v230, v234
	v_permlane32_swap_b32_e32 v231, v235
	v_permlane32_swap_b32_e32 v236, v240
	v_permlane32_swap_b32_e32 v237, v241
	v_permlane32_swap_b32_e32 v238, v242
	v_permlane32_swap_b32_e32 v239, v243
	v_permlane16_swap_b32_e32 v228, v232
	v_permlane16_swap_b32_e32 v229, v233
	v_permlane16_swap_b32_e32 v230, v234
	v_permlane16_swap_b32_e32 v231, v235
	v_permlane16_swap_b32_e32 v236, v240
	v_permlane16_swap_b32_e32 v237, v241
	v_permlane16_swap_b32_e32 v238, v242
	v_permlane16_swap_b32_e32 v239, v243
	v_pk_fma_f32 v[28:29], v[28:29], v[76:77], v[228:229]
	v_pk_fma_f32 v[30:31], v[30:31], v[78:79], v[230:231]
	v_mul_f32_e32 v210, v29, v29
	v_fmac_f32_e32 v210, v28, v28
	v_fmac_f32_e32 v210, v30, v30
	v_fmac_f32_e32 v210, v31, v31
	v_pk_mul_f32 v[228:229], v[100:101], v[28:29]
	v_pk_mul_f32 v[230:231], v[102:103], v[30:31]
	v_pk_fma_f32 v[24:25], v[24:25], v[72:73], v[232:233]
	v_pk_fma_f32 v[26:27], v[26:27], v[74:75], v[234:235]
	v_fmac_f32_e32 v210, v24, v24
	v_fmac_f32_e32 v210, v25, v25
	v_fmac_f32_e32 v210, v26, v26
	v_fmac_f32_e32 v210, v27, v27
	v_pk_mul_f32 v[232:233], v[98:99], v[24:25]
	v_pk_mul_f32 v[234:235], v[96:97], v[26:27]
	v_cvt_pk_bf16_f32 v228, v228, v229
	v_cvt_pk_bf16_f32 v229, v230, v231
	v_cvt_pk_bf16_f32 v230, v232, v233
	v_cvt_pk_bf16_f32 v231, v234, v235
	global_store_dwordx4 v208, v[228:231], s[58:59] sc1
	v_pk_fma_f32 v[20:21], v[20:21], v[68:69], v[236:237]
	v_pk_fma_f32 v[22:23], v[22:23], v[70:71], v[238:239]
	v_fmac_f32_e32 v210, v20, v20
	v_fmac_f32_e32 v210, v21, v21
	v_fmac_f32_e32 v210, v22, v22
	v_fmac_f32_e32 v210, v23, v23
	v_pk_mul_f32 v[236:237], v[86:87], v[20:21]
	v_pk_mul_f32 v[238:239], v[84:85], v[22:23]
	v_pk_fma_f32 v[16:17], v[16:17], v[64:65], v[240:241]
	v_pk_fma_f32 v[18:19], v[18:19], v[66:67], v[242:243]
	v_fmac_f32_e32 v210, v16, v16
	v_fmac_f32_e32 v210, v17, v17
	v_fmac_f32_e32 v210, v18, v18
	v_fmac_f32_e32 v210, v19, v19
	v_pk_mul_f32 v[240:241], v[80:81], v[16:17]
	v_pk_mul_f32 v[242:243], v[82:83], v[18:19]
	v_cvt_pk_bf16_f32 v236, v236, v237
	v_cvt_pk_bf16_f32 v237, v238, v239
	v_cvt_pk_bf16_f32 v238, v240, v241
	v_cvt_pk_bf16_f32 v239, v242, v243
	global_store_dwordx4 v208, v[236:239], s[58:59] offset:256 sc1
	ds_bpermute_b32 v211, v203, v210
	v_permlane16_swap_b32_e32 v28, v24
	v_permlane16_swap_b32_e32 v29, v25
	v_permlane16_swap_b32_e32 v30, v26
	v_permlane16_swap_b32_e32 v31, v27
	v_permlane16_swap_b32_e32 v20, v16
	v_permlane16_swap_b32_e32 v21, v17
	v_permlane16_swap_b32_e32 v22, v18
	v_permlane16_swap_b32_e32 v23, v19
	v_permlane32_swap_b32_e32 v28, v24
	v_permlane32_swap_b32_e32 v29, v25
	v_permlane32_swap_b32_e32 v30, v26
	v_permlane32_swap_b32_e32 v31, v27
	v_permlane32_swap_b32_e32 v20, v16
	v_permlane32_swap_b32_e32 v21, v17
	v_permlane32_swap_b32_e32 v22, v18
	v_permlane32_swap_b32_e32 v23, v19
	global_store_dwordx4 v207, v[28:31], s[92:93] sc1
	global_store_dwordx4 v207, v[24:27], s[92:93] offset:64 sc1
	global_store_dwordx4 v207, v[20:23], s[92:93] offset:512 sc1
	global_store_dwordx4 v207, v[16:19], s[92:93] offset:576 sc1
	v_add_u32_e32 v207, 0x10000, v207
	s_waitcnt lgkmcnt(0)
	v_add_f32_e32 v211, v210, v211
	ds_bpermute_b32 v212, v202, v211
	v_add_u32_e32 v208, 0x8000, v208
	s_waitcnt lgkmcnt(0)
	v_add_f32_e32 v211, v211, v212
	s_mov_b64 exec, 0xffff
	global_store_dword v209, v211, s[90:91] sc1
	s_mov_b64 exec, -1
	v_add_u32_e32 v209, 0x400, v209
	s_waitcnt vmcnt(8)
	v_permlane32_swap_b32_e32 v244, v248
	v_permlane32_swap_b32_e32 v245, v249
	v_permlane32_swap_b32_e32 v246, v250
	v_permlane32_swap_b32_e32 v247, v251
	v_permlane32_swap_b32_e32 v216, v220
	v_permlane32_swap_b32_e32 v217, v221
	v_permlane32_swap_b32_e32 v218, v222
	v_permlane32_swap_b32_e32 v219, v223
	v_permlane16_swap_b32_e32 v244, v248
	v_permlane16_swap_b32_e32 v245, v249
	v_permlane16_swap_b32_e32 v246, v250
	v_permlane16_swap_b32_e32 v247, v251
	v_permlane16_swap_b32_e32 v216, v220
	v_permlane16_swap_b32_e32 v217, v221
	v_permlane16_swap_b32_e32 v218, v222
	v_permlane16_swap_b32_e32 v219, v223
	v_pk_fma_f32 v[12:13], v[12:13], v[76:77], v[244:245]
	v_pk_fma_f32 v[14:15], v[14:15], v[78:79], v[246:247]
	v_mul_f32_e32 v210, v13, v13
	v_fmac_f32_e32 v210, v12, v12
	v_fmac_f32_e32 v210, v14, v14
	v_fmac_f32_e32 v210, v15, v15
	v_pk_mul_f32 v[244:245], v[100:101], v[12:13]
	v_pk_mul_f32 v[246:247], v[102:103], v[14:15]
	v_pk_fma_f32 v[8:9], v[8:9], v[72:73], v[248:249]
	v_pk_fma_f32 v[10:11], v[10:11], v[74:75], v[250:251]
	v_fmac_f32_e32 v210, v8, v8
	v_fmac_f32_e32 v210, v9, v9
	v_fmac_f32_e32 v210, v10, v10
	v_fmac_f32_e32 v210, v11, v11
	v_pk_mul_f32 v[248:249], v[98:99], v[8:9]
	v_pk_mul_f32 v[250:251], v[96:97], v[10:11]
	v_cvt_pk_bf16_f32 v244, v244, v245
	v_cvt_pk_bf16_f32 v245, v246, v247
	v_cvt_pk_bf16_f32 v246, v248, v249
	v_cvt_pk_bf16_f32 v247, v250, v251
	global_store_dwordx4 v208, v[244:247], s[58:59] sc1
	v_pk_fma_f32 v[4:5], v[4:5], v[68:69], v[216:217]
	v_pk_fma_f32 v[6:7], v[6:7], v[70:71], v[218:219]
	v_fmac_f32_e32 v210, v4, v4
	v_fmac_f32_e32 v210, v5, v5
	v_fmac_f32_e32 v210, v6, v6
	v_fmac_f32_e32 v210, v7, v7
	v_pk_mul_f32 v[216:217], v[86:87], v[4:5]
	v_pk_mul_f32 v[218:219], v[84:85], v[6:7]
	v_pk_fma_f32 v[0:1], v[0:1], v[64:65], v[220:221]
	v_pk_fma_f32 v[2:3], v[2:3], v[66:67], v[222:223]
	v_fmac_f32_e32 v210, v0, v0
	v_fmac_f32_e32 v210, v1, v1
	v_fmac_f32_e32 v210, v2, v2
	v_fmac_f32_e32 v210, v3, v3
	v_pk_mul_f32 v[220:221], v[80:81], v[0:1]
	v_pk_mul_f32 v[222:223], v[82:83], v[2:3]
	v_cvt_pk_bf16_f32 v216, v216, v217
	v_cvt_pk_bf16_f32 v217, v218, v219
	v_cvt_pk_bf16_f32 v218, v220, v221
	v_cvt_pk_bf16_f32 v219, v222, v223
	global_store_dwordx4 v208, v[216:219], s[58:59] offset:256 sc1
	ds_bpermute_b32 v211, v203, v210
	v_permlane16_swap_b32_e32 v12, v8
	v_permlane16_swap_b32_e32 v13, v9
	v_permlane16_swap_b32_e32 v14, v10
	v_permlane16_swap_b32_e32 v15, v11
	v_permlane16_swap_b32_e32 v4, v0
	v_permlane16_swap_b32_e32 v5, v1
	v_permlane16_swap_b32_e32 v6, v2
	v_permlane16_swap_b32_e32 v7, v3
	v_permlane32_swap_b32_e32 v12, v8
	v_permlane32_swap_b32_e32 v13, v9
	v_permlane32_swap_b32_e32 v14, v10
	v_permlane32_swap_b32_e32 v15, v11
	v_permlane32_swap_b32_e32 v4, v0
	v_permlane32_swap_b32_e32 v5, v1
	v_permlane32_swap_b32_e32 v6, v2
	v_permlane32_swap_b32_e32 v7, v3
	global_store_dwordx4 v207, v[12:15], s[92:93] sc1
	global_store_dwordx4 v207, v[8:11], s[92:93] offset:64 sc1
	global_store_dwordx4 v207, v[4:7], s[92:93] offset:512 sc1
	global_store_dwordx4 v207, v[0:3], s[92:93] offset:576 sc1
	s_waitcnt lgkmcnt(0)
	v_add_f32_e32 v211, v210, v211
	ds_bpermute_b32 v212, v202, v211
	s_waitcnt lgkmcnt(0)
	v_add_f32_e32 v211, v211, v212
	s_mov_b64 exec, 0xffff
	global_store_dword v209, v211, s[90:91] sc1
	s_mov_b64 exec, -1
	s_andn2_b64 vcc, exec, s[8:9]
	s_mov_b64 s[0:1], -1
	s_cbranch_vccnz .LBB0_1292
	s_andn2_b64 vcc, exec, s[2:3]
	s_cbranch_vccnz .LBB0_1291
	s_barrier
	s_branch .LBB0_1291

; DI u32x4 pack8(const float* v) { u32x4 w; w.x = pk2(v[0], v[1]); w.y = pk2(v[2], v[3]); w.z = pk2(v[4], v[5]); w.w = pk2(v[6], v[7]); return w; }
; #define xor16_32(s) xor16_32_l((s), fr + 16 * fq)
;     DI void operator()(AccRef acc, const Unit& u, int wr, int wc, int fr, int fq) const {
;         const int cl = wc * 32 + fq * 8;
;         const float* gate = (const float*)(ws + WS_MOD) + gate_off; const float* scn = (const float*)(ws + WS_MOD) + scn_off;
;         bf16_t* ap = has_ap ? (bf16_t*)(ws + WS_U + U_AP) : nullptr; float* ssq = (float*)(ws + WS_SSQ);
; #pragma unroll
;         for (int ai = 0; ai < 2; ++ai) {
;             const int rb = u.pm * 256 + ai * 128 + wr * 64 + fr;
;             int mb, pos0, kv0; row_info(rb, mb, pos0, kv0);
;     ...
;             for (int m = 0; m < 4; ++m) {
;                 const int row = rb + 16 * m;
;                 const float* xi = row < MP ? xin_p + (size_t)row * 1024 : xin_s + (size_t)(row - MP) * 1024;
;                 float s = 0.f;
; #pragma unroll
;                 for (int bj = 0; bj < 2; ++bj) {
;                     const int c = u.pn * 256 + bj * 128 + cl;
;                     float v[8];
; #pragma unroll
;                     for (int n = 0; n < 2; ++n) {
;                         const f32x4 x = *(const f32x4*)(xi + c + 4 * n);
;                         const f32x4 y = x + gt[bj][n] * acc[ai][bj][m][n];
;                         *(f32x4*)(xout + (size_t)row * 1024 + c + 4 * n) = y;
; #pragma unroll
;                         for (int j = 0; j < 4; ++j) { s += y[j] * y[j]; v[4 * n + j] = ap ? y[j] * gs[bj][n][j] : 0.f; }
;                     }
;                     if (ap) *(u32x4*)(ap + (size_t)row * 1024 + c) = pack8(v);
;                 }
;                 s = xor16_32(s);
;                 if (fq == 0) ssq[(size_t)row * 16 + u.pn * 4 + wc] = s;
.LBB0_1527:
	s_or_b64 exec, exec, s[4:5]
	s_sub_u32 s70, s18, 0x4000000
	s_subb_u32 s71, s19, 0
	s_cmp_ge_u32 s57, 64
	s_cselect_b32 s70, s70, s8
	s_cselect_b32 s71, s71, s9
	s_lshl_b32 s14, s56, 4
	s_add_u32 s72, s46, s14
	s_addc_u32 s73, s47, 0
	s_lshl_b32 s14, s41, 2
	s_add_u32 s72, s72, s14
	s_addc_u32 s73, s73, 0
	v_lshlrev_b32_e32 v213, 2, v172
	v_lshl_add_u32 v206, v176, 12, v213
	v_lshlrev_b32_e32 v213, 4, v194
	v_sub_u32_e32 v206, v206, v213
	v_mov_b32_e32 v207, v206
	v_lshlrev_b32_e32 v213, 11, v176
	v_lshl_add_u32 v208, v172, 1, v213
	v_lshlrev_b32_e32 v209, 6, v176
	v_lshlrev_b32_e32 v213, 2, v195
	v_lshl_add_u32 v213, v194, 6, v213
	v_xor_b32_e32 v214, 64, v213
	v_xor_b32_e32 v215, 0x80, v213
	global_load_dwordx4 v[232:235], v206, s[70:71] offset:64
	global_load_dwordx4 v[240:243], v206, s[70:71] offset:576
	global_load_dwordx4 v[228:231], v206, s[70:71]
	global_load_dwordx4 v[236:239], v206, s[70:71] offset:512
	v_add_u32_e32 v206, 0x10000, v206
	global_load_dwordx4 v[248:251], v206, s[70:71] offset:64
	global_load_dwordx4 v[220:223], v206, s[70:71] offset:576
	global_load_dwordx4 v[244:247], v206, s[70:71]
	global_load_dwordx4 v[216:219], v206, s[70:71] offset:512
	v_add_u32_e32 v206, 0x10000, v206
	s_waitcnt vmcnt(4)
	v_permlane32_swap_b32_e32 v228, v232
	v_permlane32_swap_b32_e32 v229, v233
	v_permlane32_swap_b32_e32 v230, v234
	v_permlane32_swap_b32_e32 v231, v235
	v_permlane32_swap_b32_e32 v236, v240
	v_permlane32_swap_b32_e32 v237, v241
	v_permlane32_swap_b32_e32 v238, v242
	v_permlane32_swap_b32_e32 v239, v243
	v_permlane16_swap_b32_e32 v228, v232
	v_permlane16_swap_b32_e32 v229, v233
	v_permlane16_swap_b32_e32 v230, v234
	v_permlane16_swap_b32_e32 v231, v235
	v_permlane16_swap_b32_e32 v236, v240
	v_permlane16_swap_b32_e32 v237, v241
	v_permlane16_swap_b32_e32 v238, v242
	v_permlane16_swap_b32_e32 v239, v243
	v_pk_fma_f32 v[140:141], v[140:141], v[144:145], v[228:229]
	v_pk_fma_f32 v[142:143], v[142:143], v[146:147], v[230:231]
	v_mul_f32_e32 v210, v141, v141
	v_fmac_f32_e32 v210, v140, v140
	v_fmac_f32_e32 v210, v142, v142
	v_fmac_f32_e32 v210, v143, v143
	v_pk_fma_f32 v[136:137], v[136:137], v[152:153], v[232:233]
	v_pk_fma_f32 v[138:139], v[138:139], v[154:155], v[234:235]
	v_fmac_f32_e32 v210, v136, v136
	v_fmac_f32_e32 v210, v137, v137
	v_fmac_f32_e32 v210, v138, v138
	v_fmac_f32_e32 v210, v139, v139
	v_pk_fma_f32 v[132:133], v[132:133], v[148:149], v[236:237]
	v_pk_fma_f32 v[134:135], v[134:135], v[150:151], v[238:239]
	v_fmac_f32_e32 v210, v132, v132
	v_fmac_f32_e32 v210, v133, v133
	v_fmac_f32_e32 v210, v134, v134
	v_fmac_f32_e32 v210, v135, v135
	v_pk_fma_f32 v[128:129], v[128:129], v[156:157], v[240:241]
	v_pk_fma_f32 v[130:131], v[130:131], v[158:159], v[242:243]
	v_fmac_f32_e32 v210, v128, v128
	v_fmac_f32_e32 v210, v129, v129
	v_fmac_f32_e32 v210, v130, v130
	v_fmac_f32_e32 v210, v131, v131
	s_cmp_lg_u64 s[2:3], 0
	s_cbranch_scc1 .Lnoap_C_1
	v_pk_mul_f32 v[228:229], v[64:65], v[140:141]
	v_pk_mul_f32 v[230:231], v[66:67], v[142:143]
	v_pk_mul_f32 v[232:233], v[72:73], v[136:137]
	v_pk_mul_f32 v[234:235], v[74:75], v[138:139]
	v_pk_mul_f32 v[236:237], v[68:69], v[132:133]
	v_pk_mul_f32 v[238:239], v[70:71], v[134:135]
	v_pk_mul_f32 v[240:241], v[76:77], v[128:129]
	v_pk_mul_f32 v[242:243], v[78:79], v[130:131]
	v_cvt_pk_bf16_f32 v228, v228, v229
	v_cvt_pk_bf16_f32 v229, v230, v231
	v_cvt_pk_bf16_f32 v230, v232, v233
	v_cvt_pk_bf16_f32 v231, v234, v235
	global_store_dwordx4 v208, v[228:231], s[42:43] sc1
	v_cvt_pk_bf16_f32 v236, v236, v237
	v_cvt_pk_bf16_f32 v237, v238, v239
	v_cvt_pk_bf16_f32 v238, v240, v241
	v_cvt_pk_bf16_f32 v239, v242, v243
	global_store_dwordx4 v208, v[236:239], s[42:43] offset:256 sc1
.Lnoap_C_1:
	ds_bpermute_b32 v211, v214, v210
	v_permlane16_swap_b32_e32 v140, v136
	v_permlane16_swap_b32_e32 v141, v137
	v_permlane16_swap_b32_e32 v142, v138
	v_permlane16_swap_b32_e32 v143, v139
	v_permlane16_swap_b32_e32 v132, v128
	v_permlane16_swap_b32_e32 v133, v129
	v_permlane16_swap_b32_e32 v134, v130
	v_permlane16_swap_b32_e32 v135, v131
	v_permlane32_swap_b32_e32 v140, v136
	v_permlane32_swap_b32_e32 v141, v137
	v_permlane32_swap_b32_e32 v142, v138
	v_permlane32_swap_b32_e32 v143, v139
	v_permlane32_swap_b32_e32 v132, v128
	v_permlane32_swap_b32_e32 v133, v129
	v_permlane32_swap_b32_e32 v134, v130
	v_permlane32_swap_b32_e32 v135, v131
	global_store_dwordx4 v207, v[140:143], s[8:9] sc1
	global_store_dwordx4 v207, v[136:139], s[8:9] offset:64 sc1
	global_store_dwordx4 v207, v[132:135], s[8:9] offset:512 sc1
	global_store_dwordx4 v207, v[128:131], s[8:9] offset:576 sc1
	v_add_u32_e32 v207, 0x10000, v207
	global_load_dwordx4 v[232:235], v206, s[70:71] offset:64
	global_load_dwordx4 v[240:243], v206, s[70:71] offset:576
	global_load_dwordx4 v[228:231], v206, s[70:71]
	global_load_dwordx4 v[236:239], v206, s[70:71] offset:512
	s_waitcnt lgkmcnt(0)
	v_add_f32_e32 v211, v210, v211
	ds_bpermute_b32 v212, v215, v211
	v_add_u32_e32 v208, 0x8000, v208
	s_waitcnt lgkmcnt(0)
	v_add_f32_e32 v211, v211, v212
	s_mov_b64 exec, 0xffff
	global_store_dword v209, v211, s[72:73] sc1
	s_mov_b64 exec, -1
	v_add_u32_e32 v209, 0x400, v209
	s_waitcnt vmcnt(9)
	v_permlane32_swap_b32_e32 v244, v248
	v_permlane32_swap_b32_e32 v245, v249
	v_permlane32_swap_b32_e32 v246, v250
	v_permlane32_swap_b32_e32 v247, v251
	v_permlane32_swap_b32_e32 v216, v220
	v_permlane32_swap_b32_e32 v217, v221
	v_permlane32_swap_b32_e32 v218, v222
	v_permlane32_swap_b32_e32 v219, v223
	v_permlane16_swap_b32_e32 v244, v248
	v_permlane16_swap_b32_e32 v245, v249
	v_permlane16_swap_b32_e32 v246, v250
	v_permlane16_swap_b32_e32 v247, v251
	v_permlane16_swap_b32_e32 v216, v220
	v_permlane16_swap_b32_e32 v217, v221
	v_permlane16_swap_b32_e32 v218, v222
	v_permlane16_swap_b32_e32 v219, v223
	v_pk_fma_f32 v[124:125], v[124:125], v[144:145], v[244:245]
	v_pk_fma_f32 v[126:127], v[126:127], v[146:147], v[246:247]
	v_mul_f32_e32 v210, v125, v125
	v_fmac_f32_e32 v210, v124, v124
	v_fmac_f32_e32 v210, v126, v126
	v_fmac_f32_e32 v210, v127, v127
	v_pk_fma_f32 v[120:121], v[120:121], v[152:153], v[248:249]
	v_pk_fma_f32 v[122:123], v[122:123], v[154:155], v[250:251]
	v_fmac_f32_e32 v210, v120, v120
	v_fmac_f32_e32 v210, v121, v121
	v_fmac_f32_e32 v210, v122, v122
	v_fmac_f32_e32 v210, v123, v123
	v_pk_fma_f32 v[116:117], v[116:117], v[148:149], v[216:217]
	v_pk_fma_f32 v[118:119], v[118:119], v[150:151], v[218:219]
	v_fmac_f32_e32 v210, v116, v116
	v_fmac_f32_e32 v210, v117, v117
	v_fmac_f32_e32 v210, v118, v118
	v_fmac_f32_e32 v210, v119, v119
	v_pk_fma_f32 v[112:113], v[112:113], v[156:157], v[220:221]
	v_pk_fma_f32 v[114:115], v[114:115], v[158:159], v[222:223]
	v_fmac_f32_e32 v210, v112, v112
	v_fmac_f32_e32 v210, v113, v113
	v_fmac_f32_e32 v210, v114, v114
	v_fmac_f32_e32 v210, v115, v115
	s_cmp_lg_u64 s[2:3], 0
	s_cbranch_scc1 .Lnoap_C_2
; DI u32x4 pack8(const float* v) { u32x4 w; w.x = pk2(v[0], v[1]); w.y = pk2(v[2], v[3]); w.z = pk2(v[4], v[5]); w.w = pk2(v[6], v[7]); return w; }
; #define xor16_32(s) xor16_32_l((s), fr + 16 * fq)
;     DI void operator()(AccRef acc, const Unit& u, int wr, int wc, int fr, int fq) const {
;     ...
;             for (int m = 0; m < 4; ++m) {
;                 const int row = rb + 16 * m;
;                 const float* xi = row < MP ? xin_p + (size_t)row * 1024 : xin_s + (size_t)(row - MP) * 1024;
;                 float s = 0.f;
; #pragma unroll
;                 for (int bj = 0; bj < 2; ++bj) {
;                     const int c = u.pn * 256 + bj * 128 + cl;
;                     float v[8];
; #pragma unroll
;                     for (int n = 0; n < 2; ++n) {
;                         const f32x4 x = *(const f32x4*)(xi + c + 4 * n);
;                         const f32x4 y = x + gt[bj][n] * acc[ai][bj][m][n];
;                         *(f32x4*)(xout + (size_t)row * 1024 + c + 4 * n) = y;
; #pragma unroll
;                         for (int j = 0; j < 4; ++j) { s += y[j] * y[j]; v[4 * n + j] = ap ? y[j] * gs[bj][n][j] : 0.f; }
;                     }
;                     if (ap) *(u32x4*)(ap + (size_t)row * 1024 + c) = pack8(v);
;                 }
;                 s = xor16_32(s);
;                 if (fq == 0) ssq[(size_t)row * 16 + u.pn * 4 + wc] = s;
	v_pk_mul_f32 v[244:245], v[64:65], v[124:125]
	v_pk_mul_f32 v[246:247], v[66:67], v[126:127]
	v_pk_mul_f32 v[248:249], v[72:73], v[120:121]
	v_pk_mul_f32 v[250:251], v[74:75], v[122:123]
	v_pk_mul_f32 v[216:217], v[68:69], v[116:117]
	v_pk_mul_f32 v[218:219], v[70:71], v[118:119]
	v_pk_mul_f32 v[220:221], v[76:77], v[112:113]
	v_pk_mul_f32 v[222:223], v[78:79], v[114:115]
	v_cvt_pk_bf16_f32 v244, v244, v245
	v_cvt_pk_bf16_f32 v245, v246, v247
	v_cvt_pk_bf16_f32 v246, v248, v249
	v_cvt_pk_bf16_f32 v247, v250, v251
	global_store_dwordx4 v208, v[244:247], s[42:43] sc1
	v_cvt_pk_bf16_f32 v216, v216, v217
	v_cvt_pk_bf16_f32 v217, v218, v219
	v_cvt_pk_bf16_f32 v218, v220, v221
	v_cvt_pk_bf16_f32 v219, v222, v223
	global_store_dwordx4 v208, v[216:219], s[42:43] offset:256 sc1
.Lnoap_C_2:
	ds_bpermute_b32 v211, v214, v210
	v_permlane16_swap_b32_e32 v124, v120
	v_permlane16_swap_b32_e32 v125, v121
	v_permlane16_swap_b32_e32 v126, v122
	v_permlane16_swap_b32_e32 v127, v123
	v_permlane16_swap_b32_e32 v116, v112
	v_permlane16_swap_b32_e32 v117, v113
	v_permlane16_swap_b32_e32 v118, v114
	v_permlane16_swap_b32_e32 v119, v115
	v_permlane32_swap_b32_e32 v124, v120
	v_permlane32_swap_b32_e32 v125, v121
	v_permlane32_swap_b32_e32 v126, v122
	v_permlane32_swap_b32_e32 v127, v123
	v_permlane32_swap_b32_e32 v116, v112
	v_permlane32_swap_b32_e32 v117, v113
	v_permlane32_swap_b32_e32 v118, v114
	v_permlane32_swap_b32_e32 v119, v115
	global_store_dwordx4 v207, v[124:127], s[8:9] sc1
	global_store_dwordx4 v207, v[120:123], s[8:9] offset:64 sc1
	global_store_dwordx4 v207, v[116:119], s[8:9] offset:512 sc1
	global_store_dwordx4 v207, v[112:115], s[8:9] offset:576 sc1
	v_add_u32_e32 v207, 0x10000, v207
	v_add_u32_e32 v206, 0x10000, v206
	global_load_dwordx4 v[248:251], v206, s[70:71] offset:64
	global_load_dwordx4 v[220:223], v206, s[70:71] offset:576
	global_load_dwordx4 v[244:247], v206, s[70:71]
	global_load_dwordx4 v[216:219], v206, s[70:71] offset:512
	s_waitcnt lgkmcnt(0)
	v_add_f32_e32 v211, v210, v211
	ds_bpermute_b32 v212, v215, v211
	v_add_u32_e32 v208, 0x8000, v208
	s_waitcnt lgkmcnt(0)
	v_add_f32_e32 v211, v211, v212
	s_mov_b64 exec, 0xffff
	global_store_dword v209, v211, s[72:73] sc1
	s_mov_b64 exec, -1
	v_add_u32_e32 v209, 0x400, v209
	s_waitcnt vmcnt(10)
	v_permlane32_swap_b32_e32 v228, v232
	v_permlane32_swap_b32_e32 v229, v233
	v_permlane32_swap_b32_e32 v230, v234
	v_permlane32_swap_b32_e32 v231, v235
	v_permlane32_swap_b32_e32 v236, v240
	v_permlane32_swap_b32_e32 v237, v241
	v_permlane32_swap_b32_e32 v238, v242
	v_permlane32_swap_b32_e32 v239, v243
	v_permlane16_swap_b32_e32 v228, v232
	v_permlane16_swap_b32_e32 v229, v233
	v_permlane16_swap_b32_e32 v230, v234
	v_permlane16_swap_b32_e32 v231, v235
	v_permlane16_swap_b32_e32 v236, v240
	v_permlane16_swap_b32_e32 v237, v241
	v_permlane16_swap_b32_e32 v238, v242
	v_permlane16_swap_b32_e32 v239, v243
	v_pk_fma_f32 v[108:109], v[108:109], v[144:145], v[228:229]
	v_pk_fma_f32 v[110:111], v[110:111], v[146:147], v[230:231]
	v_mul_f32_e32 v210, v109, v109
	v_fmac_f32_e32 v210, v108, v108
	v_fmac_f32_e32 v210, v110, v110
	v_fmac_f32_e32 v210, v111, v111
	v_pk_fma_f32 v[104:105], v[104:105], v[152:153], v[232:233]
	v_pk_fma_f32 v[106:107], v[106:107], v[154:155], v[234:235]
	v_fmac_f32_e32 v210, v104, v104
	v_fmac_f32_e32 v210, v105, v105
	v_fmac_f32_e32 v210, v106, v106
	v_fmac_f32_e32 v210, v107, v107
	v_pk_fma_f32 v[100:101], v[100:101], v[148:149], v[236:237]
	v_pk_fma_f32 v[102:103], v[102:103], v[150:151], v[238:239]
	v_fmac_f32_e32 v210, v100, v100
	v_fmac_f32_e32 v210, v101, v101
	v_fmac_f32_e32 v210, v102, v102
	v_fmac_f32_e32 v210, v103, v103
	v_pk_fma_f32 v[96:97], v[96:97], v[156:157], v[240:241]
	v_pk_fma_f32 v[98:99], v[98:99], v[158:159], v[242:243]
	v_fmac_f32_e32 v210, v96, v96
	v_fmac_f32_e32 v210, v97, v97
	v_fmac_f32_e32 v210, v98, v98
	v_fmac_f32_e32 v210, v99, v99
	s_cmp_lg_u64 s[2:3], 0
	s_cbranch_scc1 .Lnoap_C_3
	v_pk_mul_f32 v[228:229], v[64:65], v[108:109]
	v_pk_mul_f32 v[230:231], v[66:67], v[110:111]
	v_pk_mul_f32 v[232:233], v[72:73], v[104:105]
	v_pk_mul_f32 v[234:235], v[74:75], v[106:107]
	v_pk_mul_f32 v[236:237], v[68:69], v[100:101]
	v_pk_mul_f32 v[238:239], v[70:71], v[102:103]
	v_pk_mul_f32 v[240:241], v[76:77], v[96:97]
	v_pk_mul_f32 v[242:243], v[78:79], v[98:99]
	v_cvt_pk_bf16_f32 v228, v228, v229
	v_cvt_pk_bf16_f32 v229, v230, v231
	v_cvt_pk_bf16_f32 v230, v232, v233
	v_cvt_pk_bf16_f32 v231, v234, v235
	global_store_dwordx4 v208, v[228:231], s[42:43] sc1
	v_cvt_pk_bf16_f32 v236, v236, v237
	v_cvt_pk_bf16_f32 v237, v238, v239
	v_cvt_pk_bf16_f32 v238, v240, v241
	v_cvt_pk_bf16_f32 v239, v242, v243
	global_store_dwordx4 v208, v[236:239], s[42:43] offset:256 sc1
; DI u32x4 pack8(const float* v) { u32x4 w; w.x = pk2(v[0], v[1]); w.y = pk2(v[2], v[3]); w.z = pk2(v[4], v[5]); w.w = pk2(v[6], v[7]); return w; }
; #define xor16_32(s) xor16_32_l((s), fr + 16 * fq)
;     DI void operator()(AccRef acc, const Unit& u, int wr, int wc, int fr, int fq) const {
;     ...
;         for (int ai = 0; ai < 2; ++ai) {
;             const int rb = u.pm * 256 + ai * 128 + wr * 64 + fr;
;             int mb, pos0, kv0; row_info(rb, mb, pos0, kv0);
;             f32x4 gt[2][2], gs[2][2];
; #pragma unroll
;             for (int bj = 0; bj < 2; ++bj)
; #pragma unroll
;                 for (int n = 0; n < 2; ++n) {
;                     const int c = u.pn * 256 + bj * 128 + cl + 4 * n;
;                     gt[bj][n] = *(const f32x4*)(gate + (size_t)mb * 6144 + c);
;                     if (ap) { const f32x4 g = *(const f32x4*)(gn + c), s = *(const f32x4*)(scn + (size_t)mb * 6144 + c); gs[bj][n] = g * (s + 1.f); }
;                 }
;     ...
;             for (int m = 0; m < 4; ++m) {
;                 const int row = rb + 16 * m;
;                 const float* xi = row < MP ? xin_p + (size_t)row * 1024 : xin_s + (size_t)(row - MP) * 1024;
;                 float s = 0.f;
; #pragma unroll
;                 for (int bj = 0; bj < 2; ++bj) {
;                     const int c = u.pn * 256 + bj * 128 + cl;
;                     float v[8];
; #pragma unroll
;                     for (int n = 0; n < 2; ++n) {
;                         const f32x4 x = *(const f32x4*)(xi + c + 4 * n);
;                         const f32x4 y = x + gt[bj][n] * acc[ai][bj][m][n];
;                         *(f32x4*)(xout + (size_t)row * 1024 + c + 4 * n) = y;
; #pragma unroll
;                         for (int j = 0; j < 4; ++j) { s += y[j] * y[j]; v[4 * n + j] = ap ? y[j] * gs[bj][n][j] : 0.f; }
;                     }
;                     if (ap) *(u32x4*)(ap + (size_t)row * 1024 + c) = pack8(v);
;                 }
;                 s = xor16_32(s);
;                 if (fq == 0) ssq[(size_t)row * 16 + u.pn * 4 + wc] = s;
.Lnoap_C_3:
	ds_bpermute_b32 v211, v214, v210
	v_permlane16_swap_b32_e32 v108, v104
	v_permlane16_swap_b32_e32 v109, v105
	v_permlane16_swap_b32_e32 v110, v106
	v_permlane16_swap_b32_e32 v111, v107
	v_permlane16_swap_b32_e32 v100, v96
	v_permlane16_swap_b32_e32 v101, v97
	v_permlane16_swap_b32_e32 v102, v98
	v_permlane16_swap_b32_e32 v103, v99
	v_permlane32_swap_b32_e32 v108, v104
	v_permlane32_swap_b32_e32 v109, v105
	v_permlane32_swap_b32_e32 v110, v106
	v_permlane32_swap_b32_e32 v111, v107
	v_permlane32_swap_b32_e32 v100, v96
	v_permlane32_swap_b32_e32 v101, v97
	v_permlane32_swap_b32_e32 v102, v98
	v_permlane32_swap_b32_e32 v103, v99
	global_store_dwordx4 v207, v[108:111], s[8:9] sc1
	global_store_dwordx4 v207, v[104:107], s[8:9] offset:64 sc1
	global_store_dwordx4 v207, v[100:103], s[8:9] offset:512 sc1
	global_store_dwordx4 v207, v[96:99], s[8:9] offset:576 sc1
	v_add_u32_e32 v207, 0x10000, v207
	v_add_u32_e32 v206, 0x50000, v206
	global_load_dwordx4 v[232:235], v206, s[70:71] offset:64
	global_load_dwordx4 v[240:243], v206, s[70:71] offset:576
	global_load_dwordx4 v[228:231], v206, s[70:71]
	global_load_dwordx4 v[236:239], v206, s[70:71] offset:512
	s_waitcnt lgkmcnt(0)
	v_add_f32_e32 v211, v210, v211
	ds_bpermute_b32 v212, v215, v211
	v_add_u32_e32 v208, 0x8000, v208
	s_waitcnt lgkmcnt(0)
	v_add_f32_e32 v211, v211, v212
	s_mov_b64 exec, 0xffff
	global_store_dword v209, v211, s[72:73] sc1
	s_mov_b64 exec, -1
	v_add_u32_e32 v209, 0x400, v209
	s_waitcnt vmcnt(10)
	v_permlane32_swap_b32_e32 v244, v248
	v_permlane32_swap_b32_e32 v245, v249
	v_permlane32_swap_b32_e32 v246, v250
	v_permlane32_swap_b32_e32 v247, v251
	v_permlane32_swap_b32_e32 v216, v220
	v_permlane32_swap_b32_e32 v217, v221
	v_permlane32_swap_b32_e32 v218, v222
	v_permlane32_swap_b32_e32 v219, v223
	v_permlane16_swap_b32_e32 v244, v248
	v_permlane16_swap_b32_e32 v245, v249
	v_permlane16_swap_b32_e32 v246, v250
	v_permlane16_swap_b32_e32 v247, v251
	v_permlane16_swap_b32_e32 v216, v220
	v_permlane16_swap_b32_e32 v217, v221
	v_permlane16_swap_b32_e32 v218, v222
	v_permlane16_swap_b32_e32 v219, v223
	v_pk_fma_f32 v[92:93], v[92:93], v[144:145], v[244:245]
	v_pk_fma_f32 v[94:95], v[94:95], v[146:147], v[246:247]
	v_mul_f32_e32 v210, v93, v93
	v_fmac_f32_e32 v210, v92, v92
	v_fmac_f32_e32 v210, v94, v94
	v_fmac_f32_e32 v210, v95, v95
	v_pk_fma_f32 v[88:89], v[88:89], v[152:153], v[248:249]
	v_pk_fma_f32 v[90:91], v[90:91], v[154:155], v[250:251]
	v_fmac_f32_e32 v210, v88, v88
	v_fmac_f32_e32 v210, v89, v89
	v_fmac_f32_e32 v210, v90, v90
	v_fmac_f32_e32 v210, v91, v91
	v_pk_fma_f32 v[84:85], v[84:85], v[148:149], v[216:217]
	v_pk_fma_f32 v[86:87], v[86:87], v[150:151], v[218:219]
	v_fmac_f32_e32 v210, v84, v84
	v_fmac_f32_e32 v210, v85, v85
	v_fmac_f32_e32 v210, v86, v86
	v_fmac_f32_e32 v210, v87, v87
	v_pk_fma_f32 v[80:81], v[80:81], v[156:157], v[220:221]
	v_pk_fma_f32 v[82:83], v[82:83], v[158:159], v[222:223]
	v_fmac_f32_e32 v210, v80, v80
	v_fmac_f32_e32 v210, v81, v81
	v_fmac_f32_e32 v210, v82, v82
	v_fmac_f32_e32 v210, v83, v83
	s_cmp_lg_u64 s[2:3], 0
	s_cbranch_scc1 .Lnoap_C_4
	v_pk_mul_f32 v[244:245], v[64:65], v[92:93]
	v_pk_mul_f32 v[246:247], v[66:67], v[94:95]
	v_pk_mul_f32 v[248:249], v[72:73], v[88:89]
	v_pk_mul_f32 v[250:251], v[74:75], v[90:91]
	v_pk_mul_f32 v[216:217], v[68:69], v[84:85]
	v_pk_mul_f32 v[218:219], v[70:71], v[86:87]
	v_pk_mul_f32 v[220:221], v[76:77], v[80:81]
	v_pk_mul_f32 v[222:223], v[78:79], v[82:83]
	v_cvt_pk_bf16_f32 v244, v244, v245
	v_cvt_pk_bf16_f32 v245, v246, v247
	v_cvt_pk_bf16_f32 v246, v248, v249
	v_cvt_pk_bf16_f32 v247, v250, v251
	global_store_dwordx4 v208, v[244:247], s[42:43] sc1
	v_cvt_pk_bf16_f32 v216, v216, v217
	v_cvt_pk_bf16_f32 v217, v218, v219
	v_cvt_pk_bf16_f32 v218, v220, v221
	v_cvt_pk_bf16_f32 v219, v222, v223
	global_store_dwordx4 v208, v[216:219], s[42:43] offset:256 sc1
.Lnoap_C_4:
	ds_bpermute_b32 v211, v214, v210
	v_permlane16_swap_b32_e32 v92, v88
	v_permlane16_swap_b32_e32 v93, v89
	v_permlane16_swap_b32_e32 v94, v90
	v_permlane16_swap_b32_e32 v95, v91
	v_permlane16_swap_b32_e32 v84, v80
	v_permlane16_swap_b32_e32 v85, v81
	v_permlane16_swap_b32_e32 v86, v82
	v_permlane16_swap_b32_e32 v87, v83
	v_permlane32_swap_b32_e32 v92, v88
	v_permlane32_swap_b32_e32 v93, v89
	v_permlane32_swap_b32_e32 v94, v90
	v_permlane32_swap_b32_e32 v95, v91
	v_permlane32_swap_b32_e32 v84, v80
	v_permlane32_swap_b32_e32 v85, v81
	v_permlane32_swap_b32_e32 v86, v82
	v_permlane32_swap_b32_e32 v87, v83
	global_store_dwordx4 v207, v[92:95], s[8:9] sc1
	global_store_dwordx4 v207, v[88:91], s[8:9] offset:64 sc1
	global_store_dwordx4 v207, v[84:87], s[8:9] offset:512 sc1
	global_store_dwordx4 v207, v[80:83], s[8:9] offset:576 sc1
	v_add_u32_e32 v207, 0x50000, v207
	v_add_u32_e32 v206, 0x10000, v206
	global_load_dwordx4 v[248:251], v206, s[70:71] offset:64
	global_load_dwordx4 v[220:223], v206, s[70:71] offset:576
	global_load_dwordx4 v[244:247], v206, s[70:71]
	global_load_dwordx4 v[216:219], v206, s[70:71] offset:512
	s_waitcnt lgkmcnt(0)
	v_add_f32_e32 v211, v210, v211
	ds_bpermute_b32 v212, v215, v211
	v_add_u32_e32 v208, 0x28000, v208
	s_waitcnt lgkmcnt(0)
	v_add_f32_e32 v211, v211, v212
	s_mov_b64 exec, 0xffff
	global_store_dword v209, v211, s[72:73] sc1
	s_mov_b64 exec, -1
	v_add_u32_e32 v209, 0x1400, v209
	v_add_u32_e32 v224, 0xffffc080, v176
	v_add_u32_e32 v96, 0x80, v176
	s_waitcnt lgkmcnt(0)
	v_lshrrev_b32_e32 v81, 6, v224
	v_cmp_gt_i32_e32 vcc, s94, v96
	v_ashrrev_i32_e32 v80, 11, v96
	v_add_u32_e32 v81, 8, v81
	v_cndmask_b32_e32 v84, v81, v80, vcc
	v_mov_b64_e32 v[80:81], s[28:29]
	v_mad_i64_i32 v[80:81], s[12:13], v84, s75, v[80:81]
	v_mov_b64_e32 v[82:83], s[30:31]
	v_lshl_add_u64 v[92:93], v[172:173], 2, v[80:81]
	v_mad_i64_i32 v[84:85], s[12:13], v84, s75, v[82:83]
	global_load_dwordx4 v[80:83], v[92:93], off
	s_movk_i32 s6, 0x3fff
	v_cmp_lt_i32_e64 s[6:7], s6, v96
	s_and_b64 vcc, exec, s[2:3]
	s_cbranch_vccnz .LBB0_1567
	v_lshl_add_u64 v[64:65], v[84:85], 0, v[174:175]
	global_load_dwordx4 v[64:67], v[64:65], off
	s_nop 0
	global_load_dwordx4 v[86:89], v[178:179], off
	s_waitcnt vmcnt(1)
	v_pk_add_f32 v[66:67], v[66:67], 1.0 op_sel_hi:[1,0]
	v_pk_add_f32 v[64:65], v[64:65], 1.0 op_sel_hi:[1,0]
	s_waitcnt vmcnt(0)
	v_pk_mul_f32 v[66:67], v[88:89], v[66:67]
	v_pk_mul_f32 v[64:65], v[86:87], v[64:65]
	global_load_dwordx4 v[88:91], v[92:93], off offset:16
	s_and_b64 vcc, exec, s[2:3]
	v_lshl_add_u64 v[98:99], v[172:173], 2, v[84:85]
	s_cbranch_vccz .LBB0_1568

; DI u32x4 pack8(const float* v) { u32x4 w; w.x = pk2(v[0], v[1]); w.y = pk2(v[2], v[3]); w.z = pk2(v[4], v[5]); w.w = pk2(v[6], v[7]); return w; }
; #define xor16_32(s) xor16_32_l((s), fr + 16 * fq)
;     DI void operator()(AccRef acc, const Unit& u, int wr, int wc, int fr, int fq) const {
;     ...
;             for (int m = 0; m < 4; ++m) {
;                 const int row = rb + 16 * m;
;                 const float* xi = row < MP ? xin_p + (size_t)row * 1024 : xin_s + (size_t)(row - MP) * 1024;
;                 float s = 0.f;
; #pragma unroll
;                 for (int bj = 0; bj < 2; ++bj) {
;                     const int c = u.pn * 256 + bj * 128 + cl;
;                     float v[8];
; #pragma unroll
;                     for (int n = 0; n < 2; ++n) {
;                         const f32x4 x = *(const f32x4*)(xi + c + 4 * n);
;                         const f32x4 y = x + gt[bj][n] * acc[ai][bj][m][n];
;                         *(f32x4*)(xout + (size_t)row * 1024 + c + 4 * n) = y;
; #pragma unroll
;                         for (int j = 0; j < 4; ++j) { s += y[j] * y[j]; v[4 * n + j] = ap ? y[j] * gs[bj][n][j] : 0.f; }
;                     }
;                     if (ap) *(u32x4*)(ap + (size_t)row * 1024 + c) = pack8(v);
;                 }
;                 s = xor16_32(s);
;                 if (fq == 0) ssq[(size_t)row * 16 + u.pn * 4 + wc] = s;
.LBB0_1575:
	s_or_b64 exec, exec, s[6:7]
	s_waitcnt vmcnt(0)
	v_permlane32_swap_b32_e32 v228, v232
	v_permlane32_swap_b32_e32 v229, v233
	v_permlane32_swap_b32_e32 v230, v234
	v_permlane32_swap_b32_e32 v231, v235
	v_permlane32_swap_b32_e32 v236, v240
	v_permlane32_swap_b32_e32 v237, v241
	v_permlane32_swap_b32_e32 v238, v242
	v_permlane32_swap_b32_e32 v239, v243
	v_permlane16_swap_b32_e32 v228, v232
	v_permlane16_swap_b32_e32 v229, v233
	v_permlane16_swap_b32_e32 v230, v234
	v_permlane16_swap_b32_e32 v231, v235
	v_permlane16_swap_b32_e32 v236, v240
	v_permlane16_swap_b32_e32 v237, v241
	v_permlane16_swap_b32_e32 v238, v242
	v_permlane16_swap_b32_e32 v239, v243
	v_pk_fma_f32 v[60:61], v[60:61], v[80:81], v[228:229]
	v_pk_fma_f32 v[62:63], v[62:63], v[82:83], v[230:231]
	v_mul_f32_e32 v210, v61, v61
	v_fmac_f32_e32 v210, v60, v60
	v_fmac_f32_e32 v210, v62, v62
	v_fmac_f32_e32 v210, v63, v63
	v_pk_fma_f32 v[56:57], v[56:57], v[88:89], v[232:233]
	v_pk_fma_f32 v[58:59], v[58:59], v[90:91], v[234:235]
	v_fmac_f32_e32 v210, v56, v56
	v_fmac_f32_e32 v210, v57, v57
	v_fmac_f32_e32 v210, v58, v58
	v_fmac_f32_e32 v210, v59, v59
	v_pk_fma_f32 v[52:53], v[52:53], v[84:85], v[236:237]
	v_pk_fma_f32 v[54:55], v[54:55], v[86:87], v[238:239]
	v_fmac_f32_e32 v210, v52, v52
	v_fmac_f32_e32 v210, v53, v53
	v_fmac_f32_e32 v210, v54, v54
	v_fmac_f32_e32 v210, v55, v55
	v_pk_fma_f32 v[48:49], v[48:49], v[92:93], v[240:241]
	v_pk_fma_f32 v[50:51], v[50:51], v[94:95], v[242:243]
	v_fmac_f32_e32 v210, v48, v48
	v_fmac_f32_e32 v210, v49, v49
	v_fmac_f32_e32 v210, v50, v50
	v_fmac_f32_e32 v210, v51, v51
	s_cmp_lg_u64 s[2:3], 0
	s_cbranch_scc1 .Lnoap_C_5
	v_pk_mul_f32 v[228:229], v[64:65], v[60:61]
	v_pk_mul_f32 v[230:231], v[66:67], v[62:63]
	v_pk_mul_f32 v[232:233], v[72:73], v[56:57]
	v_pk_mul_f32 v[234:235], v[74:75], v[58:59]
	v_pk_mul_f32 v[236:237], v[68:69], v[52:53]
	v_pk_mul_f32 v[238:239], v[70:71], v[54:55]
	v_pk_mul_f32 v[240:241], v[76:77], v[48:49]
	v_pk_mul_f32 v[242:243], v[78:79], v[50:51]
	v_cvt_pk_bf16_f32 v228, v228, v229
	v_cvt_pk_bf16_f32 v229, v230, v231
	v_cvt_pk_bf16_f32 v230, v232, v233
	v_cvt_pk_bf16_f32 v231, v234, v235
	global_store_dwordx4 v208, v[228:231], s[42:43] sc1
	v_cvt_pk_bf16_f32 v236, v236, v237
	v_cvt_pk_bf16_f32 v237, v238, v239
	v_cvt_pk_bf16_f32 v238, v240, v241
	v_cvt_pk_bf16_f32 v239, v242, v243
	global_store_dwordx4 v208, v[236:239], s[42:43] offset:256 sc1
.Lnoap_C_5:
	ds_bpermute_b32 v211, v214, v210
	v_permlane16_swap_b32_e32 v60, v56
	v_permlane16_swap_b32_e32 v61, v57
	v_permlane16_swap_b32_e32 v62, v58
	v_permlane16_swap_b32_e32 v63, v59
	v_permlane16_swap_b32_e32 v52, v48
	v_permlane16_swap_b32_e32 v53, v49
	v_permlane16_swap_b32_e32 v54, v50
	v_permlane16_swap_b32_e32 v55, v51
	v_permlane32_swap_b32_e32 v60, v56
	v_permlane32_swap_b32_e32 v61, v57
	v_permlane32_swap_b32_e32 v62, v58
	v_permlane32_swap_b32_e32 v63, v59
	v_permlane32_swap_b32_e32 v52, v48
	v_permlane32_swap_b32_e32 v53, v49
	v_permlane32_swap_b32_e32 v54, v50
	v_permlane32_swap_b32_e32 v55, v51
	global_store_dwordx4 v207, v[60:63], s[8:9] sc1
	global_store_dwordx4 v207, v[56:59], s[8:9] offset:64 sc1
	global_store_dwordx4 v207, v[52:55], s[8:9] offset:512 sc1
	global_store_dwordx4 v207, v[48:51], s[8:9] offset:576 sc1
	v_add_u32_e32 v207, 0x10000, v207
	v_add_u32_e32 v206, 0x10000, v206
	global_load_dwordx4 v[232:235], v206, s[70:71] offset:64
	global_load_dwordx4 v[240:243], v206, s[70:71] offset:576
	global_load_dwordx4 v[228:231], v206, s[70:71]
	global_load_dwordx4 v[236:239], v206, s[70:71] offset:512
	s_waitcnt lgkmcnt(0)
	v_add_f32_e32 v211, v210, v211
	ds_bpermute_b32 v212, v215, v211
	v_add_u32_e32 v208, 0x8000, v208
	s_waitcnt lgkmcnt(0)
	v_add_f32_e32 v211, v211, v212
	s_mov_b64 exec, 0xffff
	global_store_dword v209, v211, s[72:73] sc1
	s_mov_b64 exec, -1
	v_add_u32_e32 v209, 0x400, v209
	v_permlane32_swap_b32_e32 v244, v248
	v_permlane32_swap_b32_e32 v245, v249
	v_permlane32_swap_b32_e32 v246, v250
	v_permlane32_swap_b32_e32 v247, v251
	v_permlane32_swap_b32_e32 v216, v220
	v_permlane32_swap_b32_e32 v217, v221
	v_permlane32_swap_b32_e32 v218, v222
	v_permlane32_swap_b32_e32 v219, v223
	v_permlane16_swap_b32_e32 v244, v248
	v_permlane16_swap_b32_e32 v245, v249
	v_permlane16_swap_b32_e32 v246, v250
	v_permlane16_swap_b32_e32 v247, v251
	v_permlane16_swap_b32_e32 v216, v220
	v_permlane16_swap_b32_e32 v217, v221
	v_permlane16_swap_b32_e32 v218, v222
	v_permlane16_swap_b32_e32 v219, v223
	v_pk_fma_f32 v[44:45], v[44:45], v[80:81], v[244:245]
	v_pk_fma_f32 v[46:47], v[46:47], v[82:83], v[246:247]
	v_mul_f32_e32 v210, v45, v45
	v_fmac_f32_e32 v210, v44, v44
	v_fmac_f32_e32 v210, v46, v46
	v_fmac_f32_e32 v210, v47, v47
	v_pk_fma_f32 v[40:41], v[40:41], v[88:89], v[248:249]
	v_pk_fma_f32 v[42:43], v[42:43], v[90:91], v[250:251]
	v_fmac_f32_e32 v210, v40, v40
	v_fmac_f32_e32 v210, v41, v41
	v_fmac_f32_e32 v210, v42, v42
	v_fmac_f32_e32 v210, v43, v43
	v_pk_fma_f32 v[36:37], v[36:37], v[84:85], v[216:217]
	v_pk_fma_f32 v[38:39], v[38:39], v[86:87], v[218:219]
	v_fmac_f32_e32 v210, v36, v36
	v_fmac_f32_e32 v210, v37, v37
	v_fmac_f32_e32 v210, v38, v38
	v_fmac_f32_e32 v210, v39, v39
	v_pk_fma_f32 v[32:33], v[32:33], v[92:93], v[220:221]
	v_pk_fma_f32 v[34:35], v[34:35], v[94:95], v[222:223]
	v_fmac_f32_e32 v210, v32, v32
	v_fmac_f32_e32 v210, v33, v33
	v_fmac_f32_e32 v210, v34, v34
	v_fmac_f32_e32 v210, v35, v35
	s_cmp_lg_u64 s[2:3], 0
	s_cbranch_scc1 .Lnoap_C_6
	v_pk_mul_f32 v[244:245], v[64:65], v[44:45]
	v_pk_mul_f32 v[246:247], v[66:67], v[46:47]
	v_pk_mul_f32 v[248:249], v[72:73], v[40:41]
	v_pk_mul_f32 v[250:251], v[74:75], v[42:43]
	v_pk_mul_f32 v[216:217], v[68:69], v[36:37]
	v_pk_mul_f32 v[218:219], v[70:71], v[38:39]
	v_pk_mul_f32 v[220:221], v[76:77], v[32:33]
	v_pk_mul_f32 v[222:223], v[78:79], v[34:35]
	v_cvt_pk_bf16_f32 v244, v244, v245
	v_cvt_pk_bf16_f32 v245, v246, v247
	v_cvt_pk_bf16_f32 v246, v248, v249
	v_cvt_pk_bf16_f32 v247, v250, v251
	global_store_dwordx4 v208, v[244:247], s[42:43] sc1
	v_cvt_pk_bf16_f32 v216, v216, v217
	v_cvt_pk_bf16_f32 v217, v218, v219
	v_cvt_pk_bf16_f32 v218, v220, v221
	v_cvt_pk_bf16_f32 v219, v222, v223
	global_store_dwordx4 v208, v[216:219], s[42:43] offset:256 sc1
; DI u32x4 pack8(const float* v) { u32x4 w; w.x = pk2(v[0], v[1]); w.y = pk2(v[2], v[3]); w.z = pk2(v[4], v[5]); w.w = pk2(v[6], v[7]); return w; }
; #define xor16_32(s) xor16_32_l((s), fr + 16 * fq)
;     DI void operator()(AccRef acc, const Unit& u, int wr, int wc, int fr, int fq) const {
;     ...
;             for (int m = 0; m < 4; ++m) {
;                 const int row = rb + 16 * m;
;                 const float* xi = row < MP ? xin_p + (size_t)row * 1024 : xin_s + (size_t)(row - MP) * 1024;
;                 float s = 0.f;
; #pragma unroll
;                 for (int bj = 0; bj < 2; ++bj) {
;                     const int c = u.pn * 256 + bj * 128 + cl;
;                     float v[8];
; #pragma unroll
;                     for (int n = 0; n < 2; ++n) {
;                         const f32x4 x = *(const f32x4*)(xi + c + 4 * n);
;                         const f32x4 y = x + gt[bj][n] * acc[ai][bj][m][n];
;                         *(f32x4*)(xout + (size_t)row * 1024 + c + 4 * n) = y;
; #pragma unroll
;                         for (int j = 0; j < 4; ++j) { s += y[j] * y[j]; v[4 * n + j] = ap ? y[j] * gs[bj][n][j] : 0.f; }
;                     }
;                     if (ap) *(u32x4*)(ap + (size_t)row * 1024 + c) = pack8(v);
;                 }
;                 s = xor16_32(s);
;                 if (fq == 0) ssq[(size_t)row * 16 + u.pn * 4 + wc] = s;
.Lnoap_C_6:
	ds_bpermute_b32 v211, v214, v210
	v_permlane16_swap_b32_e32 v44, v40
	v_permlane16_swap_b32_e32 v45, v41
	v_permlane16_swap_b32_e32 v46, v42
	v_permlane16_swap_b32_e32 v47, v43
	v_permlane16_swap_b32_e32 v36, v32
	v_permlane16_swap_b32_e32 v37, v33
	v_permlane16_swap_b32_e32 v38, v34
	v_permlane16_swap_b32_e32 v39, v35
	v_permlane32_swap_b32_e32 v44, v40
	v_permlane32_swap_b32_e32 v45, v41
	v_permlane32_swap_b32_e32 v46, v42
	v_permlane32_swap_b32_e32 v47, v43
	v_permlane32_swap_b32_e32 v36, v32
	v_permlane32_swap_b32_e32 v37, v33
	v_permlane32_swap_b32_e32 v38, v34
	v_permlane32_swap_b32_e32 v39, v35
	global_store_dwordx4 v207, v[44:47], s[8:9] sc1
	global_store_dwordx4 v207, v[40:43], s[8:9] offset:64 sc1
	global_store_dwordx4 v207, v[36:39], s[8:9] offset:512 sc1
	global_store_dwordx4 v207, v[32:35], s[8:9] offset:576 sc1
	v_add_u32_e32 v207, 0x10000, v207
	v_add_u32_e32 v206, 0x10000, v206
	global_load_dwordx4 v[248:251], v206, s[70:71] offset:64
	global_load_dwordx4 v[220:223], v206, s[70:71] offset:576
	global_load_dwordx4 v[244:247], v206, s[70:71]
	global_load_dwordx4 v[216:219], v206, s[70:71] offset:512
	s_waitcnt lgkmcnt(0)
	v_add_f32_e32 v211, v210, v211
	ds_bpermute_b32 v212, v215, v211
	v_add_u32_e32 v208, 0x8000, v208
	s_waitcnt lgkmcnt(0)
	v_add_f32_e32 v211, v211, v212
	s_mov_b64 exec, 0xffff
	global_store_dword v209, v211, s[72:73] sc1
	s_mov_b64 exec, -1
	v_add_u32_e32 v209, 0x400, v209
	s_waitcnt vmcnt(10)
	v_permlane32_swap_b32_e32 v228, v232
	v_permlane32_swap_b32_e32 v229, v233
	v_permlane32_swap_b32_e32 v230, v234
	v_permlane32_swap_b32_e32 v231, v235
	v_permlane32_swap_b32_e32 v236, v240
	v_permlane32_swap_b32_e32 v237, v241
	v_permlane32_swap_b32_e32 v238, v242
	v_permlane32_swap_b32_e32 v239, v243
	v_permlane16_swap_b32_e32 v228, v232
	v_permlane16_swap_b32_e32 v229, v233
	v_permlane16_swap_b32_e32 v230, v234
	v_permlane16_swap_b32_e32 v231, v235
	v_permlane16_swap_b32_e32 v236, v240
	v_permlane16_swap_b32_e32 v237, v241
	v_permlane16_swap_b32_e32 v238, v242
	v_permlane16_swap_b32_e32 v239, v243
	v_pk_fma_f32 v[28:29], v[28:29], v[80:81], v[228:229]
	v_pk_fma_f32 v[30:31], v[30:31], v[82:83], v[230:231]
	v_mul_f32_e32 v210, v29, v29
	v_fmac_f32_e32 v210, v28, v28
	v_fmac_f32_e32 v210, v30, v30
	v_fmac_f32_e32 v210, v31, v31
	v_pk_fma_f32 v[24:25], v[24:25], v[88:89], v[232:233]
	v_pk_fma_f32 v[26:27], v[26:27], v[90:91], v[234:235]
	v_fmac_f32_e32 v210, v24, v24
	v_fmac_f32_e32 v210, v25, v25
	v_fmac_f32_e32 v210, v26, v26
	v_fmac_f32_e32 v210, v27, v27
	v_pk_fma_f32 v[20:21], v[20:21], v[84:85], v[236:237]
	v_pk_fma_f32 v[22:23], v[22:23], v[86:87], v[238:239]
	v_fmac_f32_e32 v210, v20, v20
	v_fmac_f32_e32 v210, v21, v21
	v_fmac_f32_e32 v210, v22, v22
	v_fmac_f32_e32 v210, v23, v23
	v_pk_fma_f32 v[16:17], v[16:17], v[92:93], v[240:241]
	v_pk_fma_f32 v[18:19], v[18:19], v[94:95], v[242:243]
	v_fmac_f32_e32 v210, v16, v16
	v_fmac_f32_e32 v210, v17, v17
	v_fmac_f32_e32 v210, v18, v18
	v_fmac_f32_e32 v210, v19, v19
	s_cmp_lg_u64 s[2:3], 0
	s_cbranch_scc1 .Lnoap_C_7
	v_pk_mul_f32 v[228:229], v[64:65], v[28:29]
	v_pk_mul_f32 v[230:231], v[66:67], v[30:31]
	v_pk_mul_f32 v[232:233], v[72:73], v[24:25]
	v_pk_mul_f32 v[234:235], v[74:75], v[26:27]
	v_pk_mul_f32 v[236:237], v[68:69], v[20:21]
	v_pk_mul_f32 v[238:239], v[70:71], v[22:23]
	v_pk_mul_f32 v[240:241], v[76:77], v[16:17]
	v_pk_mul_f32 v[242:243], v[78:79], v[18:19]
	v_cvt_pk_bf16_f32 v228, v228, v229
	v_cvt_pk_bf16_f32 v229, v230, v231
	v_cvt_pk_bf16_f32 v230, v232, v233
	v_cvt_pk_bf16_f32 v231, v234, v235
	global_store_dwordx4 v208, v[228:231], s[42:43] sc1
	v_cvt_pk_bf16_f32 v236, v236, v237
	v_cvt_pk_bf16_f32 v237, v238, v239
	v_cvt_pk_bf16_f32 v238, v240, v241
	v_cvt_pk_bf16_f32 v239, v242, v243
	global_store_dwordx4 v208, v[236:239], s[42:43] offset:256 sc1
; DI u32x4 pack8(const float* v) { u32x4 w; w.x = pk2(v[0], v[1]); w.y = pk2(v[2], v[3]); w.z = pk2(v[4], v[5]); w.w = pk2(v[6], v[7]); return w; }
; #define xor16_32(s) xor16_32_l((s), fr + 16 * fq)
;     DI void operator()(AccRef acc, const Unit& u, int wr, int wc, int fr, int fq) const {
;     ...
;             for (int m = 0; m < 4; ++m) {
;                 const int row = rb + 16 * m;
;                 const float* xi = row < MP ? xin_p + (size_t)row * 1024 : xin_s + (size_t)(row - MP) * 1024;
;                 float s = 0.f;
; #pragma unroll
;                 for (int bj = 0; bj < 2; ++bj) {
;                     const int c = u.pn * 256 + bj * 128 + cl;
;                     float v[8];
; #pragma unroll
;                     for (int n = 0; n < 2; ++n) {
;                         const f32x4 x = *(const f32x4*)(xi + c + 4 * n);
;                         const f32x4 y = x + gt[bj][n] * acc[ai][bj][m][n];
;                         *(f32x4*)(xout + (size_t)row * 1024 + c + 4 * n) = y;
; #pragma unroll
;                         for (int j = 0; j < 4; ++j) { s += y[j] * y[j]; v[4 * n + j] = ap ? y[j] * gs[bj][n][j] : 0.f; }
;                     }
;                     if (ap) *(u32x4*)(ap + (size_t)row * 1024 + c) = pack8(v);
;                 }
;                 s = xor16_32(s);
;                 if (fq == 0) ssq[(size_t)row * 16 + u.pn * 4 + wc] = s;
.Lnoap_C_7:
	ds_bpermute_b32 v211, v214, v210
	v_permlane16_swap_b32_e32 v28, v24
	v_permlane16_swap_b32_e32 v29, v25
	v_permlane16_swap_b32_e32 v30, v26
	v_permlane16_swap_b32_e32 v31, v27
	v_permlane16_swap_b32_e32 v20, v16
	v_permlane16_swap_b32_e32 v21, v17
	v_permlane16_swap_b32_e32 v22, v18
	v_permlane16_swap_b32_e32 v23, v19
	v_permlane32_swap_b32_e32 v28, v24
	v_permlane32_swap_b32_e32 v29, v25
	v_permlane32_swap_b32_e32 v30, v26
	v_permlane32_swap_b32_e32 v31, v27
	v_permlane32_swap_b32_e32 v20, v16
	v_permlane32_swap_b32_e32 v21, v17
	v_permlane32_swap_b32_e32 v22, v18
	v_permlane32_swap_b32_e32 v23, v19
	global_store_dwordx4 v207, v[28:31], s[8:9] sc1
	global_store_dwordx4 v207, v[24:27], s[8:9] offset:64 sc1
	global_store_dwordx4 v207, v[20:23], s[8:9] offset:512 sc1
	global_store_dwordx4 v207, v[16:19], s[8:9] offset:576 sc1
	v_add_u32_e32 v207, 0x10000, v207
	s_waitcnt lgkmcnt(0)
	v_add_f32_e32 v211, v210, v211
	ds_bpermute_b32 v212, v215, v211
	v_add_u32_e32 v208, 0x8000, v208
	s_waitcnt lgkmcnt(0)
	v_add_f32_e32 v211, v211, v212
	s_mov_b64 exec, 0xffff
	global_store_dword v209, v211, s[72:73] sc1
	s_mov_b64 exec, -1
	v_add_u32_e32 v209, 0x400, v209
	s_waitcnt vmcnt(6)
	v_permlane32_swap_b32_e32 v244, v248
	v_permlane32_swap_b32_e32 v245, v249
	v_permlane32_swap_b32_e32 v246, v250
	v_permlane32_swap_b32_e32 v247, v251
	v_permlane32_swap_b32_e32 v216, v220
	v_permlane32_swap_b32_e32 v217, v221
	v_permlane32_swap_b32_e32 v218, v222
	v_permlane32_swap_b32_e32 v219, v223
	v_permlane16_swap_b32_e32 v244, v248
	v_permlane16_swap_b32_e32 v245, v249
	v_permlane16_swap_b32_e32 v246, v250
	v_permlane16_swap_b32_e32 v247, v251
	v_permlane16_swap_b32_e32 v216, v220
	v_permlane16_swap_b32_e32 v217, v221
	v_permlane16_swap_b32_e32 v218, v222
	v_permlane16_swap_b32_e32 v219, v223
	v_pk_fma_f32 v[12:13], v[12:13], v[80:81], v[244:245]
	v_pk_fma_f32 v[14:15], v[14:15], v[82:83], v[246:247]
	v_mul_f32_e32 v210, v13, v13
	v_fmac_f32_e32 v210, v12, v12
	v_fmac_f32_e32 v210, v14, v14
	v_fmac_f32_e32 v210, v15, v15
	v_pk_fma_f32 v[8:9], v[8:9], v[88:89], v[248:249]
	v_pk_fma_f32 v[10:11], v[10:11], v[90:91], v[250:251]
	v_fmac_f32_e32 v210, v8, v8
	v_fmac_f32_e32 v210, v9, v9
	v_fmac_f32_e32 v210, v10, v10
	v_fmac_f32_e32 v210, v11, v11
	v_pk_fma_f32 v[4:5], v[4:5], v[84:85], v[216:217]
	v_pk_fma_f32 v[6:7], v[6:7], v[86:87], v[218:219]
	v_fmac_f32_e32 v210, v4, v4
	v_fmac_f32_e32 v210, v5, v5
	v_fmac_f32_e32 v210, v6, v6
	v_fmac_f32_e32 v210, v7, v7
	v_pk_fma_f32 v[0:1], v[0:1], v[92:93], v[220:221]
	v_pk_fma_f32 v[2:3], v[2:3], v[94:95], v[222:223]
	v_fmac_f32_e32 v210, v0, v0
	v_fmac_f32_e32 v210, v1, v1
	v_fmac_f32_e32 v210, v2, v2
	v_fmac_f32_e32 v210, v3, v3
	s_cmp_lg_u64 s[2:3], 0
	s_cbranch_scc1 .Lnoap_C_8
	v_pk_mul_f32 v[244:245], v[64:65], v[12:13]
	v_pk_mul_f32 v[246:247], v[66:67], v[14:15]
	v_pk_mul_f32 v[248:249], v[72:73], v[8:9]
	v_pk_mul_f32 v[250:251], v[74:75], v[10:11]
	v_pk_mul_f32 v[216:217], v[68:69], v[4:5]
	v_pk_mul_f32 v[218:219], v[70:71], v[6:7]
	v_pk_mul_f32 v[220:221], v[76:77], v[0:1]
	v_pk_mul_f32 v[222:223], v[78:79], v[2:3]
	v_cvt_pk_bf16_f32 v244, v244, v245
	v_cvt_pk_bf16_f32 v245, v246, v247
	v_cvt_pk_bf16_f32 v246, v248, v249
	v_cvt_pk_bf16_f32 v247, v250, v251
	global_store_dwordx4 v208, v[244:247], s[42:43] sc1
	v_cvt_pk_bf16_f32 v216, v216, v217
	v_cvt_pk_bf16_f32 v217, v218, v219
	v_cvt_pk_bf16_f32 v218, v220, v221
	v_cvt_pk_bf16_f32 v219, v222, v223
	global_store_dwordx4 v208, v[216:219], s[42:43] offset:256 sc1
.Lnoap_C_8:
	ds_bpermute_b32 v211, v214, v210
	v_permlane16_swap_b32_e32 v12, v8
	v_permlane16_swap_b32_e32 v13, v9
	v_permlane16_swap_b32_e32 v14, v10
	v_permlane16_swap_b32_e32 v15, v11
	v_permlane16_swap_b32_e32 v4, v0
	v_permlane16_swap_b32_e32 v5, v1
	v_permlane16_swap_b32_e32 v6, v2
	v_permlane16_swap_b32_e32 v7, v3
	v_permlane32_swap_b32_e32 v12, v8
	v_permlane32_swap_b32_e32 v13, v9
	v_permlane32_swap_b32_e32 v14, v10
	v_permlane32_swap_b32_e32 v15, v11
	v_permlane32_swap_b32_e32 v4, v0
	v_permlane32_swap_b32_e32 v5, v1
	v_permlane32_swap_b32_e32 v6, v2
	v_permlane32_swap_b32_e32 v7, v3
	global_store_dwordx4 v207, v[12:15], s[8:9] sc1
	global_store_dwordx4 v207, v[8:11], s[8:9] offset:64 sc1
	global_store_dwordx4 v207, v[4:7], s[8:9] offset:512 sc1
	global_store_dwordx4 v207, v[0:3], s[8:9] offset:576 sc1
	s_waitcnt lgkmcnt(0)
	v_add_f32_e32 v211, v210, v211
	ds_bpermute_b32 v212, v215, v211
	s_waitcnt lgkmcnt(0)
	v_add_f32_e32 v211, v211, v212
	s_mov_b64 exec, 0xffff
	global_store_dword v209, v211, s[72:73] sc1
	s_mov_b64 exec, -1
	s_and_b64 vcc, exec, s[0:1]
	s_mov_b64 s[0:1], -1
	s_cbranch_vccnz .LBB0_1500
	s_andn2_b64 vcc, exec, s[16:17]
	s_cbranch_vccnz .LBB0_1499
	s_barrier
	s_branch .LBB0_1499

; DI u32x4 pack8(const float* v) { u32x4 w; w.x = pk2(v[0], v[1]); w.y = pk2(v[2], v[3]); w.z = pk2(v[4], v[5]); w.w = pk2(v[6], v[7]); return w; }
; #define xor16_32(s) xor16_32_l((s), fr + 16 * fq)
;     DI void operator()(AccRef acc, const Unit& u, int wr, int wc, int fr, int fq) const {
;         const int cl = wc * 32 + fq * 8;
;         const float* gate = (const float*)(ws + WS_MOD) + gate_off; const float* scn = (const float*)(ws + WS_MOD) + scn_off;
;         bf16_t* ap = has_ap ? (bf16_t*)(ws + WS_U + U_AP) : nullptr; float* ssq = (float*)(ws + WS_SSQ);
; #pragma unroll
;         for (int ai = 0; ai < 2; ++ai) {
;             const int rb = u.pm * 256 + ai * 128 + wr * 64 + fr;
;             int mb, pos0, kv0; row_info(rb, mb, pos0, kv0);
;     ...
;             for (int m = 0; m < 4; ++m) {
;                 const int row = rb + 16 * m;
;                 const float* xi = row < MP ? xin_p + (size_t)row * 1024 : xin_s + (size_t)(row - MP) * 1024;
;                 float s = 0.f;
; #pragma unroll
;                 for (int bj = 0; bj < 2; ++bj) {
;                     const int c = u.pn * 256 + bj * 128 + cl;
;                     float v[8];
; #pragma unroll
;                     for (int n = 0; n < 2; ++n) {
;                         const f32x4 x = *(const f32x4*)(xi + c + 4 * n);
;                         const f32x4 y = x + gt[bj][n] * acc[ai][bj][m][n];
;                         *(f32x4*)(xout + (size_t)row * 1024 + c + 4 * n) = y;
; #pragma unroll
;                         for (int j = 0; j < 4; ++j) { s += y[j] * y[j]; v[4 * n + j] = ap ? y[j] * gs[bj][n][j] : 0.f; }
;                     }
;                     if (ap) *(u32x4*)(ap + (size_t)row * 1024 + c) = pack8(v);
;                 }
;                 s = xor16_32(s);
;                 if (fq == 0) ssq[(size_t)row * 16 + u.pn * 4 + wc] = s;
.LBB0_2061:
	s_or_b64 exec, exec, s[4:5]
	s_sub_u32 s70, s10, 0x4000000
	s_subb_u32 s71, s11, 0
	s_cmp_ge_u32 s43, 64
	s_cselect_b32 s70, s70, s84
	s_cselect_b32 s71, s71, s85
	s_lshl_b32 s14, s42, 4
	s_add_u32 s72, s52, s14
	s_addc_u32 s73, s53, 0
	s_lshl_b32 s14, s54, 2
	s_add_u32 s72, s72, s14
	s_addc_u32 s73, s73, 0
	v_lshlrev_b32_e32 v213, 2, v172
	v_lshl_add_u32 v206, v176, 12, v213
	v_lshlrev_b32_e32 v213, 4, v194
	v_sub_u32_e32 v206, v206, v213
	v_mov_b32_e32 v207, v206
	v_lshlrev_b32_e32 v213, 11, v176
	v_lshl_add_u32 v208, v172, 1, v213
	v_lshlrev_b32_e32 v209, 6, v176
	v_lshlrev_b32_e32 v213, 2, v195
	v_lshl_add_u32 v213, v194, 6, v213
	v_xor_b32_e32 v214, 64, v213
	v_xor_b32_e32 v215, 0x80, v213
	global_load_dwordx4 v[232:235], v206, s[70:71] offset:64
	global_load_dwordx4 v[240:243], v206, s[70:71] offset:576
	global_load_dwordx4 v[228:231], v206, s[70:71]
	global_load_dwordx4 v[236:239], v206, s[70:71] offset:512
	v_add_u32_e32 v206, 0x10000, v206
	global_load_dwordx4 v[248:251], v206, s[70:71] offset:64
	global_load_dwordx4 v[220:223], v206, s[70:71] offset:576
	global_load_dwordx4 v[244:247], v206, s[70:71]
	global_load_dwordx4 v[216:219], v206, s[70:71] offset:512
	v_add_u32_e32 v206, 0x10000, v206
	s_waitcnt vmcnt(4)
	v_permlane32_swap_b32_e32 v228, v232
	v_permlane32_swap_b32_e32 v229, v233
	v_permlane32_swap_b32_e32 v230, v234
	v_permlane32_swap_b32_e32 v231, v235
	v_permlane32_swap_b32_e32 v236, v240
	v_permlane32_swap_b32_e32 v237, v241
	v_permlane32_swap_b32_e32 v238, v242
	v_permlane32_swap_b32_e32 v239, v243
	v_permlane16_swap_b32_e32 v228, v232
	v_permlane16_swap_b32_e32 v229, v233
	v_permlane16_swap_b32_e32 v230, v234
	v_permlane16_swap_b32_e32 v231, v235
	v_permlane16_swap_b32_e32 v236, v240
	v_permlane16_swap_b32_e32 v237, v241
	v_permlane16_swap_b32_e32 v238, v242
	v_permlane16_swap_b32_e32 v239, v243
	v_pk_fma_f32 v[140:141], v[140:141], v[144:145], v[228:229]
	v_pk_fma_f32 v[142:143], v[142:143], v[146:147], v[230:231]
	v_mul_f32_e32 v210, v141, v141
	v_fmac_f32_e32 v210, v140, v140
	v_fmac_f32_e32 v210, v142, v142
	v_fmac_f32_e32 v210, v143, v143
	v_pk_fma_f32 v[136:137], v[136:137], v[152:153], v[232:233]
	v_pk_fma_f32 v[138:139], v[138:139], v[154:155], v[234:235]
	v_fmac_f32_e32 v210, v136, v136
	v_fmac_f32_e32 v210, v137, v137
	v_fmac_f32_e32 v210, v138, v138
	v_fmac_f32_e32 v210, v139, v139
	v_pk_fma_f32 v[132:133], v[132:133], v[148:149], v[236:237]
	v_pk_fma_f32 v[134:135], v[134:135], v[150:151], v[238:239]
	v_fmac_f32_e32 v210, v132, v132
	v_fmac_f32_e32 v210, v133, v133
	v_fmac_f32_e32 v210, v134, v134
	v_fmac_f32_e32 v210, v135, v135
	v_pk_fma_f32 v[128:129], v[128:129], v[156:157], v[240:241]
	v_pk_fma_f32 v[130:131], v[130:131], v[158:159], v[242:243]
	v_fmac_f32_e32 v210, v128, v128
	v_fmac_f32_e32 v210, v129, v129
	v_fmac_f32_e32 v210, v130, v130
	v_fmac_f32_e32 v210, v131, v131
	s_cmp_lg_u64 s[0:1], 0
	s_cbranch_scc1 .Lnoap_D_1
	v_pk_mul_f32 v[228:229], v[64:65], v[140:141]
	v_pk_mul_f32 v[230:231], v[66:67], v[142:143]
	v_pk_mul_f32 v[232:233], v[72:73], v[136:137]
	v_pk_mul_f32 v[234:235], v[74:75], v[138:139]
	v_pk_mul_f32 v[236:237], v[68:69], v[132:133]
	v_pk_mul_f32 v[238:239], v[70:71], v[134:135]
	v_pk_mul_f32 v[240:241], v[76:77], v[128:129]
	v_pk_mul_f32 v[242:243], v[78:79], v[130:131]
	v_cvt_pk_bf16_f32 v228, v228, v229
	v_cvt_pk_bf16_f32 v229, v230, v231
	v_cvt_pk_bf16_f32 v230, v232, v233
	v_cvt_pk_bf16_f32 v231, v234, v235
	global_store_dwordx4 v208, v[228:231], s[28:29] sc1
	v_cvt_pk_bf16_f32 v236, v236, v237
	v_cvt_pk_bf16_f32 v237, v238, v239
	v_cvt_pk_bf16_f32 v238, v240, v241
	v_cvt_pk_bf16_f32 v239, v242, v243
	global_store_dwordx4 v208, v[236:239], s[28:29] offset:256 sc1
.Lnoap_D_1:
	ds_bpermute_b32 v211, v214, v210
	v_permlane16_swap_b32_e32 v140, v136
	v_permlane16_swap_b32_e32 v141, v137
	v_permlane16_swap_b32_e32 v142, v138
	v_permlane16_swap_b32_e32 v143, v139
	v_permlane16_swap_b32_e32 v132, v128
	v_permlane16_swap_b32_e32 v133, v129
	v_permlane16_swap_b32_e32 v134, v130
	v_permlane16_swap_b32_e32 v135, v131
	v_permlane32_swap_b32_e32 v140, v136
	v_permlane32_swap_b32_e32 v141, v137
	v_permlane32_swap_b32_e32 v142, v138
	v_permlane32_swap_b32_e32 v143, v139
	v_permlane32_swap_b32_e32 v132, v128
	v_permlane32_swap_b32_e32 v133, v129
	v_permlane32_swap_b32_e32 v134, v130
	v_permlane32_swap_b32_e32 v135, v131
	global_store_dwordx4 v207, v[140:143], s[84:85] sc1
	global_store_dwordx4 v207, v[136:139], s[84:85] offset:64 sc1
	global_store_dwordx4 v207, v[132:135], s[84:85] offset:512 sc1
	global_store_dwordx4 v207, v[128:131], s[84:85] offset:576 sc1
	v_add_u32_e32 v207, 0x10000, v207
	global_load_dwordx4 v[232:235], v206, s[70:71] offset:64
	global_load_dwordx4 v[240:243], v206, s[70:71] offset:576
	global_load_dwordx4 v[228:231], v206, s[70:71]
	global_load_dwordx4 v[236:239], v206, s[70:71] offset:512
	s_waitcnt lgkmcnt(0)
	v_add_f32_e32 v211, v210, v211
	ds_bpermute_b32 v212, v215, v211
	v_add_u32_e32 v208, 0x8000, v208
	s_waitcnt lgkmcnt(0)
	v_add_f32_e32 v211, v211, v212
	s_mov_b64 exec, 0xffff
	global_store_dword v209, v211, s[72:73] sc1
	s_mov_b64 exec, -1
	v_add_u32_e32 v209, 0x400, v209
	s_waitcnt vmcnt(9)
	v_permlane32_swap_b32_e32 v244, v248
	v_permlane32_swap_b32_e32 v245, v249
	v_permlane32_swap_b32_e32 v246, v250
	v_permlane32_swap_b32_e32 v247, v251
	v_permlane32_swap_b32_e32 v216, v220
	v_permlane32_swap_b32_e32 v217, v221
	v_permlane32_swap_b32_e32 v218, v222
	v_permlane32_swap_b32_e32 v219, v223
	v_permlane16_swap_b32_e32 v244, v248
	v_permlane16_swap_b32_e32 v245, v249
	v_permlane16_swap_b32_e32 v246, v250
	v_permlane16_swap_b32_e32 v247, v251
	v_permlane16_swap_b32_e32 v216, v220
	v_permlane16_swap_b32_e32 v217, v221
	v_permlane16_swap_b32_e32 v218, v222
	v_permlane16_swap_b32_e32 v219, v223
	v_pk_fma_f32 v[124:125], v[124:125], v[144:145], v[244:245]
	v_pk_fma_f32 v[126:127], v[126:127], v[146:147], v[246:247]
	v_mul_f32_e32 v210, v125, v125
	v_fmac_f32_e32 v210, v124, v124
	v_fmac_f32_e32 v210, v126, v126
	v_fmac_f32_e32 v210, v127, v127
	v_pk_fma_f32 v[120:121], v[120:121], v[152:153], v[248:249]
	v_pk_fma_f32 v[122:123], v[122:123], v[154:155], v[250:251]
	v_fmac_f32_e32 v210, v120, v120
	v_fmac_f32_e32 v210, v121, v121
	v_fmac_f32_e32 v210, v122, v122
	v_fmac_f32_e32 v210, v123, v123
	v_pk_fma_f32 v[116:117], v[116:117], v[148:149], v[216:217]
	v_pk_fma_f32 v[118:119], v[118:119], v[150:151], v[218:219]
	v_fmac_f32_e32 v210, v116, v116
	v_fmac_f32_e32 v210, v117, v117
	v_fmac_f32_e32 v210, v118, v118
	v_fmac_f32_e32 v210, v119, v119
	v_pk_fma_f32 v[112:113], v[112:113], v[156:157], v[220:221]
	v_pk_fma_f32 v[114:115], v[114:115], v[158:159], v[222:223]
	v_fmac_f32_e32 v210, v112, v112
	v_fmac_f32_e32 v210, v113, v113
	v_fmac_f32_e32 v210, v114, v114
	v_fmac_f32_e32 v210, v115, v115
	s_cmp_lg_u64 s[0:1], 0
	s_cbranch_scc1 .Lnoap_D_2
; DI u32x4 pack8(const float* v) { u32x4 w; w.x = pk2(v[0], v[1]); w.y = pk2(v[2], v[3]); w.z = pk2(v[4], v[5]); w.w = pk2(v[6], v[7]); return w; }
; #define xor16_32(s) xor16_32_l((s), fr + 16 * fq)
;     DI void operator()(AccRef acc, const Unit& u, int wr, int wc, int fr, int fq) const {
;     ...
;             for (int m = 0; m < 4; ++m) {
;                 const int row = rb + 16 * m;
;                 const float* xi = row < MP ? xin_p + (size_t)row * 1024 : xin_s + (size_t)(row - MP) * 1024;
;                 float s = 0.f;
; #pragma unroll
;                 for (int bj = 0; bj < 2; ++bj) {
;                     const int c = u.pn * 256 + bj * 128 + cl;
;                     float v[8];
; #pragma unroll
;                     for (int n = 0; n < 2; ++n) {
;                         const f32x4 x = *(const f32x4*)(xi + c + 4 * n);
;                         const f32x4 y = x + gt[bj][n] * acc[ai][bj][m][n];
;                         *(f32x4*)(xout + (size_t)row * 1024 + c + 4 * n) = y;
; #pragma unroll
;                         for (int j = 0; j < 4; ++j) { s += y[j] * y[j]; v[4 * n + j] = ap ? y[j] * gs[bj][n][j] : 0.f; }
;                     }
;                     if (ap) *(u32x4*)(ap + (size_t)row * 1024 + c) = pack8(v);
;                 }
;                 s = xor16_32(s);
;                 if (fq == 0) ssq[(size_t)row * 16 + u.pn * 4 + wc] = s;
	v_pk_mul_f32 v[244:245], v[64:65], v[124:125]
	v_pk_mul_f32 v[246:247], v[66:67], v[126:127]
	v_pk_mul_f32 v[248:249], v[72:73], v[120:121]
	v_pk_mul_f32 v[250:251], v[74:75], v[122:123]
	v_pk_mul_f32 v[216:217], v[68:69], v[116:117]
	v_pk_mul_f32 v[218:219], v[70:71], v[118:119]
	v_pk_mul_f32 v[220:221], v[76:77], v[112:113]
	v_pk_mul_f32 v[222:223], v[78:79], v[114:115]
	v_cvt_pk_bf16_f32 v244, v244, v245
	v_cvt_pk_bf16_f32 v245, v246, v247
	v_cvt_pk_bf16_f32 v246, v248, v249
	v_cvt_pk_bf16_f32 v247, v250, v251
	global_store_dwordx4 v208, v[244:247], s[28:29] sc1
	v_cvt_pk_bf16_f32 v216, v216, v217
	v_cvt_pk_bf16_f32 v217, v218, v219
	v_cvt_pk_bf16_f32 v218, v220, v221
	v_cvt_pk_bf16_f32 v219, v222, v223
	global_store_dwordx4 v208, v[216:219], s[28:29] offset:256 sc1
.Lnoap_D_2:
	ds_bpermute_b32 v211, v214, v210
	v_permlane16_swap_b32_e32 v124, v120
	v_permlane16_swap_b32_e32 v125, v121
	v_permlane16_swap_b32_e32 v126, v122
	v_permlane16_swap_b32_e32 v127, v123
	v_permlane16_swap_b32_e32 v116, v112
	v_permlane16_swap_b32_e32 v117, v113
	v_permlane16_swap_b32_e32 v118, v114
	v_permlane16_swap_b32_e32 v119, v115
	v_permlane32_swap_b32_e32 v124, v120
	v_permlane32_swap_b32_e32 v125, v121
	v_permlane32_swap_b32_e32 v126, v122
	v_permlane32_swap_b32_e32 v127, v123
	v_permlane32_swap_b32_e32 v116, v112
	v_permlane32_swap_b32_e32 v117, v113
	v_permlane32_swap_b32_e32 v118, v114
	v_permlane32_swap_b32_e32 v119, v115
	global_store_dwordx4 v207, v[124:127], s[84:85] sc1
	global_store_dwordx4 v207, v[120:123], s[84:85] offset:64 sc1
	global_store_dwordx4 v207, v[116:119], s[84:85] offset:512 sc1
	global_store_dwordx4 v207, v[112:115], s[84:85] offset:576 sc1
	v_add_u32_e32 v207, 0x10000, v207
	v_add_u32_e32 v206, 0x10000, v206
	global_load_dwordx4 v[248:251], v206, s[70:71] offset:64
	global_load_dwordx4 v[220:223], v206, s[70:71] offset:576
	global_load_dwordx4 v[244:247], v206, s[70:71]
	global_load_dwordx4 v[216:219], v206, s[70:71] offset:512
	s_waitcnt lgkmcnt(0)
	v_add_f32_e32 v211, v210, v211
	ds_bpermute_b32 v212, v215, v211
	v_add_u32_e32 v208, 0x8000, v208
	s_waitcnt lgkmcnt(0)
	v_add_f32_e32 v211, v211, v212
	s_mov_b64 exec, 0xffff
	global_store_dword v209, v211, s[72:73] sc1
	s_mov_b64 exec, -1
	v_add_u32_e32 v209, 0x400, v209
	s_waitcnt vmcnt(10)
	v_permlane32_swap_b32_e32 v228, v232
	v_permlane32_swap_b32_e32 v229, v233
	v_permlane32_swap_b32_e32 v230, v234
	v_permlane32_swap_b32_e32 v231, v235
	v_permlane32_swap_b32_e32 v236, v240
	v_permlane32_swap_b32_e32 v237, v241
	v_permlane32_swap_b32_e32 v238, v242
	v_permlane32_swap_b32_e32 v239, v243
	v_permlane16_swap_b32_e32 v228, v232
	v_permlane16_swap_b32_e32 v229, v233
	v_permlane16_swap_b32_e32 v230, v234
	v_permlane16_swap_b32_e32 v231, v235
	v_permlane16_swap_b32_e32 v236, v240
	v_permlane16_swap_b32_e32 v237, v241
	v_permlane16_swap_b32_e32 v238, v242
	v_permlane16_swap_b32_e32 v239, v243
	v_pk_fma_f32 v[108:109], v[108:109], v[144:145], v[228:229]
	v_pk_fma_f32 v[110:111], v[110:111], v[146:147], v[230:231]
	v_mul_f32_e32 v210, v109, v109
	v_fmac_f32_e32 v210, v108, v108
	v_fmac_f32_e32 v210, v110, v110
	v_fmac_f32_e32 v210, v111, v111
	v_pk_fma_f32 v[104:105], v[104:105], v[152:153], v[232:233]
	v_pk_fma_f32 v[106:107], v[106:107], v[154:155], v[234:235]
	v_fmac_f32_e32 v210, v104, v104
	v_fmac_f32_e32 v210, v105, v105
	v_fmac_f32_e32 v210, v106, v106
	v_fmac_f32_e32 v210, v107, v107
	v_pk_fma_f32 v[100:101], v[100:101], v[148:149], v[236:237]
	v_pk_fma_f32 v[102:103], v[102:103], v[150:151], v[238:239]
	v_fmac_f32_e32 v210, v100, v100
	v_fmac_f32_e32 v210, v101, v101
	v_fmac_f32_e32 v210, v102, v102
	v_fmac_f32_e32 v210, v103, v103
	v_pk_fma_f32 v[96:97], v[96:97], v[156:157], v[240:241]
	v_pk_fma_f32 v[98:99], v[98:99], v[158:159], v[242:243]
	v_fmac_f32_e32 v210, v96, v96
	v_fmac_f32_e32 v210, v97, v97
	v_fmac_f32_e32 v210, v98, v98
	v_fmac_f32_e32 v210, v99, v99
	s_cmp_lg_u64 s[0:1], 0
	s_cbranch_scc1 .Lnoap_D_3
	v_pk_mul_f32 v[228:229], v[64:65], v[108:109]
	v_pk_mul_f32 v[230:231], v[66:67], v[110:111]
	v_pk_mul_f32 v[232:233], v[72:73], v[104:105]
	v_pk_mul_f32 v[234:235], v[74:75], v[106:107]
	v_pk_mul_f32 v[236:237], v[68:69], v[100:101]
	v_pk_mul_f32 v[238:239], v[70:71], v[102:103]
	v_pk_mul_f32 v[240:241], v[76:77], v[96:97]
	v_pk_mul_f32 v[242:243], v[78:79], v[98:99]
	v_cvt_pk_bf16_f32 v228, v228, v229
	v_cvt_pk_bf16_f32 v229, v230, v231
	v_cvt_pk_bf16_f32 v230, v232, v233
	v_cvt_pk_bf16_f32 v231, v234, v235
	global_store_dwordx4 v208, v[228:231], s[28:29] sc1
	v_cvt_pk_bf16_f32 v236, v236, v237
	v_cvt_pk_bf16_f32 v237, v238, v239
	v_cvt_pk_bf16_f32 v238, v240, v241
	v_cvt_pk_bf16_f32 v239, v242, v243
	global_store_dwordx4 v208, v[236:239], s[28:29] offset:256 sc1
; DI u32x4 pack8(const float* v) { u32x4 w; w.x = pk2(v[0], v[1]); w.y = pk2(v[2], v[3]); w.z = pk2(v[4], v[5]); w.w = pk2(v[6], v[7]); return w; }
; #define xor16_32(s) xor16_32_l((s), fr + 16 * fq)
;     DI void operator()(AccRef acc, const Unit& u, int wr, int wc, int fr, int fq) const {
;     ...
;         for (int ai = 0; ai < 2; ++ai) {
;             const int rb = u.pm * 256 + ai * 128 + wr * 64 + fr;
;             int mb, pos0, kv0; row_info(rb, mb, pos0, kv0);
;             f32x4 gt[2][2], gs[2][2];
; #pragma unroll
;             for (int bj = 0; bj < 2; ++bj)
; #pragma unroll
;                 for (int n = 0; n < 2; ++n) {
;                     const int c = u.pn * 256 + bj * 128 + cl + 4 * n;
;                     gt[bj][n] = *(const f32x4*)(gate + (size_t)mb * 6144 + c);
;                     if (ap) { const f32x4 g = *(const f32x4*)(gn + c), s = *(const f32x4*)(scn + (size_t)mb * 6144 + c); gs[bj][n] = g * (s + 1.f); }
;                 }
;     ...
;             for (int m = 0; m < 4; ++m) {
;                 const int row = rb + 16 * m;
;                 const float* xi = row < MP ? xin_p + (size_t)row * 1024 : xin_s + (size_t)(row - MP) * 1024;
;                 float s = 0.f;
; #pragma unroll
;                 for (int bj = 0; bj < 2; ++bj) {
;                     const int c = u.pn * 256 + bj * 128 + cl;
;                     float v[8];
; #pragma unroll
;                     for (int n = 0; n < 2; ++n) {
;                         const f32x4 x = *(const f32x4*)(xi + c + 4 * n);
;                         const f32x4 y = x + gt[bj][n] * acc[ai][bj][m][n];
;                         *(f32x4*)(xout + (size_t)row * 1024 + c + 4 * n) = y;
; #pragma unroll
;                         for (int j = 0; j < 4; ++j) { s += y[j] * y[j]; v[4 * n + j] = ap ? y[j] * gs[bj][n][j] : 0.f; }
;                     }
;                     if (ap) *(u32x4*)(ap + (size_t)row * 1024 + c) = pack8(v);
;                 }
;                 s = xor16_32(s);
;                 if (fq == 0) ssq[(size_t)row * 16 + u.pn * 4 + wc] = s;
.Lnoap_D_3:
	ds_bpermute_b32 v211, v214, v210
	v_permlane16_swap_b32_e32 v108, v104
	v_permlane16_swap_b32_e32 v109, v105
	v_permlane16_swap_b32_e32 v110, v106
	v_permlane16_swap_b32_e32 v111, v107
	v_permlane16_swap_b32_e32 v100, v96
	v_permlane16_swap_b32_e32 v101, v97
	v_permlane16_swap_b32_e32 v102, v98
	v_permlane16_swap_b32_e32 v103, v99
	v_permlane32_swap_b32_e32 v108, v104
	v_permlane32_swap_b32_e32 v109, v105
	v_permlane32_swap_b32_e32 v110, v106
	v_permlane32_swap_b32_e32 v111, v107
	v_permlane32_swap_b32_e32 v100, v96
	v_permlane32_swap_b32_e32 v101, v97
	v_permlane32_swap_b32_e32 v102, v98
	v_permlane32_swap_b32_e32 v103, v99
	global_store_dwordx4 v207, v[108:111], s[84:85] sc1
	global_store_dwordx4 v207, v[104:107], s[84:85] offset:64 sc1
	global_store_dwordx4 v207, v[100:103], s[84:85] offset:512 sc1
	global_store_dwordx4 v207, v[96:99], s[84:85] offset:576 sc1
	v_add_u32_e32 v207, 0x10000, v207
	v_add_u32_e32 v206, 0x50000, v206
	global_load_dwordx4 v[232:235], v206, s[70:71] offset:64
	global_load_dwordx4 v[240:243], v206, s[70:71] offset:576
	global_load_dwordx4 v[228:231], v206, s[70:71]
	global_load_dwordx4 v[236:239], v206, s[70:71] offset:512
	s_waitcnt lgkmcnt(0)
	v_add_f32_e32 v211, v210, v211
	ds_bpermute_b32 v212, v215, v211
	v_add_u32_e32 v208, 0x8000, v208
	s_waitcnt lgkmcnt(0)
	v_add_f32_e32 v211, v211, v212
	s_mov_b64 exec, 0xffff
	global_store_dword v209, v211, s[72:73] sc1
	s_mov_b64 exec, -1
	v_add_u32_e32 v209, 0x400, v209
	s_waitcnt vmcnt(10)
	v_permlane32_swap_b32_e32 v244, v248
	v_permlane32_swap_b32_e32 v245, v249
	v_permlane32_swap_b32_e32 v246, v250
	v_permlane32_swap_b32_e32 v247, v251
	v_permlane32_swap_b32_e32 v216, v220
	v_permlane32_swap_b32_e32 v217, v221
	v_permlane32_swap_b32_e32 v218, v222
	v_permlane32_swap_b32_e32 v219, v223
	v_permlane16_swap_b32_e32 v244, v248
	v_permlane16_swap_b32_e32 v245, v249
	v_permlane16_swap_b32_e32 v246, v250
	v_permlane16_swap_b32_e32 v247, v251
	v_permlane16_swap_b32_e32 v216, v220
	v_permlane16_swap_b32_e32 v217, v221
	v_permlane16_swap_b32_e32 v218, v222
	v_permlane16_swap_b32_e32 v219, v223
	v_pk_fma_f32 v[92:93], v[92:93], v[144:145], v[244:245]
	v_pk_fma_f32 v[94:95], v[94:95], v[146:147], v[246:247]
	v_mul_f32_e32 v210, v93, v93
	v_fmac_f32_e32 v210, v92, v92
	v_fmac_f32_e32 v210, v94, v94
	v_fmac_f32_e32 v210, v95, v95
	v_pk_fma_f32 v[88:89], v[88:89], v[152:153], v[248:249]
	v_pk_fma_f32 v[90:91], v[90:91], v[154:155], v[250:251]
	v_fmac_f32_e32 v210, v88, v88
	v_fmac_f32_e32 v210, v89, v89
	v_fmac_f32_e32 v210, v90, v90
	v_fmac_f32_e32 v210, v91, v91
	v_pk_fma_f32 v[84:85], v[84:85], v[148:149], v[216:217]
	v_pk_fma_f32 v[86:87], v[86:87], v[150:151], v[218:219]
	v_fmac_f32_e32 v210, v84, v84
	v_fmac_f32_e32 v210, v85, v85
	v_fmac_f32_e32 v210, v86, v86
	v_fmac_f32_e32 v210, v87, v87
	v_pk_fma_f32 v[80:81], v[80:81], v[156:157], v[220:221]
	v_pk_fma_f32 v[82:83], v[82:83], v[158:159], v[222:223]
	v_fmac_f32_e32 v210, v80, v80
	v_fmac_f32_e32 v210, v81, v81
	v_fmac_f32_e32 v210, v82, v82
	v_fmac_f32_e32 v210, v83, v83
	s_cmp_lg_u64 s[0:1], 0
	s_cbranch_scc1 .Lnoap_D_4
	v_pk_mul_f32 v[244:245], v[64:65], v[92:93]
	v_pk_mul_f32 v[246:247], v[66:67], v[94:95]
	v_pk_mul_f32 v[248:249], v[72:73], v[88:89]
	v_pk_mul_f32 v[250:251], v[74:75], v[90:91]
	v_pk_mul_f32 v[216:217], v[68:69], v[84:85]
	v_pk_mul_f32 v[218:219], v[70:71], v[86:87]
	v_pk_mul_f32 v[220:221], v[76:77], v[80:81]
	v_pk_mul_f32 v[222:223], v[78:79], v[82:83]
	v_cvt_pk_bf16_f32 v244, v244, v245
	v_cvt_pk_bf16_f32 v245, v246, v247
	v_cvt_pk_bf16_f32 v246, v248, v249
	v_cvt_pk_bf16_f32 v247, v250, v251
	global_store_dwordx4 v208, v[244:247], s[28:29] sc1
	v_cvt_pk_bf16_f32 v216, v216, v217
	v_cvt_pk_bf16_f32 v217, v218, v219
	v_cvt_pk_bf16_f32 v218, v220, v221
	v_cvt_pk_bf16_f32 v219, v222, v223
	global_store_dwordx4 v208, v[216:219], s[28:29] offset:256 sc1
.Lnoap_D_4:
	ds_bpermute_b32 v211, v214, v210
	v_permlane16_swap_b32_e32 v92, v88
	v_permlane16_swap_b32_e32 v93, v89
	v_permlane16_swap_b32_e32 v94, v90
	v_permlane16_swap_b32_e32 v95, v91
	v_permlane16_swap_b32_e32 v84, v80
	v_permlane16_swap_b32_e32 v85, v81
	v_permlane16_swap_b32_e32 v86, v82
	v_permlane16_swap_b32_e32 v87, v83
	v_permlane32_swap_b32_e32 v92, v88
	v_permlane32_swap_b32_e32 v93, v89
	v_permlane32_swap_b32_e32 v94, v90
	v_permlane32_swap_b32_e32 v95, v91
	v_permlane32_swap_b32_e32 v84, v80
	v_permlane32_swap_b32_e32 v85, v81
	v_permlane32_swap_b32_e32 v86, v82
	v_permlane32_swap_b32_e32 v87, v83
	global_store_dwordx4 v207, v[92:95], s[84:85] sc1
	global_store_dwordx4 v207, v[88:91], s[84:85] offset:64 sc1
	global_store_dwordx4 v207, v[84:87], s[84:85] offset:512 sc1
	global_store_dwordx4 v207, v[80:83], s[84:85] offset:576 sc1
	v_add_u32_e32 v207, 0x50000, v207
	v_add_u32_e32 v206, 0x10000, v206
	global_load_dwordx4 v[248:251], v206, s[70:71] offset:64
	global_load_dwordx4 v[220:223], v206, s[70:71] offset:576
	global_load_dwordx4 v[244:247], v206, s[70:71]
	global_load_dwordx4 v[216:219], v206, s[70:71] offset:512
	s_waitcnt lgkmcnt(0)
	v_add_f32_e32 v211, v210, v211
	ds_bpermute_b32 v212, v215, v211
	v_add_u32_e32 v208, 0x28000, v208
	s_waitcnt lgkmcnt(0)
	v_add_f32_e32 v211, v211, v212
	s_mov_b64 exec, 0xffff
	global_store_dword v209, v211, s[72:73] sc1
	s_mov_b64 exec, -1
	v_add_u32_e32 v209, 0x1400, v209
	v_add_u32_e32 v224, 0xffffc080, v176
	v_add_u32_e32 v96, 0x80, v176
	s_waitcnt lgkmcnt(0)
	v_lshrrev_b32_e32 v81, 6, v224
	v_cmp_gt_i32_e32 vcc, s94, v96
	v_ashrrev_i32_e32 v80, 11, v96
	v_add_u32_e32 v81, 8, v81
	v_cndmask_b32_e32 v84, v81, v80, vcc
	v_mov_b64_e32 v[80:81], s[18:19]
	v_mad_i64_i32 v[80:81], s[12:13], v84, s75, v[80:81]
	v_mov_b64_e32 v[82:83], s[26:27]
	v_lshl_add_u64 v[92:93], v[172:173], 2, v[80:81]
	v_mad_i64_i32 v[84:85], s[12:13], v84, s75, v[82:83]
	global_load_dwordx4 v[80:83], v[92:93], off
	s_movk_i32 s6, 0x3fff
	v_cmp_lt_i32_e64 s[6:7], s6, v96
	s_and_b64 vcc, exec, s[0:1]
	s_cbranch_vccnz .LBB0_2101
	v_lshl_add_u64 v[64:65], v[84:85], 0, v[174:175]
	global_load_dwordx4 v[64:67], v[64:65], off
	s_nop 0
	global_load_dwordx4 v[86:89], v[178:179], off
	s_waitcnt vmcnt(1)
	v_pk_add_f32 v[66:67], v[66:67], 1.0 op_sel_hi:[1,0]
	v_pk_add_f32 v[64:65], v[64:65], 1.0 op_sel_hi:[1,0]
	s_waitcnt vmcnt(0)
	v_pk_mul_f32 v[66:67], v[88:89], v[66:67]
	v_pk_mul_f32 v[64:65], v[86:87], v[64:65]
	global_load_dwordx4 v[88:91], v[92:93], off offset:16
	s_and_b64 vcc, exec, s[0:1]
	v_lshl_add_u64 v[98:99], v[172:173], 2, v[84:85]
	s_cbranch_vccz .LBB0_2102

; DI u32x4 pack8(const float* v) { u32x4 w; w.x = pk2(v[0], v[1]); w.y = pk2(v[2], v[3]); w.z = pk2(v[4], v[5]); w.w = pk2(v[6], v[7]); return w; }
; #define xor16_32(s) xor16_32_l((s), fr + 16 * fq)
;     DI void operator()(AccRef acc, const Unit& u, int wr, int wc, int fr, int fq) const {
;     ...
;             for (int m = 0; m < 4; ++m) {
;                 const int row = rb + 16 * m;
;                 const float* xi = row < MP ? xin_p + (size_t)row * 1024 : xin_s + (size_t)(row - MP) * 1024;
;                 float s = 0.f;
; #pragma unroll
;                 for (int bj = 0; bj < 2; ++bj) {
;                     const int c = u.pn * 256 + bj * 128 + cl;
;                     float v[8];
; #pragma unroll
;                     for (int n = 0; n < 2; ++n) {
;                         const f32x4 x = *(const f32x4*)(xi + c + 4 * n);
;                         const f32x4 y = x + gt[bj][n] * acc[ai][bj][m][n];
;                         *(f32x4*)(xout + (size_t)row * 1024 + c + 4 * n) = y;
; #pragma unroll
;                         for (int j = 0; j < 4; ++j) { s += y[j] * y[j]; v[4 * n + j] = ap ? y[j] * gs[bj][n][j] : 0.f; }
;                     }
;                     if (ap) *(u32x4*)(ap + (size_t)row * 1024 + c) = pack8(v);
;                 }
;                 s = xor16_32(s);
;                 if (fq == 0) ssq[(size_t)row * 16 + u.pn * 4 + wc] = s;
.LBB0_2109:
	s_or_b64 exec, exec, s[6:7]
	s_waitcnt vmcnt(0)
	v_permlane32_swap_b32_e32 v228, v232
	v_permlane32_swap_b32_e32 v229, v233
	v_permlane32_swap_b32_e32 v230, v234
	v_permlane32_swap_b32_e32 v231, v235
	v_permlane32_swap_b32_e32 v236, v240
	v_permlane32_swap_b32_e32 v237, v241
	v_permlane32_swap_b32_e32 v238, v242
	v_permlane32_swap_b32_e32 v239, v243
	v_permlane16_swap_b32_e32 v228, v232
	v_permlane16_swap_b32_e32 v229, v233
	v_permlane16_swap_b32_e32 v230, v234
	v_permlane16_swap_b32_e32 v231, v235
	v_permlane16_swap_b32_e32 v236, v240
	v_permlane16_swap_b32_e32 v237, v241
	v_permlane16_swap_b32_e32 v238, v242
	v_permlane16_swap_b32_e32 v239, v243
	v_pk_fma_f32 v[60:61], v[60:61], v[80:81], v[228:229]
	v_pk_fma_f32 v[62:63], v[62:63], v[82:83], v[230:231]
	v_mul_f32_e32 v210, v61, v61
	v_fmac_f32_e32 v210, v60, v60
	v_fmac_f32_e32 v210, v62, v62
	v_fmac_f32_e32 v210, v63, v63
	v_pk_fma_f32 v[56:57], v[56:57], v[88:89], v[232:233]
	v_pk_fma_f32 v[58:59], v[58:59], v[90:91], v[234:235]
	v_fmac_f32_e32 v210, v56, v56
	v_fmac_f32_e32 v210, v57, v57
	v_fmac_f32_e32 v210, v58, v58
	v_fmac_f32_e32 v210, v59, v59
	v_pk_fma_f32 v[52:53], v[52:53], v[84:85], v[236:237]
	v_pk_fma_f32 v[54:55], v[54:55], v[86:87], v[238:239]
	v_fmac_f32_e32 v210, v52, v52
	v_fmac_f32_e32 v210, v53, v53
	v_fmac_f32_e32 v210, v54, v54
	v_fmac_f32_e32 v210, v55, v55
	v_pk_fma_f32 v[48:49], v[48:49], v[92:93], v[240:241]
	v_pk_fma_f32 v[50:51], v[50:51], v[94:95], v[242:243]
	v_fmac_f32_e32 v210, v48, v48
	v_fmac_f32_e32 v210, v49, v49
	v_fmac_f32_e32 v210, v50, v50
	v_fmac_f32_e32 v210, v51, v51
	s_cmp_lg_u64 s[0:1], 0
	s_cbranch_scc1 .Lnoap_D_5
	v_pk_mul_f32 v[228:229], v[64:65], v[60:61]
	v_pk_mul_f32 v[230:231], v[66:67], v[62:63]
	v_pk_mul_f32 v[232:233], v[72:73], v[56:57]
	v_pk_mul_f32 v[234:235], v[74:75], v[58:59]
	v_pk_mul_f32 v[236:237], v[68:69], v[52:53]
	v_pk_mul_f32 v[238:239], v[70:71], v[54:55]
	v_pk_mul_f32 v[240:241], v[76:77], v[48:49]
	v_pk_mul_f32 v[242:243], v[78:79], v[50:51]
	v_cvt_pk_bf16_f32 v228, v228, v229
	v_cvt_pk_bf16_f32 v229, v230, v231
	v_cvt_pk_bf16_f32 v230, v232, v233
	v_cvt_pk_bf16_f32 v231, v234, v235
	global_store_dwordx4 v208, v[228:231], s[28:29] sc1
	v_cvt_pk_bf16_f32 v236, v236, v237
	v_cvt_pk_bf16_f32 v237, v238, v239
	v_cvt_pk_bf16_f32 v238, v240, v241
	v_cvt_pk_bf16_f32 v239, v242, v243
	global_store_dwordx4 v208, v[236:239], s[28:29] offset:256 sc1
.Lnoap_D_5:
	ds_bpermute_b32 v211, v214, v210
	v_permlane16_swap_b32_e32 v60, v56
	v_permlane16_swap_b32_e32 v61, v57
	v_permlane16_swap_b32_e32 v62, v58
	v_permlane16_swap_b32_e32 v63, v59
	v_permlane16_swap_b32_e32 v52, v48
	v_permlane16_swap_b32_e32 v53, v49
	v_permlane16_swap_b32_e32 v54, v50
	v_permlane16_swap_b32_e32 v55, v51
	v_permlane32_swap_b32_e32 v60, v56
	v_permlane32_swap_b32_e32 v61, v57
	v_permlane32_swap_b32_e32 v62, v58
	v_permlane32_swap_b32_e32 v63, v59
	v_permlane32_swap_b32_e32 v52, v48
	v_permlane32_swap_b32_e32 v53, v49
	v_permlane32_swap_b32_e32 v54, v50
	v_permlane32_swap_b32_e32 v55, v51
	global_store_dwordx4 v207, v[60:63], s[84:85] sc1
	global_store_dwordx4 v207, v[56:59], s[84:85] offset:64 sc1
	global_store_dwordx4 v207, v[52:55], s[84:85] offset:512 sc1
	global_store_dwordx4 v207, v[48:51], s[84:85] offset:576 sc1
	v_add_u32_e32 v207, 0x10000, v207
	v_add_u32_e32 v206, 0x10000, v206
	global_load_dwordx4 v[232:235], v206, s[70:71] offset:64
	global_load_dwordx4 v[240:243], v206, s[70:71] offset:576
	global_load_dwordx4 v[228:231], v206, s[70:71]
	global_load_dwordx4 v[236:239], v206, s[70:71] offset:512
	s_waitcnt lgkmcnt(0)
	v_add_f32_e32 v211, v210, v211
	ds_bpermute_b32 v212, v215, v211
	v_add_u32_e32 v208, 0x8000, v208
	s_waitcnt lgkmcnt(0)
	v_add_f32_e32 v211, v211, v212
	s_mov_b64 exec, 0xffff
	global_store_dword v209, v211, s[72:73] sc1
	s_mov_b64 exec, -1
	v_add_u32_e32 v209, 0x400, v209
	v_permlane32_swap_b32_e32 v244, v248
	v_permlane32_swap_b32_e32 v245, v249
	v_permlane32_swap_b32_e32 v246, v250
	v_permlane32_swap_b32_e32 v247, v251
	v_permlane32_swap_b32_e32 v216, v220
	v_permlane32_swap_b32_e32 v217, v221
	v_permlane32_swap_b32_e32 v218, v222
	v_permlane32_swap_b32_e32 v219, v223
	v_permlane16_swap_b32_e32 v244, v248
	v_permlane16_swap_b32_e32 v245, v249
	v_permlane16_swap_b32_e32 v246, v250
	v_permlane16_swap_b32_e32 v247, v251
	v_permlane16_swap_b32_e32 v216, v220
	v_permlane16_swap_b32_e32 v217, v221
	v_permlane16_swap_b32_e32 v218, v222
	v_permlane16_swap_b32_e32 v219, v223
	v_pk_fma_f32 v[44:45], v[44:45], v[80:81], v[244:245]
	v_pk_fma_f32 v[46:47], v[46:47], v[82:83], v[246:247]
	v_mul_f32_e32 v210, v45, v45
	v_fmac_f32_e32 v210, v44, v44
	v_fmac_f32_e32 v210, v46, v46
	v_fmac_f32_e32 v210, v47, v47
	v_pk_fma_f32 v[40:41], v[40:41], v[88:89], v[248:249]
	v_pk_fma_f32 v[42:43], v[42:43], v[90:91], v[250:251]
	v_fmac_f32_e32 v210, v40, v40
	v_fmac_f32_e32 v210, v41, v41
	v_fmac_f32_e32 v210, v42, v42
	v_fmac_f32_e32 v210, v43, v43
	v_pk_fma_f32 v[36:37], v[36:37], v[84:85], v[216:217]
	v_pk_fma_f32 v[38:39], v[38:39], v[86:87], v[218:219]
	v_fmac_f32_e32 v210, v36, v36
	v_fmac_f32_e32 v210, v37, v37
	v_fmac_f32_e32 v210, v38, v38
	v_fmac_f32_e32 v210, v39, v39
	v_pk_fma_f32 v[32:33], v[32:33], v[92:93], v[220:221]
	v_pk_fma_f32 v[34:35], v[34:35], v[94:95], v[222:223]
	v_fmac_f32_e32 v210, v32, v32
	v_fmac_f32_e32 v210, v33, v33
	v_fmac_f32_e32 v210, v34, v34
	v_fmac_f32_e32 v210, v35, v35
	s_cmp_lg_u64 s[0:1], 0
	s_cbranch_scc1 .Lnoap_D_6
	v_pk_mul_f32 v[244:245], v[64:65], v[44:45]
	v_pk_mul_f32 v[246:247], v[66:67], v[46:47]
	v_pk_mul_f32 v[248:249], v[72:73], v[40:41]
	v_pk_mul_f32 v[250:251], v[74:75], v[42:43]
	v_pk_mul_f32 v[216:217], v[68:69], v[36:37]
	v_pk_mul_f32 v[218:219], v[70:71], v[38:39]
	v_pk_mul_f32 v[220:221], v[76:77], v[32:33]
	v_pk_mul_f32 v[222:223], v[78:79], v[34:35]
	v_cvt_pk_bf16_f32 v244, v244, v245
	v_cvt_pk_bf16_f32 v245, v246, v247
	v_cvt_pk_bf16_f32 v246, v248, v249
	v_cvt_pk_bf16_f32 v247, v250, v251
	global_store_dwordx4 v208, v[244:247], s[28:29] sc1
	v_cvt_pk_bf16_f32 v216, v216, v217
	v_cvt_pk_bf16_f32 v217, v218, v219
	v_cvt_pk_bf16_f32 v218, v220, v221
	v_cvt_pk_bf16_f32 v219, v222, v223
	global_store_dwordx4 v208, v[216:219], s[28:29] offset:256 sc1
; DI u32x4 pack8(const float* v) { u32x4 w; w.x = pk2(v[0], v[1]); w.y = pk2(v[2], v[3]); w.z = pk2(v[4], v[5]); w.w = pk2(v[6], v[7]); return w; }
; #define xor16_32(s) xor16_32_l((s), fr + 16 * fq)
;     DI void operator()(AccRef acc, const Unit& u, int wr, int wc, int fr, int fq) const {
;     ...
;             for (int m = 0; m < 4; ++m) {
;                 const int row = rb + 16 * m;
;                 const float* xi = row < MP ? xin_p + (size_t)row * 1024 : xin_s + (size_t)(row - MP) * 1024;
;                 float s = 0.f;
; #pragma unroll
;                 for (int bj = 0; bj < 2; ++bj) {
;                     const int c = u.pn * 256 + bj * 128 + cl;
;                     float v[8];
; #pragma unroll
;                     for (int n = 0; n < 2; ++n) {
;                         const f32x4 x = *(const f32x4*)(xi + c + 4 * n);
;                         const f32x4 y = x + gt[bj][n] * acc[ai][bj][m][n];
;                         *(f32x4*)(xout + (size_t)row * 1024 + c + 4 * n) = y;
; #pragma unroll
;                         for (int j = 0; j < 4; ++j) { s += y[j] * y[j]; v[4 * n + j] = ap ? y[j] * gs[bj][n][j] : 0.f; }
;                     }
;                     if (ap) *(u32x4*)(ap + (size_t)row * 1024 + c) = pack8(v);
;                 }
;                 s = xor16_32(s);
;                 if (fq == 0) ssq[(size_t)row * 16 + u.pn * 4 + wc] = s;
.Lnoap_D_6:
	ds_bpermute_b32 v211, v214, v210
	v_permlane16_swap_b32_e32 v44, v40
	v_permlane16_swap_b32_e32 v45, v41
	v_permlane16_swap_b32_e32 v46, v42
	v_permlane16_swap_b32_e32 v47, v43
	v_permlane16_swap_b32_e32 v36, v32
	v_permlane16_swap_b32_e32 v37, v33
	v_permlane16_swap_b32_e32 v38, v34
	v_permlane16_swap_b32_e32 v39, v35
	v_permlane32_swap_b32_e32 v44, v40
	v_permlane32_swap_b32_e32 v45, v41
	v_permlane32_swap_b32_e32 v46, v42
	v_permlane32_swap_b32_e32 v47, v43
	v_permlane32_swap_b32_e32 v36, v32
	v_permlane32_swap_b32_e32 v37, v33
	v_permlane32_swap_b32_e32 v38, v34
	v_permlane32_swap_b32_e32 v39, v35
	global_store_dwordx4 v207, v[44:47], s[84:85] sc1
	global_store_dwordx4 v207, v[40:43], s[84:85] offset:64 sc1
	global_store_dwordx4 v207, v[36:39], s[84:85] offset:512 sc1
	global_store_dwordx4 v207, v[32:35], s[84:85] offset:576 sc1
	v_add_u32_e32 v207, 0x10000, v207
	v_add_u32_e32 v206, 0x10000, v206
	global_load_dwordx4 v[248:251], v206, s[70:71] offset:64
	global_load_dwordx4 v[220:223], v206, s[70:71] offset:576
	global_load_dwordx4 v[244:247], v206, s[70:71]
	global_load_dwordx4 v[216:219], v206, s[70:71] offset:512
	s_waitcnt lgkmcnt(0)
	v_add_f32_e32 v211, v210, v211
	ds_bpermute_b32 v212, v215, v211
	v_add_u32_e32 v208, 0x8000, v208
	s_waitcnt lgkmcnt(0)
	v_add_f32_e32 v211, v211, v212
	s_mov_b64 exec, 0xffff
	global_store_dword v209, v211, s[72:73] sc1
	s_mov_b64 exec, -1
	v_add_u32_e32 v209, 0x400, v209
	s_waitcnt vmcnt(10)
	v_permlane32_swap_b32_e32 v228, v232
	v_permlane32_swap_b32_e32 v229, v233
	v_permlane32_swap_b32_e32 v230, v234
	v_permlane32_swap_b32_e32 v231, v235
	v_permlane32_swap_b32_e32 v236, v240
	v_permlane32_swap_b32_e32 v237, v241
	v_permlane32_swap_b32_e32 v238, v242
	v_permlane32_swap_b32_e32 v239, v243
	v_permlane16_swap_b32_e32 v228, v232
	v_permlane16_swap_b32_e32 v229, v233
	v_permlane16_swap_b32_e32 v230, v234
	v_permlane16_swap_b32_e32 v231, v235
	v_permlane16_swap_b32_e32 v236, v240
	v_permlane16_swap_b32_e32 v237, v241
	v_permlane16_swap_b32_e32 v238, v242
	v_permlane16_swap_b32_e32 v239, v243
	v_pk_fma_f32 v[28:29], v[28:29], v[80:81], v[228:229]
	v_pk_fma_f32 v[30:31], v[30:31], v[82:83], v[230:231]
	v_mul_f32_e32 v210, v29, v29
	v_fmac_f32_e32 v210, v28, v28
	v_fmac_f32_e32 v210, v30, v30
	v_fmac_f32_e32 v210, v31, v31
	v_pk_fma_f32 v[24:25], v[24:25], v[88:89], v[232:233]
	v_pk_fma_f32 v[26:27], v[26:27], v[90:91], v[234:235]
	v_fmac_f32_e32 v210, v24, v24
	v_fmac_f32_e32 v210, v25, v25
	v_fmac_f32_e32 v210, v26, v26
	v_fmac_f32_e32 v210, v27, v27
	v_pk_fma_f32 v[20:21], v[20:21], v[84:85], v[236:237]
	v_pk_fma_f32 v[22:23], v[22:23], v[86:87], v[238:239]
	v_fmac_f32_e32 v210, v20, v20
	v_fmac_f32_e32 v210, v21, v21
	v_fmac_f32_e32 v210, v22, v22
	v_fmac_f32_e32 v210, v23, v23
	v_pk_fma_f32 v[16:17], v[16:17], v[92:93], v[240:241]
	v_pk_fma_f32 v[18:19], v[18:19], v[94:95], v[242:243]
	v_fmac_f32_e32 v210, v16, v16
	v_fmac_f32_e32 v210, v17, v17
	v_fmac_f32_e32 v210, v18, v18
	v_fmac_f32_e32 v210, v19, v19
	s_cmp_lg_u64 s[0:1], 0
	s_cbranch_scc1 .Lnoap_D_7
	v_pk_mul_f32 v[228:229], v[64:65], v[28:29]
	v_pk_mul_f32 v[230:231], v[66:67], v[30:31]
	v_pk_mul_f32 v[232:233], v[72:73], v[24:25]
	v_pk_mul_f32 v[234:235], v[74:75], v[26:27]
	v_pk_mul_f32 v[236:237], v[68:69], v[20:21]
	v_pk_mul_f32 v[238:239], v[70:71], v[22:23]
	v_pk_mul_f32 v[240:241], v[76:77], v[16:17]
	v_pk_mul_f32 v[242:243], v[78:79], v[18:19]
	v_cvt_pk_bf16_f32 v228, v228, v229
	v_cvt_pk_bf16_f32 v229, v230, v231
	v_cvt_pk_bf16_f32 v230, v232, v233
	v_cvt_pk_bf16_f32 v231, v234, v235
	global_store_dwordx4 v208, v[228:231], s[28:29] sc1
	v_cvt_pk_bf16_f32 v236, v236, v237
	v_cvt_pk_bf16_f32 v237, v238, v239
	v_cvt_pk_bf16_f32 v238, v240, v241
	v_cvt_pk_bf16_f32 v239, v242, v243
	global_store_dwordx4 v208, v[236:239], s[28:29] offset:256 sc1
; DI u32x4 pack8(const float* v) { u32x4 w; w.x = pk2(v[0], v[1]); w.y = pk2(v[2], v[3]); w.z = pk2(v[4], v[5]); w.w = pk2(v[6], v[7]); return w; }
; #define xor16_32(s) xor16_32_l((s), fr + 16 * fq)
;     DI void operator()(AccRef acc, const Unit& u, int wr, int wc, int fr, int fq) const {
;     ...
;             for (int m = 0; m < 4; ++m) {
;                 const int row = rb + 16 * m;
;                 const float* xi = row < MP ? xin_p + (size_t)row * 1024 : xin_s + (size_t)(row - MP) * 1024;
;                 float s = 0.f;
; #pragma unroll
;                 for (int bj = 0; bj < 2; ++bj) {
;                     const int c = u.pn * 256 + bj * 128 + cl;
;                     float v[8];
; #pragma unroll
;                     for (int n = 0; n < 2; ++n) {
;                         const f32x4 x = *(const f32x4*)(xi + c + 4 * n);
;                         const f32x4 y = x + gt[bj][n] * acc[ai][bj][m][n];
;                         *(f32x4*)(xout + (size_t)row * 1024 + c + 4 * n) = y;
; #pragma unroll
;                         for (int j = 0; j < 4; ++j) { s += y[j] * y[j]; v[4 * n + j] = ap ? y[j] * gs[bj][n][j] : 0.f; }
;                     }
;                     if (ap) *(u32x4*)(ap + (size_t)row * 1024 + c) = pack8(v);
;                 }
;                 s = xor16_32(s);
;                 if (fq == 0) ssq[(size_t)row * 16 + u.pn * 4 + wc] = s;
.Lnoap_D_7:
	ds_bpermute_b32 v211, v214, v210
	v_permlane16_swap_b32_e32 v28, v24
	v_permlane16_swap_b32_e32 v29, v25
	v_permlane16_swap_b32_e32 v30, v26
	v_permlane16_swap_b32_e32 v31, v27
	v_permlane16_swap_b32_e32 v20, v16
	v_permlane16_swap_b32_e32 v21, v17
	v_permlane16_swap_b32_e32 v22, v18
	v_permlane16_swap_b32_e32 v23, v19
	v_permlane32_swap_b32_e32 v28, v24
	v_permlane32_swap_b32_e32 v29, v25
	v_permlane32_swap_b32_e32 v30, v26
	v_permlane32_swap_b32_e32 v31, v27
	v_permlane32_swap_b32_e32 v20, v16
	v_permlane32_swap_b32_e32 v21, v17
	v_permlane32_swap_b32_e32 v22, v18
	v_permlane32_swap_b32_e32 v23, v19
	global_store_dwordx4 v207, v[28:31], s[84:85] sc1
	global_store_dwordx4 v207, v[24:27], s[84:85] offset:64 sc1
	global_store_dwordx4 v207, v[20:23], s[84:85] offset:512 sc1
	global_store_dwordx4 v207, v[16:19], s[84:85] offset:576 sc1
	v_add_u32_e32 v207, 0x10000, v207
	s_waitcnt lgkmcnt(0)
	v_add_f32_e32 v211, v210, v211
	ds_bpermute_b32 v212, v215, v211
	v_add_u32_e32 v208, 0x8000, v208
	s_waitcnt lgkmcnt(0)
	v_add_f32_e32 v211, v211, v212
	s_mov_b64 exec, 0xffff
	global_store_dword v209, v211, s[72:73] sc1
	s_mov_b64 exec, -1
	v_add_u32_e32 v209, 0x400, v209
	s_waitcnt vmcnt(6)
	v_permlane32_swap_b32_e32 v244, v248
	v_permlane32_swap_b32_e32 v245, v249
	v_permlane32_swap_b32_e32 v246, v250
	v_permlane32_swap_b32_e32 v247, v251
	v_permlane32_swap_b32_e32 v216, v220
	v_permlane32_swap_b32_e32 v217, v221
	v_permlane32_swap_b32_e32 v218, v222
	v_permlane32_swap_b32_e32 v219, v223
	v_permlane16_swap_b32_e32 v244, v248
	v_permlane16_swap_b32_e32 v245, v249
	v_permlane16_swap_b32_e32 v246, v250
	v_permlane16_swap_b32_e32 v247, v251
	v_permlane16_swap_b32_e32 v216, v220
	v_permlane16_swap_b32_e32 v217, v221
	v_permlane16_swap_b32_e32 v218, v222
	v_permlane16_swap_b32_e32 v219, v223
	v_pk_fma_f32 v[12:13], v[12:13], v[80:81], v[244:245]
	v_pk_fma_f32 v[14:15], v[14:15], v[82:83], v[246:247]
	v_mul_f32_e32 v210, v13, v13
	v_fmac_f32_e32 v210, v12, v12
	v_fmac_f32_e32 v210, v14, v14
	v_fmac_f32_e32 v210, v15, v15
	v_pk_fma_f32 v[8:9], v[8:9], v[88:89], v[248:249]
	v_pk_fma_f32 v[10:11], v[10:11], v[90:91], v[250:251]
	v_fmac_f32_e32 v210, v8, v8
	v_fmac_f32_e32 v210, v9, v9
	v_fmac_f32_e32 v210, v10, v10
	v_fmac_f32_e32 v210, v11, v11
	v_pk_fma_f32 v[4:5], v[4:5], v[84:85], v[216:217]
	v_pk_fma_f32 v[6:7], v[6:7], v[86:87], v[218:219]
	v_fmac_f32_e32 v210, v4, v4
	v_fmac_f32_e32 v210, v5, v5
	v_fmac_f32_e32 v210, v6, v6
	v_fmac_f32_e32 v210, v7, v7
	v_pk_fma_f32 v[0:1], v[0:1], v[92:93], v[220:221]
	v_pk_fma_f32 v[2:3], v[2:3], v[94:95], v[222:223]
	v_fmac_f32_e32 v210, v0, v0
	v_fmac_f32_e32 v210, v1, v1
	v_fmac_f32_e32 v210, v2, v2
	v_fmac_f32_e32 v210, v3, v3
	s_cmp_lg_u64 s[0:1], 0
	s_cbranch_scc1 .Lnoap_D_8
	v_pk_mul_f32 v[244:245], v[64:65], v[12:13]
	v_pk_mul_f32 v[246:247], v[66:67], v[14:15]
	v_pk_mul_f32 v[248:249], v[72:73], v[8:9]
	v_pk_mul_f32 v[250:251], v[74:75], v[10:11]
	v_pk_mul_f32 v[216:217], v[68:69], v[4:5]
	v_pk_mul_f32 v[218:219], v[70:71], v[6:7]
	v_pk_mul_f32 v[220:221], v[76:77], v[0:1]
	v_pk_mul_f32 v[222:223], v[78:79], v[2:3]
	v_cvt_pk_bf16_f32 v244, v244, v245
	v_cvt_pk_bf16_f32 v245, v246, v247
	v_cvt_pk_bf16_f32 v246, v248, v249
	v_cvt_pk_bf16_f32 v247, v250, v251
	global_store_dwordx4 v208, v[244:247], s[28:29] sc1
	v_cvt_pk_bf16_f32 v216, v216, v217
	v_cvt_pk_bf16_f32 v217, v218, v219
	v_cvt_pk_bf16_f32 v218, v220, v221
	v_cvt_pk_bf16_f32 v219, v222, v223
	global_store_dwordx4 v208, v[216:219], s[28:29] offset:256 sc1
.Lnoap_D_8:
	ds_bpermute_b32 v211, v214, v210
	v_permlane16_swap_b32_e32 v12, v8
	v_permlane16_swap_b32_e32 v13, v9
	v_permlane16_swap_b32_e32 v14, v10
	v_permlane16_swap_b32_e32 v15, v11
	v_permlane16_swap_b32_e32 v4, v0
	v_permlane16_swap_b32_e32 v5, v1
	v_permlane16_swap_b32_e32 v6, v2
	v_permlane16_swap_b32_e32 v7, v3
	v_permlane32_swap_b32_e32 v12, v8
	v_permlane32_swap_b32_e32 v13, v9
	v_permlane32_swap_b32_e32 v14, v10
	v_permlane32_swap_b32_e32 v15, v11
	v_permlane32_swap_b32_e32 v4, v0
	v_permlane32_swap_b32_e32 v5, v1
	v_permlane32_swap_b32_e32 v6, v2
	v_permlane32_swap_b32_e32 v7, v3
	global_store_dwordx4 v207, v[12:15], s[84:85] sc1
	global_store_dwordx4 v207, v[8:11], s[84:85] offset:64 sc1
	global_store_dwordx4 v207, v[4:7], s[84:85] offset:512 sc1
	global_store_dwordx4 v207, v[0:3], s[84:85] offset:576 sc1
	s_waitcnt lgkmcnt(0)
	v_add_f32_e32 v211, v210, v211
	ds_bpermute_b32 v212, v215, v211
	s_waitcnt lgkmcnt(0)
	v_add_f32_e32 v211, v211, v212
	s_mov_b64 exec, 0xffff
	global_store_dword v209, v211, s[72:73] sc1
	s_mov_b64 exec, -1
	s_and_b64 vcc, exec, s[2:3]
	s_mov_b64 s[2:3], -1
	s_cbranch_vccnz .LBB0_2034
	s_andn2_b64 vcc, exec, s[8:9]
	s_cbranch_vccnz .LBB0_2033
	s_barrier
	s_branch .LBB0_2033
